# combo27 + 13 more FFT sign/twiddle folds found with wider pattern windows
# speedup vs baseline: 1.0084x; 1.0011x over previous
.Lmy_fft_kj:
	v_mov_b32 v66, 0
	v_mov_b32_e32 v68, v1
	v_add_u32_e32 v0, v66, v0
	v_cvt_f32_i32_e32 v70, v0
	v_ashrrev_i32_e32 v66, 5, v0
	v_lshlrev_b32_e32 v69, 3, v0
	v_add_u32_e32 v73, 0x400, v0
	v_add_u32_e32 v75, 0x800, v0
	v_add_u32_e32 v76, 0xc00, v0
	v_add_u32_e32 v78, 0x1000, v0
	v_add_u32_e32 v80, 0x1400, v0
	v_add_u32_e32 v82, 0x1800, v0
	v_add_u32_e32 v85, 0x1c00, v0
	v_add_u32_e32 v87, 0x2000, v0
	v_add_u32_e32 v89, 0x2400, v0
	v_add_u32_e32 v91, 0x2800, v0
	v_add_u32_e32 v92, 0x2c00, v0
	v_add_u32_e32 v95, 0x3000, v0
	v_add_u32_e32 v96, 0x3400, v0
	v_add_u32_e32 v99, 0x3800, v0
	v_add_u32_e32 v0, 0x3c00, v0
	v_lshlrev_b32_e32 v66, 3, v66
	v_ashrrev_i32_e32 v73, 5, v73
	v_ashrrev_i32_e32 v75, 5, v75
	v_ashrrev_i32_e32 v76, 5, v76
	v_ashrrev_i32_e32 v78, 5, v78
	v_ashrrev_i32_e32 v80, 5, v80
	v_ashrrev_i32_e32 v82, 5, v82
	v_ashrrev_i32_e32 v85, 5, v85
	v_ashrrev_i32_e32 v100, 5, v87
	v_ashrrev_i32_e32 v103, 5, v89
	v_ashrrev_i32_e32 v105, 5, v91
	v_ashrrev_i32_e32 v106, 5, v92
	v_ashrrev_i32_e32 v107, 5, v95
	v_ashrrev_i32_e32 v124, 5, v96
	v_ashrrev_i32_e32 v125, 5, v99
	v_ashrrev_i32_e32 v126, 5, v0
	v_lshlrev_b32_e32 v0, 3, v0
	v_add3_u32 v127, 0, v66, v69
	v_lshlrev_b32_e32 v66, 3, v73
	v_lshlrev_b32_e32 v73, 3, v75
	v_lshlrev_b32_e32 v75, 3, v76
	v_lshlrev_b32_e32 v76, 3, v78
	v_lshlrev_b32_e32 v78, 3, v80
	v_lshlrev_b32_e32 v80, 3, v82
	v_lshlrev_b32_e32 v82, 3, v85
	v_lshlrev_b32_e32 v85, 3, v100
	v_lshlrev_b32_e32 v100, 3, v103
	v_lshlrev_b32_e32 v103, 3, v105
	v_lshlrev_b32_e32 v105, 3, v106
	v_lshlrev_b32_e32 v106, 3, v107
	v_lshlrev_b32_e32 v107, 3, v124
	v_lshlrev_b32_e32 v124, 3, v125
	v_lshlrev_b32_e32 v125, 3, v126
	v_lshlrev_b32_e32 v96, 3, v96
	v_add3_u32 v196, 0, v125, v0
	v_mul_f32_e32 v0, 0x38800000, v70
	v_lshlrev_b32_e32 v95, 3, v95
	v_add3_u32 v194, 0, v107, v96
	v_sin_f32_e32 v107, v0
	v_add3_u32 v193, 0, v106, v95
	v_cos_f32_e32 v106, v0
	v_lshlrev_b32_e32 v99, 3, v99
	v_add3_u32 v195, 0, v124, v99
	v_xor_b32_e32 v124, 0x80000000, v107
	v_mov_b32_e32 v125, v107
	v_pk_mul_f32 v[128:129], v[124:125], v[106:107] op_sel:[0,1] op_sel_hi:[1,0]
	v_lshlrev_b32_e32 v87, 3, v87
	v_pk_fma_f32 v[128:129], v[106:107], v[106:107], v[128:129] op_sel_hi:[1,0,1]
	v_add3_u32 v186, 0, v76, v69
	v_pk_mul_f32 v[132:133], v[124:125], v[128:129] op_sel:[0,1] op_sel_hi:[1,0]
	s_waitcnt vmcnt(21)
	v_sub_f32_e32 v70, v112, v120
	v_pk_fma_f32 v[132:133], v[128:129], v[106:107], v[132:133] op_sel_hi:[1,0,1]
	s_waitcnt vmcnt(20)
	v_sub_f32_e32 v76, v113, v121
	v_pk_mul_f32 v[136:137], v[124:125], v[132:133] op_sel:[0,1] op_sel_hi:[1,0]
	v_add3_u32 v171, 0, v66, v69
	v_pk_fma_f32 v[136:137], v[132:133], v[106:107], v[136:137] op_sel_hi:[1,0,1]
	v_add3_u32 v184, 0, v73, v69
	v_pk_mul_f32 v[140:141], v[124:125], v[136:137] op_sel:[0,1] op_sel_hi:[1,0]
	v_add3_u32 v190, 0, v85, v87
	v_pk_fma_f32 v[140:141], v[136:137], v[106:107], v[140:141] op_sel_hi:[1,0,1]
	v_sub_f32_e32 v66, v109, v119
	v_pk_mul_f32 v[144:145], v[124:125], v[140:141] op_sel:[0,1] op_sel_hi:[1,0]
	v_mul_f32_e32 v73, 0xbf3504f3, v70
	v_pk_fma_f32 v[144:145], v[140:141], v[106:107], v[144:145] op_sel_hi:[1,0,1]
	v_mul_f32_e32 v85, 0xbf6c835e, v76
	v_pk_mul_f32 v[148:149], v[124:125], v[144:145] op_sel:[0,1] op_sel_hi:[1,0]
	v_lshlrev_b32_e32 v91, 3, v91
	v_pk_fma_f32 v[148:149], v[144:145], v[106:107], v[148:149] op_sel_hi:[1,0,1]
	v_add3_u32 v185, 0, v75, v69
	v_pk_mul_f32 v[152:153], v[124:125], v[148:149] op_sel:[0,1] op_sel_hi:[1,0]
	v_add3_u32 v187, 0, v78, v69
	v_pk_fma_f32 v[152:153], v[148:149], v[106:107], v[152:153] op_sel_hi:[1,0,1]
	v_add3_u32 v188, 0, v80, v69
	v_pk_mul_f32 v[156:157], v[124:125], v[152:153] op_sel:[0,1] op_sel_hi:[1,0]
	v_add3_u32 v189, 0, v82, v69
	v_pk_fma_f32 v[156:157], v[152:153], v[106:107], v[156:157] op_sel_hi:[1,0,1]
	v_sub_f32_e32 v0, v108, v118
	v_pk_mul_f32 v[160:161], v[124:125], v[156:157] op_sel:[0,1] op_sel_hi:[1,0]
	v_pk_add_f32 v[108:109], v[108:109], v[118:119]
	v_pk_fma_f32 v[160:161], v[156:157], v[106:107], v[160:161] op_sel_hi:[1,0,1]
	v_mul_f32_e32 v69, 0xbec3ef15, v66
	v_pk_mul_f32 v[164:165], v[124:125], v[160:161] op_sel:[0,1] op_sel_hi:[1,0]
	v_pk_fma_f32 v[70:71], v[70:71], s[10:11], v[72:73] op_sel_hi:[1,0,1]
	v_pk_fma_f32 v[72:73], v[76:77], s[14:15], v[84:85] op_sel_hi:[1,0,1]
	s_waitcnt vmcnt(18)
	v_sub_f32_e32 v82, v115, v123
	v_pk_add_f32 v[76:77], v[114:115], v[122:123]
	v_mov_b32_e32 v83, v1
	v_mov_b32_e32 v90, v1
	s_movk_i32 s5, 0x200
	v_lshlrev_b32_e32 v89, 3, v89
	v_add3_u32 v192, 0, v103, v91
	v_pk_fma_f32 v[164:165], v[160:161], v[106:107], v[164:165] op_sel_hi:[1,0,1]
	v_pk_fma_f32 v[66:67], v[66:67], s[6:7], v[68:69] op_sel_hi:[1,0,1]
	v_pk_add_f32 v[68:69], v[112:113], v[120:121]
	v_mul_f32_e32 v91, 0xbf6c835e, v82
	s_waitcnt vmcnt(17)
	v_sub_f32_e32 v80, v116, v110
	v_pk_add_f32 v[112:113], v[108:109], v[76:77] neg_lo:[0,1] neg_hi:[0,1]
	v_mov_b32_e32 v81, v1
	v_mov_b32_e32 v88, v1
	v_mov_b32_e32 v101, v1
	v_mov_b32_e32 v102, v1
	v_add3_u32 v191, 0, v100, v89
	v_pk_mul_f32 v[168:169], v[124:125], v[164:165] op_sel:[0,1] op_sel_hi:[1,0]
	v_pk_fma_f32 v[82:83], v[82:83], s[4:5], v[90:91] op_sel_hi:[1,0,1]
	v_mul_f32_e32 v89, 0xbf3504f3, v80
	s_waitcnt vmcnt(16)
	v_sub_f32_e32 v78, v117, v111
	v_pk_add_f32 v[90:91], v[116:117], v[110:111]
	v_mov_b32_e32 v100, v113
	v_mul_f32_e32 v103, 0xbf3504f3, v113
	v_mov_b32_e32 v79, v1
	v_mov_b32_e32 v86, v1
	v_pk_fma_f32 v[168:169], v[164:165], v[106:107], v[168:169] op_sel_hi:[1,0,1]
	v_sub_f32_e32 v75, v114, v122
	v_pk_fma_f32 v[80:81], v[80:81], s[8:9], v[88:89] op_sel_hi:[1,0,1]
	v_mul_f32_e32 v87, 0xbec3ef15, v78
	v_pk_add_f32 v[88:89], v[66:67], v[82:83]
	v_pk_add_f32 v[66:67], v[66:67], v[82:83] neg_lo:[0,1] neg_hi:[0,1]
	v_pk_fma_f32 v[82:83], v[100:101], s[10:11], v[102:103] op_sel_hi:[1,0,1]
	v_pk_add_f32 v[100:101], v[68:69], v[90:91] neg_lo:[0,1] neg_hi:[0,1]
	v_mov_b32_e32 v74, v1
	v_mov_b32_e32 v97, v1
	v_mov_b32_e32 v98, v1
	v_pk_mul_f32 v[174:175], v[124:125], v[168:169] op_sel:[0,1] op_sel_hi:[1,0]
	v_xor_b32_e32 v75, 0x80000000, v75
	v_pk_add_f32 v[76:77], v[108:109], v[76:77]
	v_pk_add_f32 v[68:69], v[68:69], v[90:91]
	v_pk_fma_f32 v[78:79], v[78:79], s[12:13], v[86:87] op_sel_hi:[1,0,1]
	v_pk_add_f32 v[90:91], v[70:71], v[80:81]
	v_pk_add_f32 v[70:71], v[70:71], v[80:81] neg_lo:[0,1] neg_hi:[0,1]
	v_mov_b32_e32 v96, v101
	v_mul_f32_e32 v99, 0xbf3504f3, v101
	v_lshlrev_b32_e32 v92, 3, v92
	v_pk_fma_f32 v[174:175], v[168:169], v[106:107], v[174:175] op_sel_hi:[1,0,1]
	v_pk_add_f32 v[84:85], v[0:1], v[74:75]
	v_pk_add_f32 v[80:81], v[76:77], v[68:69] neg_lo:[0,1] neg_hi:[0,1]
	v_pk_add_f32 v[68:69], v[76:77], v[68:69]
	v_xor_b32_e32 v77, 0x80000000, v70
	v_mov_b32_e32 v76, v71
	v_pk_add_f32 v[70:71], v[72:73], v[78:79]
	v_pk_add_f32 v[72:73], v[72:73], v[78:79] neg_lo:[0,1] neg_hi:[0,1]
	v_pk_fma_f32 v[78:79], v[96:97], s[8:9], v[98:99] op_sel_hi:[1,0,1]
	v_mov_b32_e32 v94, v1
	v_add3_u32 v105, 0, v105, v92
	v_pk_mul_f32 v[178:179], v[124:125], v[174:175] op_sel:[0,1] op_sel_hi:[1,0]
	v_pk_add_f32 v[74:75], v[0:1], v[74:75] neg_lo:[0,1] neg_hi:[0,1]
	v_mov_b32_e32 v0, v112
	v_pk_mul_f32 v[86:87], v[66:67], s[16:17]
	v_xor_b32_e32 v95, 0x80000000, v100
	v_mov_b32_e32 v92, v80
	v_pk_add_f32 v[80:81], v[80:81], 0 neg_lo:[1,1] neg_hi:[1,1]
	v_pk_add_f32 v[96:97], v[84:85], v[90:91]
	v_pk_add_f32 v[84:85], v[84:85], v[90:91] neg_lo:[0,1] neg_hi:[0,1]
	v_pk_add_f32 v[90:91], v[68:69], v[68:69] op_sel:[0,1] op_sel_hi:[1,0]
	v_pk_mul_f32 v[98:99], v[72:73], s[16:17]
	v_pk_add_f32 v[100:101], v[82:83], v[78:79]
	v_pk_add_f32 v[78:79], v[82:83], v[78:79] neg_lo:[0,1] neg_hi:[0,1]
	v_pk_add_f32 v[82:83], v[88:89], v[70:71]
	v_pk_add_f32 v[70:71], v[88:89], v[70:71] neg_lo:[0,1] neg_hi:[0,1]
	v_mov_b32_e32 v93, v1
	v_mov_b32_e32 v126, v107
	v_pk_add_f32 v[130:131], v[128:129], 0 neg_lo:[1,1] neg_hi:[1,1]
	v_pk_add_f32 v[158:159], v[156:157], 0 neg_lo:[1,1] neg_hi:[1,1]
	v_pk_fma_f32 v[178:179], v[174:175], v[106:107], v[178:179] op_sel_hi:[1,0,1]
	v_pk_fma_f32 v[66:67], v[66:67], s[10:11], v[86:87] op_sel:[0,0,1] op_sel_hi:[1,0,0]
	v_pk_add_f32 v[86:87], v[0:1], v[94:95]
	v_pk_add_f32 v[94:95], v[0:1], v[94:95] neg_lo:[0,1] neg_hi:[0,1]
	v_mov_b32_e32 v80, v1
	v_pk_add_f32 v[88:89], v[74:75], v[76:77]
	v_pk_add_f32 v[74:75], v[74:75], v[76:77] neg_lo:[0,1] neg_hi:[0,1]
	v_mov_b32_e32 v91, v1
	v_pk_fma_f32 v[72:73], v[72:73], s[8:9], v[98:99] op_sel:[0,0,1] op_sel_hi:[1,0,0]
	v_xor_b32_e32 v77, 0x80000000, v78
	v_mov_b32_e32 v76, v79
	v_xor_b32_e32 v79, 0x80000000, v70
	v_mov_b32_e32 v78, v71
	v_pk_add_f32 v[98:99], v[96:97], v[82:83]
	v_mov_b32_e32 v130, v129
	v_pk_add_f32 v[134:135], v[132:133], 0 neg_lo:[1,1] neg_hi:[1,1]
	v_pk_add_f32 v[142:143], v[140:141], 0 neg_lo:[1,1] neg_hi:[1,1]
	v_mov_b32_e32 v158, v157
	v_pk_mul_f32 v[124:125], v[124:125], v[178:179] op_sel:[0,1] op_sel_hi:[1,0]
	v_pk_add_f32 v[70:71], v[92:93], v[80:81]
	v_pk_add_f32 v[80:81], v[92:93], v[80:81] neg_lo:[0,1] neg_hi:[0,1]
	v_pk_add_f32 v[92:93], v[86:87], v[100:101]
	v_pk_add_f32 v[82:83], v[96:97], v[82:83] neg_lo:[0,1] neg_hi:[0,1]
	ds_write_b64 v127, v[90:91]
	v_pk_add_f32 v[90:91], v[66:67], v[72:73]
	v_pk_add_f32 v[112:113], v[66:67], v[72:73] op_sel:[1,1] op_sel_hi:[0,0] neg_lo:[0,1] neg_hi:[1,0]
	v_pk_add_f32 v[72:73], v[94:95], v[76:77]
	v_pk_add_f32 v[76:77], v[94:95], v[76:77] neg_lo:[0,1] neg_hi:[0,1]
	v_pk_add_f32 v[94:95], v[84:85], v[78:79]
	v_pk_add_f32 v[78:79], v[84:85], v[78:79] neg_lo:[0,1] neg_hi:[0,1]
	v_pk_mul_f32 v[84:85], v[126:127], v[98:99] op_sel:[0,1] op_sel_hi:[0,0] neg_hi:[1,0]
	v_mov_b32_e32 v134, v133
	v_pk_add_f32 v[138:139], v[136:137], 0 neg_lo:[1,1] neg_hi:[1,1]
	v_mov_b32_e32 v142, v141
	v_pk_add_f32 v[146:147], v[144:145], 0 neg_lo:[1,1] neg_hi:[1,1]
	v_pk_add_f32 v[150:151], v[148:149], 0 neg_lo:[1,1] neg_hi:[1,1]
	v_pk_add_f32 v[166:167], v[164:165], 0 neg_lo:[1,1] neg_hi:[1,1]
	v_pk_fma_f32 v[124:125], v[178:179], v[106:107], v[124:125] op_sel_hi:[1,0,1]
	v_pk_mul_f32 v[96:97], v[92:93], v[130:131] op_sel:[1,0] op_sel_hi:[0,1]
	v_pk_mul_f32 v[102:103], v[82:83], v[158:159] op_sel:[1,0] op_sel_hi:[0,1]
	v_pk_add_f32 v[66:67], v[88:89], v[90:91]
	v_pk_fma_f32 v[84:85], v[98:99], v[106:107], v[84:85] op_sel_hi:[1,0,1]
	v_mov_b32_e32 v138, v137
	v_mov_b32_e32 v146, v145
	v_mov_b32_e32 v150, v149
	v_pk_add_f32 v[154:155], v[152:153], 0 neg_lo:[1,1] neg_hi:[1,1]
	v_pk_add_f32 v[162:163], v[160:161], 0 neg_lo:[1,1] neg_hi:[1,1]
	v_mov_b32_e32 v166, v165
	v_pk_add_f32 v[172:173], v[168:169], 0 neg_lo:[1,1] neg_hi:[1,1]
	v_pk_add_f32 v[176:177], v[174:175], 0 neg_lo:[1,1] neg_hi:[1,1]
	v_pk_add_f32 v[180:181], v[178:179], 0 neg_lo:[1,1] neg_hi:[1,1]
	v_pk_add_f32 v[182:183], v[124:125], 0 neg_lo:[1,1] neg_hi:[1,1]
	v_pk_add_f32 v[68:69], v[68:69], v[68:69] op_sel:[0,1] op_sel_hi:[1,0] neg_lo:[0,1] neg_hi:[0,1]
	v_pk_add_f32 v[88:89], v[88:89], v[90:91] neg_lo:[0,1] neg_hi:[0,1]
	v_pk_fma_f32 v[90:91], v[92:93], v[128:129], v[96:97] op_sel_hi:[1,0,1]
	v_pk_mul_f32 v[92:93], v[94:95], v[142:143] op_sel:[1,0] op_sel_hi:[0,1]
	v_pk_fma_f32 v[82:83], v[82:83], v[156:157], v[102:103] op_sel_hi:[1,0,1]
	v_pk_add_f32 v[102:103], v[74:75], v[112:113]
	ds_write_b64 v171, v[84:85] offset:8192
	ds_write_b64 v184, v[90:91] offset:16384
	v_pk_mul_f32 v[84:85], v[66:67], v[134:135] op_sel:[1,0] op_sel_hi:[0,1]
	v_mov_b32_e32 v154, v153
	v_mov_b32_e32 v162, v161
	v_mov_b32_e32 v172, v169
	v_mov_b32_e32 v176, v175
	v_mov_b32_e32 v180, v179
	v_mov_b32_e32 v182, v125
	v_mov_b32_e32 v0, v68
	v_pk_mov_b32 v[68:69], s[2:3], v[68:69] op_sel:[1,0]
	v_pk_add_f32 v[86:87], v[86:87], v[100:101] neg_lo:[0,1] neg_hi:[0,1]
	v_pk_mul_f32 v[100:101], v[70:71], v[138:139] op_sel:[1,0] op_sel_hi:[0,1]
	v_pk_mul_f32 v[96:97], v[72:73], v[146:147] op_sel:[1,0] op_sel_hi:[0,1]
	v_pk_add_f32 v[74:75], v[74:75], v[112:113] neg_lo:[0,1] neg_hi:[0,1]
	v_pk_fma_f32 v[90:91], v[94:95], v[140:141], v[92:93] op_sel_hi:[1,0,1]
	v_pk_mul_f32 v[92:93], v[88:89], v[166:167] op_sel:[1,0] op_sel_hi:[0,1]
	v_pk_fma_f32 v[66:67], v[66:67], v[132:133], v[84:85] op_sel_hi:[1,0,1]
	v_pk_mul_f32 v[84:85], v[102:103], v[150:151] op_sel:[1,0] op_sel_hi:[0,1]
	s_mov_b64 s[46:47], 0
	s_and_b64 vcc, exec, s[0:1]
	v_pk_mul_f32 v[68:69], v[68:69], v[154:155]
	v_pk_mul_f32 v[108:109], v[86:87], v[162:163] op_sel:[1,0] op_sel_hi:[0,1]
	v_pk_mul_f32 v[110:111], v[80:81], v[172:173] op_sel:[1,0] op_sel_hi:[0,1]
	v_pk_fma_f32 v[70:71], v[70:71], v[136:137], v[100:101] op_sel_hi:[1,0,1]
	v_pk_mul_f32 v[98:99], v[78:79], v[176:177] op_sel:[1,0] op_sel_hi:[0,1]
	v_pk_mul_f32 v[100:101], v[76:77], v[180:181] op_sel:[1,0] op_sel_hi:[0,1]
	v_pk_fma_f32 v[72:73], v[72:73], v[144:145], v[96:97] op_sel_hi:[1,0,1]
	v_pk_fma_f32 v[88:89], v[88:89], v[164:165], v[92:93] op_sel_hi:[1,0,1]
	v_pk_mul_f32 v[92:93], v[74:75], v[182:183] op_sel:[1,0] op_sel_hi:[0,1]
	ds_write_b64 v185, v[66:67] offset:24576
	ds_write_b64 v186, v[70:71] offset:32768
	ds_write_b64 v187, v[90:91] offset:40960
	ds_write_b64 v188, v[72:73] offset:49152
	v_pk_fma_f32 v[66:67], v[102:103], v[148:149], v[84:85] op_sel_hi:[1,0,1]
	v_pk_fma_f32 v[68:69], v[0:1], v[152:153], v[68:69] op_sel_hi:[1,0,1]
	v_pk_fma_f32 v[86:87], v[86:87], v[160:161], v[108:109] op_sel_hi:[1,0,1]
	v_pk_fma_f32 v[80:81], v[80:81], v[168:169], v[110:111] op_sel_hi:[1,0,1]
	v_pk_fma_f32 v[78:79], v[78:79], v[174:175], v[98:99] op_sel_hi:[1,0,1]
	v_pk_fma_f32 v[76:77], v[76:77], v[178:179], v[100:101] op_sel_hi:[1,0,1]
	v_pk_fma_f32 v[70:71], v[74:75], v[124:125], v[92:93] op_sel_hi:[1,0,1]
	ds_write_b64 v189, v[66:67] offset:57344
	ds_write_b64 v190, v[68:69]
	ds_write_b64 v191, v[82:83]
	ds_write_b64 v192, v[86:87]
	ds_write_b64 v105, v[88:89]
	ds_write_b64 v193, v[80:81]
	ds_write_b64 v194, v[78:79]
	ds_write_b64 v195, v[76:77]
	ds_write_b64 v196, v[70:71]
	s_cbranch_vccz .LBB0_359
	s_waitcnt lgkmcnt(0)
	s_barrier
	v_mov_b32 v0, 0
	s_mov_b32 s5, s14
	v_add_u32_e32 v74, v0, v170
	v_lshlrev_b32_e32 v0, 5, v74
	v_and_b32_e32 v71, 0xfffffc00, v0
	v_or_b32_e32 v75, 0x80, v71
	v_and_b32_e32 v70, 31, v74
	v_ashrrev_i32_e32 v75, 2, v75
	v_lshlrev_b32_e32 v78, 3, v71
	v_lshlrev_b32_e32 v79, 3, v70
	v_add_u32_e32 v75, 0, v75
	v_add3_u32 v111, v75, v78, v79
	v_or_b32_e32 v75, 0xa0, v71
	v_ashrrev_i32_e32 v75, 2, v75
	v_add_u32_e32 v75, 0, v75
	v_add3_u32 v110, v75, v78, v79
	v_or_b32_e32 v75, 0xc0, v71
	v_ashrrev_i32_e32 v75, 2, v75
	v_add_u32_e32 v75, 0, v75
	v_add3_u32 v109, v75, v78, v79
	v_or_b32_e32 v75, 0xe0, v71
	v_ashrrev_i32_e32 v75, 2, v75
	v_add_u32_e32 v75, 0, v75
	v_add3_u32 v108, v75, v78, v79
	v_or_b32_e32 v75, 0x100, v71
	v_ashrrev_i32_e32 v75, 2, v75
	v_add_u32_e32 v75, 0, v75
	v_add3_u32 v107, v75, v78, v79
	v_or_b32_e32 v75, 0x120, v71
	v_ashrrev_i32_e32 v75, 2, v75
	v_add_u32_e32 v75, 0, v75
	v_add3_u32 v106, v75, v78, v79
	v_or_b32_e32 v75, 0x140, v71
	v_ashrrev_i32_e32 v75, 2, v75
	v_add_u32_e32 v75, 0, v75
	v_add3_u32 v105, v75, v78, v79
	v_or_b32_e32 v75, 0x160, v71
	v_ashrrev_i32_e32 v75, 2, v75
	v_add_u32_e32 v75, 0, v75
	v_add3_u32 v103, v75, v78, v79
	v_or_b32_e32 v75, 0x180, v71
	v_ashrrev_i32_e32 v75, 2, v75
	v_add_u32_e32 v75, 0, v75
	v_add3_u32 v102, v75, v78, v79
	v_or_b32_e32 v75, 0x1a0, v71
	v_ashrrev_i32_e32 v75, 2, v75
	v_add_u32_e32 v75, 0, v75
	v_add3_u32 v101, v75, v78, v79
	v_or_b32_e32 v75, 0x1c0, v71
	v_ashrrev_i32_e32 v75, 2, v75
	v_add_u32_e32 v75, 0, v75
	v_add3_u32 v100, v75, v78, v79
	v_or_b32_e32 v75, 0x1e0, v71
	v_ashrrev_i32_e32 v75, 2, v75
	v_add_u32_e32 v75, 0, v75
	v_add3_u32 v99, v75, v78, v79
	v_or_b32_e32 v75, 0x200, v71
	v_ashrrev_i32_e32 v75, 2, v75
	v_add_u32_e32 v75, 0, v75
	v_add3_u32 v98, v75, v78, v79
	v_or_b32_e32 v75, 0x220, v71
	v_ashrrev_i32_e32 v75, 2, v75
	v_add_u32_e32 v75, 0, v75
	v_add3_u32 v97, v75, v78, v79
	v_or_b32_e32 v75, 0x240, v71
	v_ashrrev_i32_e32 v75, 2, v75
	v_add_u32_e32 v75, 0, v75
	v_add3_u32 v96, v75, v78, v79
	v_or_b32_e32 v75, 0x260, v71
	v_ashrrev_i32_e32 v75, 2, v75
	v_add_u32_e32 v75, 0, v75
	v_add3_u32 v95, v75, v78, v79
	v_or_b32_e32 v75, 0x280, v71
	v_or_b32_e32 v67, 32, v71
	v_ashrrev_i32_e32 v75, 2, v75
	v_ashrrev_i32_e32 v67, 2, v67
	v_add_u32_e32 v75, 0, v75
	v_add_u32_e32 v67, 0, v67
	v_add3_u32 v94, v75, v78, v79
	v_or_b32_e32 v75, 0x2a0, v71
	v_add3_u32 v114, v67, v78, v79
	v_or_b32_e32 v67, 64, v71
	v_ashrrev_i32_e32 v75, 2, v75
	v_ashrrev_i32_e32 v67, 2, v67
	v_add_u32_e32 v75, 0, v75
	v_add_u32_e32 v67, 0, v67
	v_add3_u32 v93, v75, v78, v79
	v_or_b32_e32 v75, 0x2c0, v71
	v_ashrrev_i32_e32 v66, 2, v71
	v_add3_u32 v113, v67, v78, v79
	v_or_b32_e32 v67, 0x60, v71
	v_ashrrev_i32_e32 v75, 2, v75
	v_add_u32_e32 v66, 0, v66
	v_ashrrev_i32_e32 v67, 2, v67
	v_add_u32_e32 v75, 0, v75
	v_add3_u32 v66, v66, v78, v79
	v_add_u32_e32 v67, 0, v67
	v_add3_u32 v92, v75, v78, v79
	v_or_b32_e32 v75, 0x2e0, v71
	v_add3_u32 v112, v67, v78, v79
	ds_read_b64 v[66:67], v66
	ds_read_b64 v[68:69], v114 offset:256
	ds_read_b64 v[72:73], v113 offset:512
	ds_read_b64 v[76:77], v112 offset:768
	ds_read_b64 v[80:81], v111 offset:1024
	ds_read_b64 v[82:83], v110 offset:1280
	ds_read_b64 v[116:117], v109 offset:1536
	ds_read_b64 v[118:119], v108 offset:1792
	ds_read_b64 v[120:121], v107 offset:2048
	ds_read_b64 v[122:123], v106 offset:2304
	ds_read_b64 v[124:125], v105 offset:2560
	ds_read_b64 v[126:127], v103 offset:2816
	ds_read_b64 v[128:129], v102 offset:3072
	ds_read_b64 v[130:131], v101 offset:3328
	ds_read_b64 v[132:133], v100 offset:3584
	ds_read_b64 v[134:135], v99 offset:3840
	ds_read_b64 v[136:137], v98 offset:4096
	ds_read_b64 v[138:139], v97 offset:4352
	ds_read_b64 v[140:141], v96 offset:4608
	ds_read_b64 v[142:143], v95 offset:4864
	v_ashrrev_i32_e32 v75, 2, v75
	v_add_u32_e32 v75, 0, v75
	v_add3_u32 v91, v75, v78, v79
	v_or_b32_e32 v75, 0x300, v71
	v_ashrrev_i32_e32 v75, 2, v75
	s_waitcnt lgkmcnt(3)
	v_pk_add_f32 v[168:169], v[66:67], v[136:137]
	v_pk_add_f32 v[66:67], v[66:67], v[136:137] neg_lo:[0,1] neg_hi:[0,1]
	s_waitcnt lgkmcnt(2)
	v_pk_add_f32 v[136:137], v[68:69], v[138:139]
	v_pk_add_f32 v[68:69], v[68:69], v[138:139] neg_lo:[0,1] neg_hi:[0,1]
	v_add_u32_e32 v75, 0, v75
	v_pk_mul_f32 v[138:139], v[68:69], s[18:19]
	v_add3_u32 v90, v75, v78, v79
	v_or_b32_e32 v75, 0x320, v71
	v_pk_fma_f32 v[68:69], v[68:69], s[20:21], v[138:139] op_sel:[0,0,1] op_sel_hi:[1,0,0]
	s_waitcnt lgkmcnt(1)
	v_pk_add_f32 v[138:139], v[72:73], v[140:141]
	v_pk_add_f32 v[72:73], v[72:73], v[140:141] neg_lo:[0,1] neg_hi:[0,1]
	v_ashrrev_i32_e32 v75, 2, v75
	v_pk_mul_f32 v[140:141], v[72:73], s[4:5]
	ds_read_b64 v[144:145], v94 offset:5120
	ds_read_b64 v[146:147], v93 offset:5376
	ds_read_b64 v[148:149], v92 offset:5632
	ds_read_b64 v[150:151], v91 offset:5888
	v_add_u32_e32 v75, 0, v75
	v_pk_fma_f32 v[72:73], v[72:73], s[6:7], v[140:141] op_sel:[0,0,1] op_sel_hi:[1,0,0]
	s_waitcnt lgkmcnt(4)
	v_pk_add_f32 v[140:141], v[76:77], v[142:143]
	v_pk_add_f32 v[76:77], v[76:77], v[142:143] neg_lo:[0,1] neg_hi:[0,1]
	v_add3_u32 v89, v75, v78, v79
	v_or_b32_e32 v75, 0x340, v71
	v_pk_mul_f32 v[142:143], v[76:77], s[22:23]
	v_ashrrev_i32_e32 v75, 2, v75
	v_pk_fma_f32 v[76:77], v[76:77], s[24:25], v[142:143] op_sel:[0,0,1] op_sel_hi:[1,0,0]
	s_waitcnt lgkmcnt(3)
	v_pk_add_f32 v[142:143], v[80:81], v[144:145]
	v_pk_add_f32 v[80:81], v[80:81], v[144:145] neg_lo:[0,1] neg_hi:[0,1]
	s_mov_b32 s9, s10
	v_add_u32_e32 v75, 0, v75
	v_pk_mul_f32 v[144:145], v[80:81], s[8:9]
	v_add3_u32 v88, v75, v78, v79
	v_or_b32_e32 v75, 0x360, v71
	v_pk_fma_f32 v[80:81], v[80:81], s[10:11], v[144:145] op_sel:[0,0,1] op_sel_hi:[1,0,0]
	s_waitcnt lgkmcnt(2)
	v_pk_add_f32 v[144:145], v[82:83], v[146:147]
	v_pk_add_f32 v[82:83], v[82:83], v[146:147] neg_lo:[0,1] neg_hi:[0,1]
	s_mov_b32 s27, s24
	v_ashrrev_i32_e32 v75, 2, v75
	v_pk_mul_f32 v[146:147], v[82:83], s[26:27]
	s_mov_b32 s0, s23
	v_add_u32_e32 v75, 0, v75
	v_pk_fma_f32 v[82:83], v[82:83], s[0:1], v[146:147] op_sel:[0,0,1] op_sel_hi:[1,0,0]
	s_waitcnt lgkmcnt(1)
	v_pk_add_f32 v[146:147], v[116:117], v[148:149]
	v_pk_add_f32 v[116:117], v[116:117], v[148:149] neg_lo:[0,1] neg_hi:[0,1]
	s_mov_b32 s13, s6
	v_add3_u32 v87, v75, v78, v79
	v_or_b32_e32 v75, 0x380, v71
	v_pk_mul_f32 v[148:149], v[116:117], s[12:13]
	ds_read_b64 v[152:153], v90 offset:6144
	ds_read_b64 v[154:155], v89 offset:6400
	ds_read_b64 v[156:157], v88 offset:6656
	ds_read_b64 v[158:159], v87 offset:6912
	v_ashrrev_i32_e32 v75, 2, v75
	v_pk_fma_f32 v[116:117], v[116:117], s[14:15], v[148:149] op_sel:[0,0,1] op_sel_hi:[1,0,0]
	s_waitcnt lgkmcnt(4)
	v_pk_add_f32 v[148:149], v[118:119], v[150:151]
	v_pk_add_f32 v[118:119], v[118:119], v[150:151] neg_lo:[0,1] neg_hi:[0,1]
	s_mov_b32 s35, s20
	v_add_u32_e32 v75, 0, v75
	v_pk_mul_f32 v[150:151], v[118:119], s[34:35]
	s_mov_b32 s44, s19
	v_add3_u32 v86, v75, v78, v79
	v_or_b32_e32 v75, 0x3a0, v71
	v_or_b32_e32 v71, 0x3c0, v71
	v_pk_fma_f32 v[118:119], v[118:119], s[44:45], v[150:151] op_sel:[0,0,1] op_sel_hi:[1,0,0]
	s_waitcnt lgkmcnt(3)
	v_pk_add_f32 v[150:151], v[120:121], v[152:153]
	v_pk_add_f32 v[152:153], v[120:121], v[152:153] op_sel:[1,1] op_sel_hi:[0,0] neg_lo:[0,1] neg_hi:[1,0]
	v_ashrrev_i32_e32 v71, 2, v71
	s_waitcnt lgkmcnt(2)
	v_pk_add_f32 v[120:121], v[122:123], v[154:155]
	v_pk_add_f32 v[122:123], v[122:123], v[154:155] neg_lo:[0,1] neg_hi:[0,1]
	v_add_u32_e32 v71, 0, v71
	v_or_b32_e32 v0, 0x3e0, v0
	v_pk_mul_f32 v[154:155], v[122:123], s[34:35]
	v_ashrrev_i32_e32 v75, 2, v75
	v_add3_u32 v84, v71, v78, v79
	v_ashrrev_i32_e32 v71, 2, v0
	v_pk_fma_f32 v[122:123], v[122:123], s[18:19], v[154:155] op_sel:[0,0,1] op_sel_hi:[1,0,0]
	s_waitcnt lgkmcnt(1)
	v_pk_add_f32 v[154:155], v[124:125], v[156:157]
	v_pk_add_f32 v[124:125], v[124:125], v[156:157] neg_lo:[0,1] neg_hi:[0,1]
	v_add_u32_e32 v75, 0, v75
	v_add_u32_e32 v71, 0, v71
	v_lshlrev_b32_e32 v0, 3, v0
	v_pk_mul_f32 v[156:157], v[124:125], s[12:13]
	v_add3_u32 v85, v75, v78, v79
	v_add3_u32 v0, v71, v0, v79
	ds_read_b64 v[160:161], v86 offset:7168
	ds_read_b64 v[162:163], v85 offset:7424
	ds_read_b64 v[164:165], v84 offset:7680
	ds_read_b64 v[166:167], v0
	v_pk_fma_f32 v[124:125], v[124:125], s[4:5], v[156:157] op_sel:[0,0,1] op_sel_hi:[1,0,0]
	s_waitcnt lgkmcnt(4)
	v_pk_add_f32 v[156:157], v[126:127], v[158:159]
	v_pk_add_f32 v[126:127], v[126:127], v[158:159] neg_lo:[0,1] neg_hi:[0,1]
	v_lshlrev_b32_e32 v70, 4, v70
	v_pk_mul_f32 v[158:159], v[126:127], s[26:27]
	v_cvt_f32_u32_e32 v75, v70
	v_pk_fma_f32 v[126:127], v[126:127], s[22:23], v[158:159] op_sel:[0,0,1] op_sel_hi:[1,0,0]
	s_waitcnt lgkmcnt(3)
	v_pk_add_f32 v[158:159], v[128:129], v[160:161]
	v_pk_add_f32 v[128:129], v[128:129], v[160:161] neg_lo:[0,1] neg_hi:[0,1]
	v_and_b32_e32 v74, 0x1fffffe0, v74
	v_pk_mul_f32 v[160:161], v[128:129], s[8:9]
	v_mul_f32_e32 v115, 0x38800000, v75
	v_pk_fma_f32 v[128:129], v[128:129], s[8:9], v[160:161] op_sel:[0,0,1] op_sel_hi:[1,0,0]
	s_waitcnt lgkmcnt(2)
	v_pk_add_f32 v[160:161], v[130:131], v[162:163]
	v_pk_add_f32 v[130:131], v[130:131], v[162:163] neg_lo:[0,1] neg_hi:[0,1]
	v_lshl_add_u32 v74, v74, 3, 0
	v_pk_mul_f32 v[162:163], v[130:131], s[22:23]
	v_sin_f32_e32 v75, v115
	v_pk_fma_f32 v[130:131], v[130:131], s[26:27], v[162:163] op_sel:[0,0,1] op_sel_hi:[1,0,0]
	s_waitcnt lgkmcnt(1)
	v_pk_add_f32 v[162:163], v[132:133], v[164:165]
	v_pk_add_f32 v[132:133], v[132:133], v[164:165] neg_lo:[0,1] neg_hi:[0,1]
	v_add3_u32 v74, v74, v78, v79
	v_pk_mul_f32 v[164:165], v[132:133], s[4:5]
	v_xor_b32_e32 v78, 0x80000000, v75
	v_pk_fma_f32 v[132:133], v[132:133], s[12:13], v[164:165] op_sel:[0,0,1] op_sel_hi:[1,0,0]
	s_waitcnt lgkmcnt(0)
	v_pk_add_f32 v[164:165], v[134:135], v[166:167]
	v_pk_add_f32 v[134:135], v[134:135], v[166:167] neg_lo:[0,1] neg_hi:[0,1]
	v_mov_b32_e32 v79, v75
	v_pk_mul_f32 v[166:167], v[134:135], s[18:19]
	s_add_u32 s41, s56, s42
	v_pk_fma_f32 v[134:135], v[134:135], s[34:35], v[166:167] op_sel:[0,0,1] op_sel_hi:[1,0,0]
	v_pk_add_f32 v[166:167], v[168:169], v[150:151]
	v_pk_add_f32 v[150:151], v[168:169], v[150:151] neg_lo:[0,1] neg_hi:[0,1]
	v_pk_add_f32 v[168:169], v[136:137], v[120:121]
	v_pk_add_f32 v[120:121], v[136:137], v[120:121] neg_lo:[0,1] neg_hi:[0,1]
	s_addc_u32 s61, s57, s43
	v_pk_mul_f32 v[136:137], v[120:121], s[4:5]
	s_nop 0
	v_pk_fma_f32 v[120:121], v[120:121], s[6:7], v[136:137] op_sel:[0,0,1] op_sel_hi:[1,0,0]
	v_pk_add_f32 v[136:137], v[138:139], v[154:155]
	v_pk_add_f32 v[138:139], v[138:139], v[154:155] neg_lo:[0,1] neg_hi:[0,1]
	s_nop 0
	v_pk_mul_f32 v[154:155], v[138:139], s[8:9]
	s_nop 0
	v_pk_fma_f32 v[138:139], v[138:139], s[10:11], v[154:155] op_sel:[0,0,1] op_sel_hi:[1,0,0]
	v_pk_add_f32 v[154:155], v[140:141], v[156:157]
	v_pk_add_f32 v[140:141], v[140:141], v[156:157] neg_lo:[0,1] neg_hi:[0,1]
	s_nop 0
	v_pk_mul_f32 v[156:157], v[140:141], s[12:13]
	s_nop 0
	v_pk_fma_f32 v[140:141], v[140:141], s[14:15], v[156:157] op_sel:[0,0,1] op_sel_hi:[1,0,0]
	v_pk_add_f32 v[156:157], v[142:143], v[158:159]
	v_pk_add_f32 v[158:159], v[142:143], v[158:159] op_sel:[1,1] op_sel_hi:[0,0] neg_lo:[0,1] neg_hi:[1,0]
	s_nop 0
	v_pk_add_f32 v[142:143], v[144:145], v[160:161]
	v_pk_add_f32 v[144:145], v[144:145], v[160:161] neg_lo:[0,1] neg_hi:[0,1]
	s_nop 0
	v_pk_mul_f32 v[160:161], v[144:145], s[12:13]
	s_nop 0
	v_pk_fma_f32 v[144:145], v[144:145], s[4:5], v[160:161] op_sel:[0,0,1] op_sel_hi:[1,0,0]
	v_pk_add_f32 v[160:161], v[146:147], v[162:163]
	v_pk_add_f32 v[146:147], v[146:147], v[162:163] neg_lo:[0,1] neg_hi:[0,1]
	s_nop 0
	v_pk_mul_f32 v[162:163], v[146:147], s[8:9]
	s_nop 0
	v_pk_fma_f32 v[146:147], v[146:147], s[8:9], v[162:163] op_sel:[0,0,1] op_sel_hi:[1,0,0]
	v_pk_add_f32 v[162:163], v[148:149], v[164:165]
	v_pk_add_f32 v[148:149], v[148:149], v[164:165] neg_lo:[0,1] neg_hi:[0,1]
	s_nop 0
	v_pk_mul_f32 v[164:165], v[148:149], s[4:5]
	s_nop 0
	v_pk_fma_f32 v[148:149], v[148:149], s[12:13], v[164:165] op_sel:[0,0,1] op_sel_hi:[1,0,0]
	v_pk_add_f32 v[164:165], v[66:67], v[152:153]
	v_pk_add_f32 v[66:67], v[66:67], v[152:153] neg_lo:[0,1] neg_hi:[0,1]
	v_pk_add_f32 v[152:153], v[68:69], v[122:123]
	v_pk_add_f32 v[68:69], v[68:69], v[122:123] neg_lo:[0,1] neg_hi:[0,1]
	s_nop 0
	v_pk_mul_f32 v[122:123], v[68:69], s[4:5]
	s_nop 0
	v_pk_fma_f32 v[68:69], v[68:69], s[6:7], v[122:123] op_sel:[0,0,1] op_sel_hi:[1,0,0]
	v_pk_add_f32 v[122:123], v[72:73], v[124:125]
	v_pk_add_f32 v[72:73], v[72:73], v[124:125] neg_lo:[0,1] neg_hi:[0,1]
	s_nop 0
	v_pk_mul_f32 v[124:125], v[72:73], s[8:9]
	s_nop 0
	v_pk_fma_f32 v[72:73], v[72:73], s[10:11], v[124:125] op_sel:[0,0,1] op_sel_hi:[1,0,0]
	v_pk_add_f32 v[124:125], v[76:77], v[126:127]
	v_pk_add_f32 v[76:77], v[76:77], v[126:127] neg_lo:[0,1] neg_hi:[0,1]
	s_nop 0
	v_pk_mul_f32 v[126:127], v[76:77], s[12:13]
	s_nop 0
	v_pk_fma_f32 v[76:77], v[76:77], s[14:15], v[126:127] op_sel:[0,0,1] op_sel_hi:[1,0,0]
	v_pk_add_f32 v[126:127], v[80:81], v[128:129]
	v_pk_add_f32 v[128:129], v[80:81], v[128:129] op_sel:[1,1] op_sel_hi:[0,0] neg_lo:[0,1] neg_hi:[1,0]
	s_nop 0
	v_pk_add_f32 v[80:81], v[82:83], v[130:131]
	v_pk_add_f32 v[82:83], v[82:83], v[130:131] neg_lo:[0,1] neg_hi:[0,1]
	s_nop 0
	v_pk_mul_f32 v[130:131], v[82:83], s[12:13]
	s_nop 0
	v_pk_fma_f32 v[82:83], v[82:83], s[4:5], v[130:131] op_sel:[0,0,1] op_sel_hi:[1,0,0]
	v_pk_add_f32 v[130:131], v[116:117], v[132:133]
	v_pk_add_f32 v[116:117], v[116:117], v[132:133] neg_lo:[0,1] neg_hi:[0,1]
	s_nop 0
	v_pk_mul_f32 v[132:133], v[116:117], s[8:9]
	s_nop 0
	v_pk_fma_f32 v[116:117], v[116:117], s[8:9], v[132:133] op_sel:[0,0,1] op_sel_hi:[1,0,0]
	v_pk_add_f32 v[132:133], v[118:119], v[134:135]
	v_pk_add_f32 v[118:119], v[118:119], v[134:135] neg_lo:[0,1] neg_hi:[0,1]
	s_nop 0
	v_pk_mul_f32 v[134:135], v[118:119], s[4:5]
	s_nop 0
	v_pk_fma_f32 v[118:119], v[118:119], s[12:13], v[134:135] op_sel:[0,0,1] op_sel_hi:[1,0,0]
	v_pk_add_f32 v[134:135], v[166:167], v[156:157]
	v_pk_add_f32 v[156:157], v[166:167], v[156:157] neg_lo:[0,1] neg_hi:[0,1]
	v_pk_add_f32 v[166:167], v[168:169], v[142:143]
	v_pk_add_f32 v[142:143], v[168:169], v[142:143] neg_lo:[0,1] neg_hi:[0,1]
	s_nop 0
	v_pk_mul_f32 v[168:169], v[142:143], s[8:9]
	s_nop 0
	v_pk_fma_f32 v[142:143], v[142:143], s[10:11], v[168:169] op_sel:[0,0,1] op_sel_hi:[1,0,0]
	v_pk_add_f32 v[168:169], v[136:137], v[160:161]
	v_pk_add_f32 v[160:161], v[136:137], v[160:161] op_sel:[1,1] op_sel_hi:[0,0] neg_lo:[0,1] neg_hi:[1,0]
	s_nop 0
	v_pk_add_f32 v[136:137], v[154:155], v[162:163]
	v_pk_add_f32 v[154:155], v[154:155], v[162:163] neg_lo:[0,1] neg_hi:[0,1]
	s_nop 0
	v_pk_mul_f32 v[162:163], v[154:155], s[8:9]
	s_nop 0
	v_pk_fma_f32 v[154:155], v[154:155], s[8:9], v[162:163] op_sel:[0,0,1] op_sel_hi:[1,0,0]
	v_pk_add_f32 v[162:163], v[150:151], v[158:159]
	v_pk_add_f32 v[150:151], v[150:151], v[158:159] neg_lo:[0,1] neg_hi:[0,1]
	v_pk_add_f32 v[158:159], v[120:121], v[144:145]
	v_pk_add_f32 v[120:121], v[120:121], v[144:145] neg_lo:[0,1] neg_hi:[0,1]
	s_nop 0
	v_pk_mul_f32 v[144:145], v[120:121], s[8:9]
	s_nop 0
	v_pk_fma_f32 v[120:121], v[120:121], s[10:11], v[144:145] op_sel:[0,0,1] op_sel_hi:[1,0,0]
	v_pk_add_f32 v[144:145], v[138:139], v[146:147]
	v_pk_add_f32 v[146:147], v[138:139], v[146:147] op_sel:[1,1] op_sel_hi:[0,0] neg_lo:[0,1] neg_hi:[1,0]
	s_nop 0
	v_pk_add_f32 v[138:139], v[140:141], v[148:149]
	v_pk_add_f32 v[140:141], v[140:141], v[148:149] neg_lo:[0,1] neg_hi:[0,1]
	s_nop 0
	v_pk_mul_f32 v[148:149], v[140:141], s[8:9]
	s_nop 0
	v_pk_fma_f32 v[140:141], v[140:141], s[8:9], v[148:149] op_sel:[0,0,1] op_sel_hi:[1,0,0]
	v_pk_add_f32 v[148:149], v[164:165], v[126:127]
	v_pk_add_f32 v[126:127], v[164:165], v[126:127] neg_lo:[0,1] neg_hi:[0,1]
	v_pk_add_f32 v[164:165], v[152:153], v[80:81]
	v_pk_add_f32 v[80:81], v[152:153], v[80:81] neg_lo:[0,1] neg_hi:[0,1]
	s_nop 0
	v_pk_mul_f32 v[152:153], v[80:81], s[8:9]
	s_nop 0
	v_pk_fma_f32 v[80:81], v[80:81], s[10:11], v[152:153] op_sel:[0,0,1] op_sel_hi:[1,0,0]
	v_pk_add_f32 v[152:153], v[122:123], v[130:131]
	v_pk_add_f32 v[130:131], v[122:123], v[130:131] op_sel:[1,1] op_sel_hi:[0,0] neg_lo:[0,1] neg_hi:[1,0]
	s_nop 0
	v_pk_add_f32 v[122:123], v[124:125], v[132:133]
	v_pk_add_f32 v[124:125], v[124:125], v[132:133] neg_lo:[0,1] neg_hi:[0,1]
	s_nop 0
	v_pk_mul_f32 v[132:133], v[124:125], s[8:9]
	s_nop 0
	v_pk_fma_f32 v[124:125], v[124:125], s[8:9], v[132:133] op_sel:[0,0,1] op_sel_hi:[1,0,0]
	v_pk_add_f32 v[132:133], v[66:67], v[128:129]
	v_pk_add_f32 v[66:67], v[66:67], v[128:129] neg_lo:[0,1] neg_hi:[0,1]
	v_pk_add_f32 v[128:129], v[68:69], v[82:83]
	v_pk_add_f32 v[68:69], v[68:69], v[82:83] neg_lo:[0,1] neg_hi:[0,1]
	s_nop 0
	v_pk_mul_f32 v[82:83], v[68:69], s[8:9]
	s_nop 0
	v_pk_fma_f32 v[68:69], v[68:69], s[10:11], v[82:83] op_sel:[0,0,1] op_sel_hi:[1,0,0]
	v_pk_add_f32 v[82:83], v[72:73], v[116:117]
	v_pk_add_f32 v[116:117], v[72:73], v[116:117] op_sel:[1,1] op_sel_hi:[0,0] neg_lo:[0,1] neg_hi:[1,0]
	s_nop 0
	v_pk_add_f32 v[72:73], v[76:77], v[118:119]
	v_pk_add_f32 v[76:77], v[76:77], v[118:119] neg_lo:[0,1] neg_hi:[0,1]
	v_pk_add_f32 v[174:175], v[66:67], v[116:117]
	v_pk_mul_f32 v[118:119], v[76:77], s[8:9]
	v_pk_add_f32 v[116:117], v[66:67], v[116:117] neg_lo:[0,1] neg_hi:[0,1]
	v_pk_fma_f32 v[76:77], v[76:77], s[8:9], v[118:119] op_sel:[0,0,1] op_sel_hi:[1,0,0]
	v_pk_add_f32 v[118:119], v[134:135], v[168:169]
	v_pk_add_f32 v[134:135], v[134:135], v[168:169] neg_lo:[0,1] neg_hi:[0,1]
	v_pk_add_f32 v[168:169], v[166:167], v[136:137]
	v_pk_add_f32 v[166:167], v[166:167], v[136:137] op_sel:[1,1] op_sel_hi:[0,0] neg_lo:[0,1] neg_hi:[1,0]
	v_pk_add_f32 v[180:181], v[118:119], v[168:169]
	v_pk_add_f32 v[136:137], v[156:157], v[160:161]
	v_pk_add_f32 v[156:157], v[156:157], v[160:161] neg_lo:[0,1] neg_hi:[0,1]
	v_pk_add_f32 v[160:161], v[142:143], v[154:155]
	v_pk_add_f32 v[154:155], v[142:143], v[154:155] op_sel:[1,1] op_sel_hi:[0,0] neg_lo:[0,1] neg_hi:[1,0]
	v_pk_add_f32 v[178:179], v[68:69], v[76:77] op_sel:[1,1] op_sel_hi:[0,0] neg_lo:[0,1] neg_hi:[1,0]
	v_pk_add_f32 v[142:143], v[162:163], v[144:145]
	v_pk_add_f32 v[144:145], v[162:163], v[144:145] neg_lo:[0,1] neg_hi:[0,1]
	v_pk_add_f32 v[162:163], v[158:159], v[138:139]
	v_pk_add_f32 v[158:159], v[158:159], v[138:139] op_sel:[1,1] op_sel_hi:[0,0] neg_lo:[0,1] neg_hi:[1,0]
	ds_write_b64 v74, v[180:181]
	v_pk_add_f32 v[138:139], v[150:151], v[146:147]
	v_pk_add_f32 v[146:147], v[150:151], v[146:147] neg_lo:[0,1] neg_hi:[0,1]
	v_pk_add_f32 v[150:151], v[120:121], v[140:141]
	v_pk_add_f32 v[140:141], v[120:121], v[140:141] op_sel:[1,1] op_sel_hi:[0,0] neg_lo:[0,1] neg_hi:[1,0]
	v_cos_f32_e32 v74, v115
	v_pk_add_f32 v[120:121], v[148:149], v[152:153]
	v_pk_add_f32 v[148:149], v[148:149], v[152:153] neg_lo:[0,1] neg_hi:[0,1]
	v_pk_add_f32 v[152:153], v[164:165], v[122:123]
	v_pk_add_f32 v[164:165], v[164:165], v[122:123] op_sel:[1,1] op_sel_hi:[0,0] neg_lo:[0,1] neg_hi:[1,0]
	v_pk_add_f32 v[122:123], v[126:127], v[130:131]
	v_pk_add_f32 v[126:127], v[126:127], v[130:131] neg_lo:[0,1] neg_hi:[0,1]
	v_pk_add_f32 v[130:131], v[80:81], v[124:125]
	v_pk_add_f32 v[124:125], v[80:81], v[124:125] op_sel:[1,1] op_sel_hi:[0,0] neg_lo:[0,1] neg_hi:[1,0]
	v_pk_add_f32 v[80:81], v[132:133], v[82:83]
	v_pk_add_f32 v[132:133], v[132:133], v[82:83] neg_lo:[0,1] neg_hi:[0,1]
	v_pk_add_f32 v[176:177], v[68:69], v[76:77]
	v_pk_add_f32 v[118:119], v[118:119], v[168:169] neg_lo:[0,1] neg_hi:[0,1]
	v_pk_add_f32 v[168:169], v[134:135], v[166:167]
	v_pk_add_f32 v[82:83], v[134:135], v[166:167] neg_lo:[0,1] neg_hi:[0,1]
	v_pk_add_f32 v[134:135], v[136:137], v[160:161]
	v_pk_add_f32 v[136:137], v[136:137], v[160:161] neg_lo:[0,1] neg_hi:[0,1]
	v_pk_add_f32 v[160:161], v[156:157], v[154:155]
	v_pk_add_f32 v[68:69], v[156:157], v[154:155] neg_lo:[0,1] neg_hi:[0,1]
	v_pk_add_f32 v[154:155], v[142:143], v[162:163]
	v_pk_add_f32 v[142:143], v[142:143], v[162:163] neg_lo:[0,1] neg_hi:[0,1]
	v_pk_add_f32 v[156:157], v[144:145], v[158:159]
	v_pk_add_f32 v[76:77], v[144:145], v[158:159] neg_lo:[0,1] neg_hi:[0,1]
	v_pk_add_f32 v[144:145], v[138:139], v[150:151]
	v_pk_add_f32 v[138:139], v[138:139], v[150:151] neg_lo:[0,1] neg_hi:[0,1]
	v_pk_add_f32 v[150:151], v[146:147], v[140:141]
	v_pk_add_f32 v[66:67], v[146:147], v[140:141] neg_lo:[0,1] neg_hi:[0,1]
	v_pk_add_f32 v[140:141], v[120:121], v[152:153]
	v_pk_add_f32 v[162:163], v[116:117], v[178:179]
	v_pk_add_f32 v[70:71], v[116:117], v[178:179] neg_lo:[0,1] neg_hi:[0,1]
	v_mov_b32_e32 v116, v75
	v_pk_mul_f32 v[116:117], v[116:117], v[140:141] op_sel:[0,1] op_sel_hi:[0,0] neg_hi:[1,0]
	v_pk_fma_f32 v[116:117], v[140:141], v[74:75], v[116:117] op_sel_hi:[1,0,1]
	ds_write_b64 v114, v[116:117] offset:256
	v_pk_mul_f32 v[114:115], v[78:79], v[74:75] op_sel:[0,1] op_sel_hi:[1,0]
	v_pk_add_f32 v[172:173], v[128:129], v[72:73]
	v_pk_fma_f32 v[114:115], v[74:75], v[74:75], v[114:115] op_sel_hi:[1,0,1]
	v_pk_add_f32 v[128:129], v[128:129], v[72:73] op_sel:[1,1] op_sel_hi:[0,0] neg_lo:[0,1] neg_hi:[1,0]
	v_pk_mul_f32 v[116:117], v[154:155], v[114:115] op_sel:[1,1] op_sel_hi:[0,1] neg_hi:[0,1]
	v_pk_fma_f32 v[116:117], v[154:155], v[114:115], v[116:117] op_sel_hi:[1,0,1]
	ds_write_b64 v113, v[116:117] offset:512
	v_pk_mul_f32 v[116:117], v[78:79], v[114:115] op_sel:[0,1] op_sel_hi:[1,0]
	v_pk_add_f32 v[120:121], v[120:121], v[152:153] neg_lo:[0,1] neg_hi:[0,1]
	v_pk_fma_f32 v[114:115], v[114:115], v[74:75], v[116:117] op_sel_hi:[1,0,1]
	v_pk_add_f32 v[152:153], v[122:123], v[130:131]
	v_pk_add_f32 v[122:123], v[122:123], v[130:131] neg_lo:[0,1] neg_hi:[0,1]
	v_pk_add_f32 v[130:131], v[126:127], v[124:125]
	v_pk_add_f32 v[72:73], v[126:127], v[124:125] neg_lo:[0,1] neg_hi:[0,1]
	v_pk_add_f32 v[124:125], v[80:81], v[172:173]
	v_pk_mul_f32 v[116:117], v[124:125], v[114:115] op_sel:[1,1] op_sel_hi:[0,1] neg_hi:[0,1]
	v_pk_add_f32 v[126:127], v[80:81], v[172:173] neg_lo:[0,1] neg_hi:[0,1]
	v_pk_fma_f32 v[116:117], v[124:125], v[114:115], v[116:117] op_sel_hi:[1,0,1]
	ds_write_b64 v112, v[116:117] offset:768
	v_pk_mul_f32 v[112:113], v[78:79], v[114:115] op_sel:[0,1] op_sel_hi:[1,0]
	v_pk_add_f32 v[158:159], v[132:133], v[128:129]
	v_pk_fma_f32 v[112:113], v[114:115], v[74:75], v[112:113] op_sel_hi:[1,0,1]
	v_pk_add_f32 v[80:81], v[132:133], v[128:129] neg_lo:[0,1] neg_hi:[0,1]
	v_pk_add_f32 v[128:129], v[174:175], v[176:177]
	v_pk_mul_f32 v[114:115], v[134:135], v[112:113] op_sel:[1,1] op_sel_hi:[0,1] neg_hi:[0,1]
	v_pk_add_f32 v[146:147], v[148:149], v[164:165]
	v_pk_fma_f32 v[114:115], v[134:135], v[112:113], v[114:115] op_sel_hi:[1,0,1]
	ds_write_b64 v111, v[114:115] offset:1024
	v_pk_mul_f32 v[114:115], v[78:79], v[112:113] op_sel:[0,1] op_sel_hi:[1,0]
	v_pk_add_f32 v[132:133], v[174:175], v[176:177] neg_lo:[0,1] neg_hi:[0,1]
	v_pk_fma_f32 v[112:113], v[112:113], v[74:75], v[114:115] op_sel_hi:[1,0,1]
	v_pk_add_f32 v[148:149], v[148:149], v[164:165] neg_lo:[0,1] neg_hi:[0,1]
	s_nop 0
	v_pk_mul_f32 v[114:115], v[152:153], v[112:113] op_sel:[1,1] op_sel_hi:[0,1] neg_hi:[0,1]
	s_nop 0
	v_pk_fma_f32 v[114:115], v[152:153], v[112:113], v[114:115] op_sel_hi:[1,0,1]
	ds_write_b64 v110, v[114:115] offset:1280
	v_pk_mul_f32 v[110:111], v[78:79], v[112:113] op_sel:[0,1] op_sel_hi:[1,0]
	s_nop 0
	v_pk_fma_f32 v[110:111], v[112:113], v[74:75], v[110:111] op_sel_hi:[1,0,1]
	s_nop 0
	s_nop 0
	v_pk_mul_f32 v[112:113], v[144:145], v[110:111] op_sel:[1,1] op_sel_hi:[0,1] neg_hi:[0,1]
	s_nop 0
	v_pk_fma_f32 v[112:113], v[144:145], v[110:111], v[112:113] op_sel_hi:[1,0,1]
	ds_write_b64 v109, v[112:113] offset:1536
	v_pk_mul_f32 v[112:113], v[78:79], v[110:111] op_sel:[0,1] op_sel_hi:[1,0]
	s_nop 0
	v_pk_fma_f32 v[110:111], v[110:111], v[74:75], v[112:113] op_sel_hi:[1,0,1]
	s_nop 0
	s_nop 0
	v_pk_mul_f32 v[112:113], v[128:129], v[110:111] op_sel:[1,1] op_sel_hi:[0,1] neg_hi:[0,1]
	s_nop 0
	v_pk_fma_f32 v[112:113], v[128:129], v[110:111], v[112:113] op_sel_hi:[1,0,1]
	ds_write_b64 v108, v[112:113] offset:1792
	v_pk_mul_f32 v[108:109], v[78:79], v[110:111] op_sel:[0,1] op_sel_hi:[1,0]
	s_nop 0
	v_pk_fma_f32 v[108:109], v[110:111], v[74:75], v[108:109] op_sel_hi:[1,0,1]
	s_nop 0
	s_nop 0
	v_pk_mul_f32 v[110:111], v[168:169], v[108:109] op_sel:[1,1] op_sel_hi:[0,1] neg_hi:[0,1]
	s_nop 0
	v_pk_fma_f32 v[110:111], v[168:169], v[108:109], v[110:111] op_sel_hi:[1,0,1]
	ds_write_b64 v107, v[110:111] offset:2048
	v_pk_mul_f32 v[110:111], v[78:79], v[108:109] op_sel:[0,1] op_sel_hi:[1,0]
	s_nop 0
	v_pk_fma_f32 v[108:109], v[108:109], v[74:75], v[110:111] op_sel_hi:[1,0,1]
	s_nop 0
	s_nop 0
	v_pk_mul_f32 v[110:111], v[146:147], v[108:109] op_sel:[1,1] op_sel_hi:[0,1] neg_hi:[0,1]
	s_nop 0
	v_pk_fma_f32 v[110:111], v[146:147], v[108:109], v[110:111] op_sel_hi:[1,0,1]
	ds_write_b64 v106, v[110:111] offset:2304
	v_pk_mul_f32 v[106:107], v[78:79], v[108:109] op_sel:[0,1] op_sel_hi:[1,0]
	s_nop 0
	v_pk_fma_f32 v[106:107], v[108:109], v[74:75], v[106:107] op_sel_hi:[1,0,1]
	s_nop 0
	s_nop 0
	v_pk_mul_f32 v[108:109], v[156:157], v[106:107] op_sel:[1,1] op_sel_hi:[0,1] neg_hi:[0,1]
	s_nop 0
	v_pk_fma_f32 v[108:109], v[156:157], v[106:107], v[108:109] op_sel_hi:[1,0,1]
	ds_write_b64 v105, v[108:109] offset:2560
	v_pk_mul_f32 v[108:109], v[78:79], v[106:107] op_sel:[0,1] op_sel_hi:[1,0]
	s_nop 0
	v_pk_fma_f32 v[106:107], v[106:107], v[74:75], v[108:109] op_sel_hi:[1,0,1]
	s_nop 0
	s_nop 0
	v_pk_mul_f32 v[108:109], v[158:159], v[106:107] op_sel:[1,1] op_sel_hi:[0,1] neg_hi:[0,1]
	s_nop 0
	v_pk_fma_f32 v[108:109], v[158:159], v[106:107], v[108:109] op_sel_hi:[1,0,1]
	ds_write_b64 v103, v[108:109] offset:2816
	v_pk_mul_f32 v[108:109], v[78:79], v[106:107] op_sel:[0,1] op_sel_hi:[1,0]
	s_nop 0
	v_pk_fma_f32 v[106:107], v[106:107], v[74:75], v[108:109] op_sel_hi:[1,0,1]
	s_nop 0
	s_nop 0
	v_pk_mul_f32 v[108:109], v[160:161], v[106:107] op_sel:[1,1] op_sel_hi:[0,1] neg_hi:[0,1]
	s_nop 0
	v_pk_fma_f32 v[108:109], v[160:161], v[106:107], v[108:109] op_sel_hi:[1,0,1]
	ds_write_b64 v102, v[108:109] offset:3072
	v_pk_mul_f32 v[102:103], v[78:79], v[106:107] op_sel:[0,1] op_sel_hi:[1,0]
	s_nop 0
	v_pk_fma_f32 v[102:103], v[106:107], v[74:75], v[102:103] op_sel_hi:[1,0,1]
	s_nop 0
	s_nop 0
	v_pk_mul_f32 v[106:107], v[130:131], v[102:103] op_sel:[1,1] op_sel_hi:[0,1] neg_hi:[0,1]
	s_nop 0
	v_pk_fma_f32 v[106:107], v[130:131], v[102:103], v[106:107] op_sel_hi:[1,0,1]
	ds_write_b64 v101, v[106:107] offset:3328
	v_pk_mul_f32 v[106:107], v[78:79], v[102:103] op_sel:[0,1] op_sel_hi:[1,0]
	s_nop 0
	v_pk_fma_f32 v[102:103], v[102:103], v[74:75], v[106:107] op_sel_hi:[1,0,1]
	s_nop 0
	s_nop 0
	v_pk_mul_f32 v[106:107], v[150:151], v[102:103] op_sel:[1,1] op_sel_hi:[0,1] neg_hi:[0,1]
	v_pk_fma_f32 v[106:107], v[150:151], v[102:103], v[106:107] op_sel_hi:[1,0,1]
	ds_write_b64 v100, v[106:107] offset:3584
	v_pk_mul_f32 v[100:101], v[78:79], v[102:103] op_sel:[0,1] op_sel_hi:[1,0]
	s_nop 0
	v_pk_fma_f32 v[100:101], v[102:103], v[74:75], v[100:101] op_sel_hi:[1,0,1]
	s_nop 0
	s_nop 0
	v_pk_mul_f32 v[102:103], v[162:163], v[100:101] op_sel:[1,1] op_sel_hi:[0,1] neg_hi:[0,1]
	v_pk_fma_f32 v[102:103], v[162:163], v[100:101], v[102:103] op_sel_hi:[1,0,1]
	ds_write_b64 v99, v[102:103] offset:3840
	v_pk_mul_f32 v[102:103], v[78:79], v[100:101] op_sel:[0,1] op_sel_hi:[1,0]
	s_nop 0
	v_pk_fma_f32 v[100:101], v[100:101], v[74:75], v[102:103] op_sel_hi:[1,0,1]
	s_nop 0
	s_nop 0
	v_pk_mul_f32 v[102:103], v[118:119], v[100:101] op_sel:[1,1] op_sel_hi:[0,1] neg_hi:[0,1]
	v_pk_fma_f32 v[102:103], v[118:119], v[100:101], v[102:103] op_sel_hi:[1,0,1]
	ds_write_b64 v98, v[102:103] offset:4096
	v_pk_mul_f32 v[98:99], v[78:79], v[100:101] op_sel:[0,1] op_sel_hi:[1,0]
	s_nop 0
	v_pk_fma_f32 v[98:99], v[100:101], v[74:75], v[98:99] op_sel_hi:[1,0,1]
	s_nop 0
	s_nop 0
	v_pk_mul_f32 v[100:101], v[120:121], v[98:99] op_sel:[1,1] op_sel_hi:[0,1] neg_hi:[0,1]
	v_pk_fma_f32 v[100:101], v[120:121], v[98:99], v[100:101] op_sel_hi:[1,0,1]
	ds_write_b64 v97, v[100:101] offset:4352
	v_pk_mul_f32 v[100:101], v[78:79], v[98:99] op_sel:[0,1] op_sel_hi:[1,0]
	s_nop 0
	v_pk_fma_f32 v[98:99], v[98:99], v[74:75], v[100:101] op_sel_hi:[1,0,1]
	s_nop 0
	s_nop 0
	v_pk_mul_f32 v[100:101], v[142:143], v[98:99] op_sel:[1,1] op_sel_hi:[0,1] neg_hi:[0,1]
	v_pk_fma_f32 v[100:101], v[142:143], v[98:99], v[100:101] op_sel_hi:[1,0,1]
	ds_write_b64 v96, v[100:101] offset:4608
	v_pk_mul_f32 v[96:97], v[78:79], v[98:99] op_sel:[0,1] op_sel_hi:[1,0]
	s_nop 0
	v_pk_fma_f32 v[96:97], v[98:99], v[74:75], v[96:97] op_sel_hi:[1,0,1]
	s_nop 0
	s_nop 0
	v_pk_mul_f32 v[98:99], v[126:127], v[96:97] op_sel:[1,1] op_sel_hi:[0,1] neg_hi:[0,1]
	v_pk_fma_f32 v[98:99], v[126:127], v[96:97], v[98:99] op_sel_hi:[1,0,1]
	ds_write_b64 v95, v[98:99] offset:4864
	v_pk_mul_f32 v[98:99], v[78:79], v[96:97] op_sel:[0,1] op_sel_hi:[1,0]
	s_nop 0
	v_pk_fma_f32 v[96:97], v[96:97], v[74:75], v[98:99] op_sel_hi:[1,0,1]
	s_nop 0
	s_nop 0
	v_pk_mul_f32 v[98:99], v[136:137], v[96:97] op_sel:[1,1] op_sel_hi:[0,1] neg_hi:[0,1]
	v_pk_fma_f32 v[98:99], v[136:137], v[96:97], v[98:99] op_sel_hi:[1,0,1]
	ds_write_b64 v94, v[98:99] offset:5120
	v_pk_mul_f32 v[94:95], v[78:79], v[96:97] op_sel:[0,1] op_sel_hi:[1,0]
	s_nop 0
	v_pk_fma_f32 v[94:95], v[96:97], v[74:75], v[94:95] op_sel_hi:[1,0,1]
	s_nop 0
	s_nop 0
	v_pk_mul_f32 v[96:97], v[122:123], v[94:95] op_sel:[1,1] op_sel_hi:[0,1] neg_hi:[0,1]
	v_pk_fma_f32 v[96:97], v[122:123], v[94:95], v[96:97] op_sel_hi:[1,0,1]
	ds_write_b64 v93, v[96:97] offset:5376
	v_pk_mul_f32 v[96:97], v[78:79], v[94:95] op_sel:[0,1] op_sel_hi:[1,0]
	s_nop 0
	v_pk_fma_f32 v[94:95], v[94:95], v[74:75], v[96:97] op_sel_hi:[1,0,1]
	s_nop 0
	s_nop 0
	v_pk_mul_f32 v[96:97], v[138:139], v[94:95] op_sel:[1,1] op_sel_hi:[0,1] neg_hi:[0,1]
	v_pk_fma_f32 v[96:97], v[138:139], v[94:95], v[96:97] op_sel_hi:[1,0,1]
	ds_write_b64 v92, v[96:97] offset:5632
	v_pk_mul_f32 v[92:93], v[78:79], v[94:95] op_sel:[0,1] op_sel_hi:[1,0]
	s_nop 0
	v_pk_fma_f32 v[92:93], v[94:95], v[74:75], v[92:93] op_sel_hi:[1,0,1]
	s_nop 0
	s_nop 0
	v_pk_mul_f32 v[94:95], v[132:133], v[92:93] op_sel:[1,1] op_sel_hi:[0,1] neg_hi:[0,1]
	v_pk_fma_f32 v[94:95], v[132:133], v[92:93], v[94:95] op_sel_hi:[1,0,1]
	ds_write_b64 v91, v[94:95] offset:5888
	v_pk_mul_f32 v[94:95], v[78:79], v[92:93] op_sel:[0,1] op_sel_hi:[1,0]
	s_nop 0
	v_pk_fma_f32 v[92:93], v[92:93], v[74:75], v[94:95] op_sel_hi:[1,0,1]
	s_nop 0
	s_nop 0
	v_pk_mul_f32 v[94:95], v[82:83], v[92:93] op_sel:[1,1] op_sel_hi:[0,1] neg_hi:[0,1]
	v_pk_fma_f32 v[82:83], v[82:83], v[92:93], v[94:95] op_sel_hi:[1,0,1]
	ds_write_b64 v90, v[82:83] offset:6144
	v_pk_mul_f32 v[82:83], v[78:79], v[92:93] op_sel:[0,1] op_sel_hi:[1,0]
	s_nop 0
	v_pk_fma_f32 v[82:83], v[92:93], v[74:75], v[82:83] op_sel_hi:[1,0,1]
	s_nop 0
	s_nop 0
	v_pk_mul_f32 v[90:91], v[148:149], v[82:83] op_sel:[1,1] op_sel_hi:[0,1] neg_hi:[0,1]
	v_pk_fma_f32 v[90:91], v[148:149], v[82:83], v[90:91] op_sel_hi:[1,0,1]
	ds_write_b64 v89, v[90:91] offset:6400
	v_pk_mul_f32 v[90:91], v[78:79], v[82:83] op_sel:[0,1] op_sel_hi:[1,0]
	s_nop 0
	v_pk_fma_f32 v[82:83], v[82:83], v[74:75], v[90:91] op_sel_hi:[1,0,1]
	s_nop 0
	s_nop 0
	v_pk_mul_f32 v[90:91], v[76:77], v[82:83] op_sel:[1,1] op_sel_hi:[0,1] neg_hi:[0,1]
	v_pk_fma_f32 v[76:77], v[76:77], v[82:83], v[90:91] op_sel_hi:[1,0,1]
	ds_write_b64 v88, v[76:77] offset:6656
	v_pk_mul_f32 v[76:77], v[78:79], v[82:83] op_sel:[0,1] op_sel_hi:[1,0]
	s_nop 0
	v_pk_fma_f32 v[76:77], v[82:83], v[74:75], v[76:77] op_sel_hi:[1,0,1]
	s_nop 0
	s_nop 0
	v_pk_mul_f32 v[82:83], v[80:81], v[76:77] op_sel:[1,1] op_sel_hi:[0,1] neg_hi:[0,1]
	v_pk_fma_f32 v[80:81], v[80:81], v[76:77], v[82:83] op_sel_hi:[1,0,1]
	ds_write_b64 v87, v[80:81] offset:6912
	v_pk_mul_f32 v[80:81], v[78:79], v[76:77] op_sel:[0,1] op_sel_hi:[1,0]
	s_nop 0
	v_pk_fma_f32 v[76:77], v[76:77], v[74:75], v[80:81] op_sel_hi:[1,0,1]
	s_nop 0
	s_nop 0
	v_pk_mul_f32 v[80:81], v[68:69], v[76:77] op_sel:[1,1] op_sel_hi:[0,1] neg_hi:[0,1]
	v_pk_fma_f32 v[68:69], v[68:69], v[76:77], v[80:81] op_sel_hi:[1,0,1]
	ds_write_b64 v86, v[68:69] offset:7168
	v_pk_mul_f32 v[68:69], v[78:79], v[76:77] op_sel:[0,1] op_sel_hi:[1,0]
	s_nop 0
	v_pk_fma_f32 v[68:69], v[76:77], v[74:75], v[68:69] op_sel_hi:[1,0,1]
	s_nop 0
	s_nop 0
	v_pk_mul_f32 v[76:77], v[72:73], v[68:69] op_sel:[1,1] op_sel_hi:[0,1] neg_hi:[0,1]
	v_pk_fma_f32 v[72:73], v[72:73], v[68:69], v[76:77] op_sel_hi:[1,0,1]
	ds_write_b64 v85, v[72:73] offset:7424
	v_pk_mul_f32 v[72:73], v[78:79], v[68:69] op_sel:[0,1] op_sel_hi:[1,0]
	s_nop 0
	v_pk_fma_f32 v[68:69], v[68:69], v[74:75], v[72:73] op_sel_hi:[1,0,1]
	s_nop 0
	s_nop 0
	v_pk_mul_f32 v[72:73], v[66:67], v[68:69] op_sel:[1,1] op_sel_hi:[0,1] neg_hi:[0,1]
	v_pk_fma_f32 v[66:67], v[66:67], v[68:69], v[72:73] op_sel_hi:[1,0,1]
	ds_write_b64 v84, v[66:67] offset:7680
	v_pk_mul_f32 v[66:67], v[78:79], v[68:69] op_sel:[0,1] op_sel_hi:[1,0]
	s_nop 0
	v_pk_fma_f32 v[66:67], v[68:69], v[74:75], v[66:67] op_sel_hi:[1,0,1]
	s_nop 0
	s_nop 0
	v_pk_mul_f32 v[68:69], v[70:71], v[66:67] op_sel:[1,1] op_sel_hi:[0,1] neg_hi:[0,1]
	v_pk_fma_f32 v[66:67], v[70:71], v[66:67], v[68:69] op_sel_hi:[1,0,1]
	ds_write_b64 v0, v[66:67]
	s_waitcnt lgkmcnt(0)
	s_barrier
	ds_read2_b64 v[66:69], v104 offset1:1
	ds_read2_b64 v[70:73], v104 offset0:2 offset1:3
	ds_read2_b64 v[74:77], v104 offset0:4 offset1:5
	ds_read2_b64 v[78:81], v104 offset0:6 offset1:7
	ds_read2_b64 v[82:85], v104 offset0:8 offset1:9
	ds_read2_b64 v[86:89], v104 offset0:10 offset1:11
	ds_read2_b64 v[90:93], v104 offset0:12 offset1:13
	ds_read2_b64 v[94:97], v104 offset0:14 offset1:15
	ds_read2_b64 v[98:101], v104 offset0:16 offset1:17
	ds_read2_b64 v[106:109], v104 offset0:18 offset1:19
	ds_read2_b64 v[110:113], v104 offset0:20 offset1:21
	ds_read2_b64 v[114:117], v104 offset0:22 offset1:23
	ds_read2_b64 v[118:121], v104 offset0:24 offset1:25
	ds_read2_b64 v[122:125], v104 offset0:26 offset1:27
	ds_read2_b64 v[126:129], v104 offset0:28 offset1:29
	ds_read2_b64 v[130:133], v104 offset0:30 offset1:31
	s_waitcnt lgkmcnt(7)
	v_pk_add_f32 v[102:103], v[66:67], v[98:99]
	v_pk_add_f32 v[66:67], v[66:67], v[98:99] neg_lo:[0,1] neg_hi:[0,1]
	v_pk_add_f32 v[98:99], v[68:69], v[100:101]
	v_pk_add_f32 v[68:69], v[68:69], v[100:101] neg_lo:[0,1] neg_hi:[0,1]
	s_nop 0
	v_pk_mul_f32 v[100:101], v[68:69], s[18:19]
	s_nop 0
	v_pk_fma_f32 v[68:69], v[68:69], s[20:21], v[100:101] op_sel:[0,0,1] op_sel_hi:[1,0,0]
	s_waitcnt lgkmcnt(6)
	v_pk_add_f32 v[100:101], v[70:71], v[106:107]
	v_pk_add_f32 v[70:71], v[70:71], v[106:107] neg_lo:[0,1] neg_hi:[0,1]
	s_nop 0
	v_pk_mul_f32 v[106:107], v[70:71], s[4:5]
	s_nop 0
	v_pk_fma_f32 v[70:71], v[70:71], s[6:7], v[106:107] op_sel:[0,0,1] op_sel_hi:[1,0,0]
	v_pk_add_f32 v[106:107], v[72:73], v[108:109]
	v_pk_add_f32 v[72:73], v[72:73], v[108:109] neg_lo:[0,1] neg_hi:[0,1]
	s_nop 0
	v_pk_mul_f32 v[108:109], v[72:73], s[22:23]
	s_nop 0
	v_pk_fma_f32 v[72:73], v[72:73], s[24:25], v[108:109] op_sel:[0,0,1] op_sel_hi:[1,0,0]
	s_waitcnt lgkmcnt(5)
	v_pk_add_f32 v[108:109], v[74:75], v[110:111]
	v_pk_add_f32 v[74:75], v[74:75], v[110:111] neg_lo:[0,1] neg_hi:[0,1]
	s_nop 0
	v_pk_mul_f32 v[110:111], v[74:75], s[8:9]
	s_nop 0
	v_pk_fma_f32 v[74:75], v[74:75], s[10:11], v[110:111] op_sel:[0,0,1] op_sel_hi:[1,0,0]
	v_pk_add_f32 v[110:111], v[76:77], v[112:113]
	v_pk_add_f32 v[76:77], v[76:77], v[112:113] neg_lo:[0,1] neg_hi:[0,1]
	s_nop 0
	v_pk_mul_f32 v[112:113], v[76:77], s[26:27]
	s_nop 0
	v_pk_fma_f32 v[76:77], v[76:77], s[0:1], v[112:113] op_sel:[0,0,1] op_sel_hi:[1,0,0]
	s_waitcnt lgkmcnt(4)
	v_pk_add_f32 v[112:113], v[78:79], v[114:115]
	v_pk_add_f32 v[78:79], v[78:79], v[114:115] neg_lo:[0,1] neg_hi:[0,1]
	s_mov_b64 s[0:1], 0
	v_pk_mul_f32 v[114:115], v[78:79], s[12:13]
	s_nop 0
	v_pk_fma_f32 v[78:79], v[78:79], s[14:15], v[114:115] op_sel:[0,0,1] op_sel_hi:[1,0,0]
	v_pk_add_f32 v[114:115], v[80:81], v[116:117]
	v_pk_add_f32 v[80:81], v[80:81], v[116:117] neg_lo:[0,1] neg_hi:[0,1]
	s_nop 0
	v_pk_mul_f32 v[116:117], v[80:81], s[34:35]
	s_nop 0
	v_pk_fma_f32 v[80:81], v[80:81], s[44:45], v[116:117] op_sel:[0,0,1] op_sel_hi:[1,0,0]
	s_waitcnt lgkmcnt(3)
	v_pk_add_f32 v[116:117], v[82:83], v[118:119]
	v_pk_add_f32 v[118:119], v[82:83], v[118:119] op_sel:[1,1] op_sel_hi:[0,0] neg_lo:[0,1] neg_hi:[1,0]
	s_mov_b64 s[44:45], -1
	v_pk_add_f32 v[82:83], v[84:85], v[120:121]
	v_pk_add_f32 v[84:85], v[84:85], v[120:121] neg_lo:[0,1] neg_hi:[0,1]
	s_nop 0
	v_pk_mul_f32 v[120:121], v[84:85], s[34:35]
	s_nop 0
	v_pk_fma_f32 v[84:85], v[84:85], s[18:19], v[120:121] op_sel:[0,0,1] op_sel_hi:[1,0,0]
	s_waitcnt lgkmcnt(2)
	v_pk_add_f32 v[120:121], v[86:87], v[122:123]
	v_pk_add_f32 v[86:87], v[86:87], v[122:123] neg_lo:[0,1] neg_hi:[0,1]
	s_nop 0
	v_pk_mul_f32 v[122:123], v[86:87], s[12:13]
	s_nop 0
	v_pk_fma_f32 v[86:87], v[86:87], s[4:5], v[122:123] op_sel:[0,0,1] op_sel_hi:[1,0,0]
	v_pk_add_f32 v[122:123], v[88:89], v[124:125]
	v_pk_add_f32 v[88:89], v[88:89], v[124:125] neg_lo:[0,1] neg_hi:[0,1]
	s_nop 0
	v_pk_mul_f32 v[124:125], v[88:89], s[26:27]
	s_nop 0
	v_pk_fma_f32 v[88:89], v[88:89], s[22:23], v[124:125] op_sel:[0,0,1] op_sel_hi:[1,0,0]
	s_waitcnt lgkmcnt(1)
	v_pk_add_f32 v[124:125], v[90:91], v[126:127]
	v_pk_add_f32 v[90:91], v[90:91], v[126:127] neg_lo:[0,1] neg_hi:[0,1]
	s_nop 0
	v_pk_mul_f32 v[126:127], v[90:91], s[8:9]
	s_nop 0
	v_pk_fma_f32 v[90:91], v[90:91], s[8:9], v[126:127] op_sel:[0,0,1] op_sel_hi:[1,0,0]
	v_pk_add_f32 v[126:127], v[92:93], v[128:129]
	v_pk_add_f32 v[92:93], v[92:93], v[128:129] neg_lo:[0,1] neg_hi:[0,1]
	s_nop 0
	v_pk_mul_f32 v[128:129], v[92:93], s[22:23]
	s_nop 0
	v_pk_fma_f32 v[92:93], v[92:93], s[26:27], v[128:129] op_sel:[0,0,1] op_sel_hi:[1,0,0]
	s_waitcnt lgkmcnt(0)
	v_pk_add_f32 v[128:129], v[94:95], v[130:131]
	v_pk_add_f32 v[94:95], v[94:95], v[130:131] neg_lo:[0,1] neg_hi:[0,1]
	s_nop 0
	v_pk_mul_f32 v[130:131], v[94:95], s[4:5]
	s_nop 0
	v_pk_fma_f32 v[94:95], v[94:95], s[12:13], v[130:131] op_sel:[0,0,1] op_sel_hi:[1,0,0]
	v_pk_add_f32 v[130:131], v[96:97], v[132:133]
	v_pk_add_f32 v[96:97], v[96:97], v[132:133] neg_lo:[0,1] neg_hi:[0,1]
	s_nop 0
	v_pk_mul_f32 v[132:133], v[96:97], s[18:19]
	s_nop 0
	v_pk_fma_f32 v[96:97], v[96:97], s[34:35], v[132:133] op_sel:[0,0,1] op_sel_hi:[1,0,0]
	v_pk_add_f32 v[132:133], v[102:103], v[116:117]
	v_pk_add_f32 v[102:103], v[102:103], v[116:117] neg_lo:[0,1] neg_hi:[0,1]
	v_pk_add_f32 v[116:117], v[98:99], v[82:83]
	v_pk_add_f32 v[82:83], v[98:99], v[82:83] neg_lo:[0,1] neg_hi:[0,1]
	s_nop 0
	v_pk_mul_f32 v[98:99], v[82:83], s[4:5]
	s_nop 0
	v_pk_fma_f32 v[82:83], v[82:83], s[6:7], v[98:99] op_sel:[0,0,1] op_sel_hi:[1,0,0]
	v_pk_add_f32 v[98:99], v[100:101], v[120:121]
	v_pk_add_f32 v[100:101], v[100:101], v[120:121] neg_lo:[0,1] neg_hi:[0,1]
	s_nop 0
	v_pk_mul_f32 v[120:121], v[100:101], s[8:9]
	s_nop 0
	v_pk_fma_f32 v[100:101], v[100:101], s[10:11], v[120:121] op_sel:[0,0,1] op_sel_hi:[1,0,0]
	v_pk_add_f32 v[120:121], v[106:107], v[122:123]
	v_pk_add_f32 v[106:107], v[106:107], v[122:123] neg_lo:[0,1] neg_hi:[0,1]
	s_nop 0
	v_pk_mul_f32 v[122:123], v[106:107], s[12:13]
	s_nop 0
	v_pk_fma_f32 v[106:107], v[106:107], s[14:15], v[122:123] op_sel:[0,0,1] op_sel_hi:[1,0,0]
	v_pk_add_f32 v[122:123], v[108:109], v[124:125]
	v_pk_add_f32 v[124:125], v[108:109], v[124:125] op_sel:[1,1] op_sel_hi:[0,0] neg_lo:[0,1] neg_hi:[1,0]
	s_nop 0
	v_pk_add_f32 v[108:109], v[110:111], v[126:127]
	v_pk_add_f32 v[110:111], v[110:111], v[126:127] neg_lo:[0,1] neg_hi:[0,1]
	s_nop 0
	v_pk_mul_f32 v[126:127], v[110:111], s[12:13]
	s_nop 0
	v_pk_fma_f32 v[110:111], v[110:111], s[4:5], v[126:127] op_sel:[0,0,1] op_sel_hi:[1,0,0]
	v_pk_add_f32 v[126:127], v[112:113], v[128:129]
	v_pk_add_f32 v[112:113], v[112:113], v[128:129] neg_lo:[0,1] neg_hi:[0,1]
	s_nop 0
	v_pk_mul_f32 v[128:129], v[112:113], s[8:9]
	s_nop 0
	v_pk_fma_f32 v[112:113], v[112:113], s[8:9], v[128:129] op_sel:[0,0,1] op_sel_hi:[1,0,0]
	v_pk_add_f32 v[128:129], v[114:115], v[130:131]
	v_pk_add_f32 v[114:115], v[114:115], v[130:131] neg_lo:[0,1] neg_hi:[0,1]
	s_nop 0
	v_pk_mul_f32 v[130:131], v[114:115], s[4:5]
	s_nop 0
	v_pk_fma_f32 v[114:115], v[114:115], s[12:13], v[130:131] op_sel:[0,0,1] op_sel_hi:[1,0,0]
	v_pk_add_f32 v[130:131], v[66:67], v[118:119]
	v_pk_add_f32 v[66:67], v[66:67], v[118:119] neg_lo:[0,1] neg_hi:[0,1]
	v_pk_add_f32 v[118:119], v[68:69], v[84:85]
	v_pk_add_f32 v[68:69], v[68:69], v[84:85] neg_lo:[0,1] neg_hi:[0,1]
	s_nop 0
	v_pk_mul_f32 v[84:85], v[68:69], s[4:5]
	s_nop 0
	v_pk_fma_f32 v[68:69], v[68:69], s[6:7], v[84:85] op_sel:[0,0,1] op_sel_hi:[1,0,0]
	v_pk_add_f32 v[84:85], v[70:71], v[86:87]
	v_pk_add_f32 v[70:71], v[70:71], v[86:87] neg_lo:[0,1] neg_hi:[0,1]
	s_nop 0
	v_pk_mul_f32 v[86:87], v[70:71], s[8:9]
	s_nop 0
	v_pk_fma_f32 v[70:71], v[70:71], s[10:11], v[86:87] op_sel:[0,0,1] op_sel_hi:[1,0,0]
	v_pk_add_f32 v[86:87], v[72:73], v[88:89]
	v_pk_add_f32 v[72:73], v[72:73], v[88:89] neg_lo:[0,1] neg_hi:[0,1]
	s_nop 0
	v_pk_mul_f32 v[88:89], v[72:73], s[12:13]
	s_nop 0
	v_pk_fma_f32 v[72:73], v[72:73], s[14:15], v[88:89] op_sel:[0,0,1] op_sel_hi:[1,0,0]
	v_pk_add_f32 v[88:89], v[74:75], v[90:91]
	v_pk_add_f32 v[90:91], v[74:75], v[90:91] op_sel:[1,1] op_sel_hi:[0,0] neg_lo:[0,1] neg_hi:[1,0]
	s_nop 0
	v_pk_add_f32 v[74:75], v[76:77], v[92:93]
	v_pk_add_f32 v[76:77], v[76:77], v[92:93] neg_lo:[0,1] neg_hi:[0,1]
	s_nop 0
	v_pk_mul_f32 v[92:93], v[76:77], s[12:13]
	s_nop 0
	v_pk_fma_f32 v[76:77], v[76:77], s[4:5], v[92:93] op_sel:[0,0,1] op_sel_hi:[1,0,0]
	v_pk_add_f32 v[92:93], v[78:79], v[94:95]
	v_pk_add_f32 v[78:79], v[78:79], v[94:95] neg_lo:[0,1] neg_hi:[0,1]
	s_nop 0
	v_pk_mul_f32 v[94:95], v[78:79], s[8:9]
	s_nop 0
	v_pk_fma_f32 v[78:79], v[78:79], s[8:9], v[94:95] op_sel:[0,0,1] op_sel_hi:[1,0,0]
	v_pk_add_f32 v[94:95], v[80:81], v[96:97]
	v_pk_add_f32 v[80:81], v[80:81], v[96:97] neg_lo:[0,1] neg_hi:[0,1]
	s_nop 0
	v_pk_mul_f32 v[96:97], v[80:81], s[4:5]
	s_nop 0
	v_pk_fma_f32 v[80:81], v[80:81], s[12:13], v[96:97] op_sel:[0,0,1] op_sel_hi:[1,0,0]
	v_pk_add_f32 v[96:97], v[132:133], v[122:123]
	v_pk_add_f32 v[122:123], v[132:133], v[122:123] neg_lo:[0,1] neg_hi:[0,1]
	v_pk_add_f32 v[132:133], v[116:117], v[108:109]
	v_pk_add_f32 v[108:109], v[116:117], v[108:109] neg_lo:[0,1] neg_hi:[0,1]
	s_nop 0
	v_pk_mul_f32 v[116:117], v[108:109], s[8:9]
	s_nop 0
	v_pk_fma_f32 v[108:109], v[108:109], s[10:11], v[116:117] op_sel:[0,0,1] op_sel_hi:[1,0,0]
	v_pk_add_f32 v[116:117], v[98:99], v[126:127]
	v_pk_add_f32 v[126:127], v[98:99], v[126:127] op_sel:[1,1] op_sel_hi:[0,0] neg_lo:[0,1] neg_hi:[1,0]
	s_nop 0
	v_pk_add_f32 v[98:99], v[120:121], v[128:129]
	v_pk_add_f32 v[120:121], v[120:121], v[128:129] neg_lo:[0,1] neg_hi:[0,1]
	s_nop 0
	v_pk_mul_f32 v[128:129], v[120:121], s[8:9]
	s_nop 0
	v_pk_fma_f32 v[120:121], v[120:121], s[8:9], v[128:129] op_sel:[0,0,1] op_sel_hi:[1,0,0]
	v_pk_add_f32 v[128:129], v[102:103], v[124:125]
	v_pk_add_f32 v[102:103], v[102:103], v[124:125] neg_lo:[0,1] neg_hi:[0,1]
	v_pk_add_f32 v[124:125], v[82:83], v[110:111]
	v_pk_add_f32 v[82:83], v[82:83], v[110:111] neg_lo:[0,1] neg_hi:[0,1]
	s_nop 0
	v_pk_mul_f32 v[110:111], v[82:83], s[8:9]
	s_nop 0
	v_pk_fma_f32 v[82:83], v[82:83], s[10:11], v[110:111] op_sel:[0,0,1] op_sel_hi:[1,0,0]
	v_pk_add_f32 v[110:111], v[100:101], v[112:113]
	v_pk_add_f32 v[112:113], v[100:101], v[112:113] op_sel:[1,1] op_sel_hi:[0,0] neg_lo:[0,1] neg_hi:[1,0]
	s_nop 0
	v_pk_add_f32 v[100:101], v[106:107], v[114:115]
	v_pk_add_f32 v[106:107], v[106:107], v[114:115] neg_lo:[0,1] neg_hi:[0,1]
	s_nop 0
	v_pk_mul_f32 v[114:115], v[106:107], s[8:9]
	s_nop 0
	v_pk_fma_f32 v[106:107], v[106:107], s[8:9], v[114:115] op_sel:[0,0,1] op_sel_hi:[1,0,0]
	v_pk_add_f32 v[114:115], v[130:131], v[88:89]
	v_pk_add_f32 v[88:89], v[130:131], v[88:89] neg_lo:[0,1] neg_hi:[0,1]
	v_pk_add_f32 v[130:131], v[118:119], v[74:75]
	v_pk_add_f32 v[74:75], v[118:119], v[74:75] neg_lo:[0,1] neg_hi:[0,1]
	s_nop 0
	v_pk_mul_f32 v[118:119], v[74:75], s[8:9]
	s_nop 0
	v_pk_fma_f32 v[74:75], v[74:75], s[10:11], v[118:119] op_sel:[0,0,1] op_sel_hi:[1,0,0]
	v_pk_add_f32 v[118:119], v[84:85], v[92:93]
	v_pk_add_f32 v[92:93], v[84:85], v[92:93] op_sel:[1,1] op_sel_hi:[0,0] neg_lo:[0,1] neg_hi:[1,0]
	s_nop 0
	v_pk_add_f32 v[84:85], v[86:87], v[94:95]
	v_pk_add_f32 v[86:87], v[86:87], v[94:95] neg_lo:[0,1] neg_hi:[0,1]
	s_nop 0
	v_pk_mul_f32 v[94:95], v[86:87], s[8:9]
	s_nop 0
	v_pk_fma_f32 v[86:87], v[86:87], s[8:9], v[94:95] op_sel:[0,0,1] op_sel_hi:[1,0,0]
	v_pk_add_f32 v[94:95], v[66:67], v[90:91]
	v_pk_add_f32 v[66:67], v[66:67], v[90:91] neg_lo:[0,1] neg_hi:[0,1]
	v_pk_add_f32 v[90:91], v[68:69], v[76:77]
	v_pk_add_f32 v[68:69], v[68:69], v[76:77] neg_lo:[0,1] neg_hi:[0,1]
	s_nop 0
	v_pk_mul_f32 v[76:77], v[68:69], s[8:9]
	s_nop 0
	v_pk_fma_f32 v[68:69], v[68:69], s[10:11], v[76:77] op_sel:[0,0,1] op_sel_hi:[1,0,0]
	v_pk_add_f32 v[76:77], v[70:71], v[78:79]
	v_pk_add_f32 v[78:79], v[70:71], v[78:79] op_sel:[1,1] op_sel_hi:[0,0] neg_lo:[0,1] neg_hi:[1,0]
	s_nop 0
	v_pk_add_f32 v[70:71], v[72:73], v[80:81]
	v_pk_add_f32 v[72:73], v[72:73], v[80:81] neg_lo:[0,1] neg_hi:[0,1]
	s_nop 0
	v_pk_mul_f32 v[80:81], v[72:73], s[8:9]
	s_nop 0
	v_pk_fma_f32 v[72:73], v[72:73], s[8:9], v[80:81] op_sel:[0,0,1] op_sel_hi:[1,0,0]
	v_pk_add_f32 v[80:81], v[96:97], v[116:117]
	v_pk_add_f32 v[96:97], v[96:97], v[116:117] neg_lo:[0,1] neg_hi:[0,1]
	v_pk_add_f32 v[116:117], v[132:133], v[98:99]
	v_pk_add_f32 v[132:133], v[132:133], v[98:99] op_sel:[1,1] op_sel_hi:[0,0] neg_lo:[0,1] neg_hi:[1,0]
	s_nop 0
	v_pk_add_f32 v[98:99], v[122:123], v[126:127]
	v_pk_add_f32 v[122:123], v[122:123], v[126:127] neg_lo:[0,1] neg_hi:[0,1]
	v_pk_add_f32 v[126:127], v[108:109], v[120:121]
	v_pk_add_f32 v[120:121], v[108:109], v[120:121] op_sel:[1,1] op_sel_hi:[0,0] neg_lo:[0,1] neg_hi:[1,0]
	s_nop 0
	v_pk_add_f32 v[108:109], v[128:129], v[110:111]
	v_pk_add_f32 v[110:111], v[128:129], v[110:111] neg_lo:[0,1] neg_hi:[0,1]
	v_pk_add_f32 v[128:129], v[124:125], v[100:101]
	v_pk_add_f32 v[124:125], v[124:125], v[100:101] op_sel:[1,1] op_sel_hi:[0,0] neg_lo:[0,1] neg_hi:[1,0]
	s_nop 0
	v_pk_add_f32 v[100:101], v[102:103], v[112:113]
	v_pk_add_f32 v[102:103], v[102:103], v[112:113] neg_lo:[0,1] neg_hi:[0,1]
	v_pk_add_f32 v[112:113], v[82:83], v[106:107]
	v_pk_add_f32 v[106:107], v[82:83], v[106:107] op_sel:[1,1] op_sel_hi:[0,0] neg_lo:[0,1] neg_hi:[1,0]
	s_nop 0
	v_pk_add_f32 v[82:83], v[114:115], v[118:119]
	v_pk_add_f32 v[114:115], v[114:115], v[118:119] neg_lo:[0,1] neg_hi:[0,1]
	v_pk_add_f32 v[118:119], v[130:131], v[84:85]
	v_pk_add_f32 v[130:131], v[130:131], v[84:85] op_sel:[1,1] op_sel_hi:[0,0] neg_lo:[0,1] neg_hi:[1,0]
	s_nop 0
	v_pk_add_f32 v[84:85], v[88:89], v[92:93]
	v_pk_add_f32 v[88:89], v[88:89], v[92:93] neg_lo:[0,1] neg_hi:[0,1]
	v_pk_add_f32 v[92:93], v[74:75], v[86:87]
	v_pk_add_f32 v[86:87], v[74:75], v[86:87] op_sel:[1,1] op_sel_hi:[0,0] neg_lo:[0,1] neg_hi:[1,0]
	s_nop 0
	v_pk_add_f32 v[74:75], v[94:95], v[76:77]
	v_pk_add_f32 v[76:77], v[94:95], v[76:77] neg_lo:[0,1] neg_hi:[0,1]
	v_pk_add_f32 v[94:95], v[90:91], v[70:71]
	v_pk_add_f32 v[90:91], v[90:91], v[70:71] op_sel:[1,1] op_sel_hi:[0,0] neg_lo:[0,1] neg_hi:[1,0]
	s_nop 0
	v_pk_add_f32 v[70:71], v[66:67], v[78:79]
	v_pk_add_f32 v[66:67], v[66:67], v[78:79] neg_lo:[0,1] neg_hi:[0,1]
	v_pk_add_f32 v[78:79], v[68:69], v[72:73]
	v_pk_add_f32 v[72:73], v[68:69], v[72:73] op_sel:[1,1] op_sel_hi:[0,0] neg_lo:[0,1] neg_hi:[1,0]
	s_nop 0
	v_pk_add_f32 v[68:69], v[80:81], v[116:117]
	v_pk_add_f32 v[80:81], v[80:81], v[116:117] neg_lo:[0,1] neg_hi:[0,1]
	v_pk_add_f32 v[116:117], v[96:97], v[132:133]
	v_pk_add_f32 v[96:97], v[96:97], v[132:133] neg_lo:[0,1] neg_hi:[0,1]
	v_pk_add_f32 v[132:133], v[98:99], v[126:127]
	v_pk_add_f32 v[98:99], v[98:99], v[126:127] neg_lo:[0,1] neg_hi:[0,1]
	v_pk_add_f32 v[126:127], v[122:123], v[120:121]
	v_pk_add_f32 v[120:121], v[122:123], v[120:121] neg_lo:[0,1] neg_hi:[0,1]
	v_pk_add_f32 v[122:123], v[108:109], v[128:129]
	v_pk_add_f32 v[108:109], v[108:109], v[128:129] neg_lo:[0,1] neg_hi:[0,1]
	v_pk_add_f32 v[128:129], v[110:111], v[124:125]
	v_pk_add_f32 v[110:111], v[110:111], v[124:125] neg_lo:[0,1] neg_hi:[0,1]
	v_pk_add_f32 v[124:125], v[100:101], v[112:113]
	v_pk_add_f32 v[100:101], v[100:101], v[112:113] neg_lo:[0,1] neg_hi:[0,1]
	v_pk_add_f32 v[112:113], v[102:103], v[106:107]
	v_pk_add_f32 v[102:103], v[102:103], v[106:107] neg_lo:[0,1] neg_hi:[0,1]
	v_pk_add_f32 v[106:107], v[82:83], v[118:119]
	v_pk_mul_f32 v[68:69], v[68:69], s[2:3] op_sel_hi:[1,0]
	global_store_dwordx2 v[2:3], v[68:69], off
	v_pk_mul_f32 v[68:69], v[106:107], s[2:3] op_sel_hi:[1,0]
	v_pk_add_f32 v[82:83], v[82:83], v[118:119] neg_lo:[0,1] neg_hi:[0,1]
	v_pk_add_f32 v[118:119], v[114:115], v[130:131]
	v_pk_add_f32 v[114:115], v[114:115], v[130:131] neg_lo:[0,1] neg_hi:[0,1]
	v_pk_add_f32 v[130:131], v[84:85], v[92:93]
	v_pk_add_f32 v[84:85], v[84:85], v[92:93] neg_lo:[0,1] neg_hi:[0,1]
	v_pk_add_f32 v[92:93], v[88:89], v[86:87]
	v_pk_add_f32 v[86:87], v[88:89], v[86:87] neg_lo:[0,1] neg_hi:[0,1]
	v_pk_add_f32 v[88:89], v[74:75], v[94:95]
	global_store_dwordx2 v[4:5], v[68:69], off
	v_pk_mul_f32 v[68:69], v[122:123], s[2:3] op_sel_hi:[1,0]
	global_store_dwordx2 v[6:7], v[68:69], off
	v_pk_mul_f32 v[68:69], v[88:89], s[2:3] op_sel_hi:[1,0]
	global_store_dwordx2 v[8:9], v[68:69], off
	v_pk_mul_f32 v[68:69], v[132:133], s[2:3] op_sel_hi:[1,0]
	global_store_dwordx2 v[10:11], v[68:69], off
	v_pk_mul_f32 v[68:69], v[130:131], s[2:3] op_sel_hi:[1,0]
	v_pk_add_f32 v[74:75], v[74:75], v[94:95] neg_lo:[0,1] neg_hi:[0,1]
	v_pk_add_f32 v[94:95], v[76:77], v[90:91]
	v_pk_add_f32 v[76:77], v[76:77], v[90:91] neg_lo:[0,1] neg_hi:[0,1]
	v_pk_add_f32 v[90:91], v[70:71], v[78:79]
	global_store_dwordx2 v[12:13], v[68:69], off
	v_pk_mul_f32 v[68:69], v[124:125], s[2:3] op_sel_hi:[1,0]
	global_store_dwordx2 v[14:15], v[68:69], off
	v_pk_mul_f32 v[68:69], v[90:91], s[2:3] op_sel_hi:[1,0]
	global_store_dwordx2 v[16:17], v[68:69], off
	v_pk_mul_f32 v[68:69], v[116:117], s[2:3] op_sel_hi:[1,0]
	global_store_dwordx2 v[18:19], v[68:69], off
	v_pk_mul_f32 v[68:69], v[118:119], s[2:3] op_sel_hi:[1,0]
	global_store_dwordx2 v[20:21], v[68:69], off
	v_pk_mul_f32 v[68:69], v[128:129], s[2:3] op_sel_hi:[1,0]
	global_store_dwordx2 v[22:23], v[68:69], off
	v_pk_mul_f32 v[68:69], v[94:95], s[2:3] op_sel_hi:[1,0]
	global_store_dwordx2 v[24:25], v[68:69], off
	v_pk_mul_f32 v[68:69], v[126:127], s[2:3] op_sel_hi:[1,0]
	global_store_dwordx2 v[26:27], v[68:69], off
	v_pk_mul_f32 v[68:69], v[92:93], s[2:3] op_sel_hi:[1,0]
	v_pk_add_f32 v[70:71], v[70:71], v[78:79] neg_lo:[0,1] neg_hi:[0,1]
	v_pk_add_f32 v[78:79], v[66:67], v[72:73]
	global_store_dwordx2 v[28:29], v[68:69], off
	v_pk_mul_f32 v[68:69], v[112:113], s[2:3] op_sel_hi:[1,0]
	global_store_dwordx2 v[30:31], v[68:69], off
	v_pk_mul_f32 v[68:69], v[78:79], s[2:3] op_sel_hi:[1,0]
	global_store_dwordx2 v[32:33], v[68:69], off
	v_pk_mul_f32 v[68:69], v[80:81], s[2:3] op_sel_hi:[1,0]
	global_store_dwordx2 v[34:35], v[68:69], off
	v_pk_mul_f32 v[68:69], v[82:83], s[2:3] op_sel_hi:[1,0]
	global_store_dwordx2 v[36:37], v[68:69], off
	v_pk_mul_f32 v[68:69], v[108:109], s[2:3] op_sel_hi:[1,0]
	global_store_dwordx2 v[38:39], v[68:69], off
	v_pk_mul_f32 v[68:69], v[74:75], s[2:3] op_sel_hi:[1,0]
	global_store_dwordx2 v[40:41], v[68:69], off
	v_pk_mul_f32 v[68:69], v[98:99], s[2:3] op_sel_hi:[1,0]
	global_store_dwordx2 v[42:43], v[68:69], off
	v_pk_mul_f32 v[68:69], v[84:85], s[2:3] op_sel_hi:[1,0]
	global_store_dwordx2 v[44:45], v[68:69], off
	v_pk_mul_f32 v[68:69], v[100:101], s[2:3] op_sel_hi:[1,0]
	global_store_dwordx2 v[46:47], v[68:69], off
	v_pk_mul_f32 v[68:69], v[70:71], s[2:3] op_sel_hi:[1,0]
	global_store_dwordx2 v[48:49], v[68:69], off
	v_pk_mul_f32 v[68:69], v[96:97], s[2:3] op_sel_hi:[1,0]
	global_store_dwordx2 v[50:51], v[68:69], off
	v_pk_mul_f32 v[68:69], v[114:115], s[2:3] op_sel_hi:[1,0]
	global_store_dwordx2 v[52:53], v[68:69], off
	v_pk_mul_f32 v[68:69], v[110:111], s[2:3] op_sel_hi:[1,0]
	global_store_dwordx2 v[54:55], v[68:69], off
	v_pk_mul_f32 v[68:69], v[76:77], s[2:3] op_sel_hi:[1,0]
	global_store_dwordx2 v[56:57], v[68:69], off
	v_pk_mul_f32 v[68:69], v[120:121], s[2:3] op_sel_hi:[1,0]
	v_pk_add_f32 v[66:67], v[66:67], v[72:73] neg_lo:[0,1] neg_hi:[0,1]
	global_store_dwordx2 v[58:59], v[68:69], off
	v_pk_mul_f32 v[68:69], v[86:87], s[2:3] op_sel_hi:[1,0]
	global_store_dwordx2 v[60:61], v[68:69], off
	v_pk_mul_f32 v[68:69], v[102:103], s[2:3] op_sel_hi:[1,0]
	v_pk_mul_f32 v[66:67], v[66:67], s[2:3] op_sel_hi:[1,0]
	global_store_dwordx2 v[62:63], v[68:69], off
	global_store_dwordx2 v[64:65], v[66:67], off
	s_barrier

.Lmy_fft_hj:
	v_mov_b32 v66, 0
	s_movk_i32 s5, 0x200
	v_add_u32_e32 v0, v66, v0
	v_cvt_f32_i32_e32 v68, v0
	v_ashrrev_i32_e32 v66, 5, v0
	v_lshlrev_b32_e32 v67, 3, v0
	v_add_u32_e32 v69, 0x400, v0
	v_add_u32_e32 v70, 0x800, v0
	v_add_u32_e32 v71, 0xc00, v0
	v_add_u32_e32 v72, 0x1000, v0
	v_add_u32_e32 v73, 0x1400, v0
	v_add_u32_e32 v74, 0x1800, v0
	v_add_u32_e32 v75, 0x1c00, v0
	v_add_u32_e32 v76, 0x2000, v0
	v_add_u32_e32 v77, 0x2400, v0
	v_add_u32_e32 v78, 0x2800, v0
	v_add_u32_e32 v79, 0x2c00, v0
	v_add_u32_e32 v80, 0x3000, v0
	v_add_u32_e32 v81, 0x3400, v0
	v_add_u32_e32 v82, 0x3800, v0
	v_add_u32_e32 v0, 0x3c00, v0
	v_lshlrev_b32_e32 v66, 3, v66
	v_ashrrev_i32_e32 v69, 5, v69
	v_ashrrev_i32_e32 v70, 5, v70
	v_ashrrev_i32_e32 v71, 5, v71
	v_ashrrev_i32_e32 v72, 5, v72
	v_ashrrev_i32_e32 v73, 5, v73
	v_ashrrev_i32_e32 v74, 5, v74
	v_ashrrev_i32_e32 v75, 5, v75
	v_ashrrev_i32_e32 v83, 5, v76
	v_ashrrev_i32_e32 v84, 5, v77
	v_ashrrev_i32_e32 v85, 5, v78
	v_ashrrev_i32_e32 v86, 5, v79
	v_ashrrev_i32_e32 v87, 5, v80
	v_ashrrev_i32_e32 v88, 5, v81
	v_ashrrev_i32_e32 v89, 5, v82
	v_ashrrev_i32_e32 v90, 5, v0
	v_lshlrev_b32_e32 v0, 3, v0
	v_add3_u32 v171, 0, v66, v67
	v_lshlrev_b32_e32 v66, 3, v69
	v_lshlrev_b32_e32 v69, 3, v70
	v_lshlrev_b32_e32 v70, 3, v71
	v_lshlrev_b32_e32 v71, 3, v72
	v_lshlrev_b32_e32 v72, 3, v73
	v_lshlrev_b32_e32 v73, 3, v74
	v_lshlrev_b32_e32 v74, 3, v75
	v_lshlrev_b32_e32 v75, 3, v83
	v_lshlrev_b32_e32 v83, 3, v84
	v_lshlrev_b32_e32 v84, 3, v85
	v_lshlrev_b32_e32 v85, 3, v86
	v_lshlrev_b32_e32 v86, 3, v87
	v_lshlrev_b32_e32 v87, 3, v88
	v_lshlrev_b32_e32 v88, 3, v89
	v_lshlrev_b32_e32 v89, 3, v90
	v_add3_u32 v186, 0, v89, v0
	v_mul_f32_e32 v0, 0x38800000, v68
	v_add3_u32 v172, 0, v66, v67
	v_add3_u32 v173, 0, v69, v67
	v_add3_u32 v174, 0, v70, v67
	v_add3_u32 v175, 0, v71, v67
	v_add3_u32 v176, 0, v72, v67
	v_add3_u32 v177, 0, v73, v67
	v_add3_u32 v178, 0, v74, v67
	v_sin_f32_e32 v67, v0
	v_cos_f32_e32 v66, v0
	v_lshlrev_b32_e32 v76, 3, v76
	v_add3_u32 v179, 0, v75, v76
	v_xor_b32_e32 v68, 0x80000000, v67
	v_mov_b32_e32 v69, v67
	v_pk_mul_f32 v[70:71], v[68:69], v[66:67] op_sel:[0,1] op_sel_hi:[1,0]
	v_lshlrev_b32_e32 v78, 3, v78
	v_pk_fma_f32 v[70:71], v[66:67], v[66:67], v[70:71] op_sel_hi:[1,0,1]
	v_lshlrev_b32_e32 v79, 3, v79
	v_pk_mul_f32 v[74:75], v[68:69], v[70:71] op_sel:[0,1] op_sel_hi:[1,0]
	v_add3_u32 v181, 0, v84, v78
	v_pk_fma_f32 v[74:75], v[70:71], v[66:67], v[74:75] op_sel_hi:[1,0,1]
	v_add3_u32 v182, 0, v85, v79
	v_pk_mul_f32 v[78:79], v[68:69], v[74:75] op_sel:[0,1] op_sel_hi:[1,0]
	v_lshlrev_b32_e32 v77, 3, v77
	v_lshlrev_b32_e32 v82, 3, v82
	v_pk_fma_f32 v[78:79], v[74:75], v[66:67], v[78:79] op_sel_hi:[1,0,1]
	v_add3_u32 v180, 0, v83, v77
	v_add3_u32 v185, 0, v88, v82
	v_pk_mul_f32 v[82:83], v[68:69], v[78:79] op_sel:[0,1] op_sel_hi:[1,0]
	v_lshlrev_b32_e32 v80, 3, v80
	v_lshlrev_b32_e32 v81, 3, v81
	v_pk_fma_f32 v[82:83], v[78:79], v[66:67], v[82:83] op_sel_hi:[1,0,1]
	v_add3_u32 v183, 0, v86, v80
	v_add3_u32 v184, 0, v87, v81
	v_pk_mul_f32 v[86:87], v[68:69], v[82:83] op_sel:[0,1] op_sel_hi:[1,0]
	s_waitcnt vmcnt(31)
	v_lshlrev_b32_e32 v126, 16, v105
	v_pk_fma_f32 v[86:87], v[82:83], v[66:67], v[86:87] op_sel_hi:[1,0,1]
	s_waitcnt vmcnt(30)
	v_lshlrev_b32_e32 v127, 16, v127
	v_pk_mul_f32 v[90:91], v[68:69], v[86:87] op_sel:[0,1] op_sel_hi:[1,0]
	s_waitcnt vmcnt(29)
	v_lshlrev_b32_e32 v129, 16, v128
	v_pk_fma_f32 v[90:91], v[86:87], v[66:67], v[90:91] op_sel_hi:[1,0,1]
	s_waitcnt vmcnt(24)
	v_lshlrev_b32_e32 v128, 16, v134
	v_pk_mul_f32 v[94:95], v[68:69], v[90:91] op_sel:[0,1] op_sel_hi:[1,0]
	v_lshlrev_b32_e32 v130, 16, v130
	v_pk_fma_f32 v[94:95], v[90:91], v[66:67], v[94:95] op_sel_hi:[1,0,1]
	v_lshlrev_b32_e32 v131, 16, v131
	v_pk_mul_f32 v[98:99], v[68:69], v[94:95] op_sel:[0,1] op_sel_hi:[1,0]
	v_lshlrev_b32_e32 v132, 16, v132
	v_pk_fma_f32 v[98:99], v[94:95], v[66:67], v[98:99] op_sel_hi:[1,0,1]
	v_lshlrev_b32_e32 v133, 16, v133
	v_pk_mul_f32 v[102:103], v[68:69], v[98:99] op_sel:[0,1] op_sel_hi:[1,0]
	s_waitcnt vmcnt(22)
	v_lshlrev_b32_e32 v135, 16, v135
	v_pk_fma_f32 v[102:103], v[98:99], v[66:67], v[102:103] op_sel_hi:[1,0,1]
	v_lshlrev_b32_e32 v134, 16, v136
	v_pk_mul_f32 v[108:109], v[68:69], v[102:103] op_sel:[0,1] op_sel_hi:[1,0]
	s_waitcnt vmcnt(21)
	v_lshlrev_b32_e32 v136, 16, v137
	v_pk_fma_f32 v[108:109], v[102:103], v[66:67], v[108:109] op_sel_hi:[1,0,1]
	s_waitcnt vmcnt(20)
	v_lshlrev_b32_e32 v137, 16, v138
	v_pk_mul_f32 v[112:113], v[68:69], v[108:109] op_sel:[0,1] op_sel_hi:[1,0]
	s_waitcnt vmcnt(19)
	v_lshlrev_b32_e32 v138, 16, v139
	s_waitcnt vmcnt(18)
	v_lshlrev_b32_e32 v139, 16, v140
	s_waitcnt vmcnt(17)
	v_lshlrev_b32_e32 v140, 16, v141
	s_waitcnt vmcnt(16)
	v_lshlrev_b32_e32 v141, 16, v142
	v_pk_fma_f32 v[112:113], v[108:109], v[66:67], v[112:113] op_sel_hi:[1,0,1]
	v_pk_add_f32 v[142:143], v[126:127], 0 op_sel_hi:[1,0]
	v_pk_add_f32 v[144:145], v[128:129], 0 op_sel_hi:[1,0]
	v_pk_mul_f32 v[146:147], v[128:129], s[36:37]
	v_pk_add_f32 v[148:149], v[130:131], 0 op_sel_hi:[1,0]
	v_pk_mul_f32 v[150:151], v[130:131], s[16:17]
	v_pk_add_f32 v[152:153], v[132:133], 0 op_sel_hi:[1,0]
	v_pk_mul_f32 v[154:155], v[132:133], s[38:39]
	v_pk_add_f32 v[156:157], v[134:135], 0 op_sel_hi:[1,0]
	v_xor_b32_e32 v159, 0x80000000, v134
	v_mov_b32_e32 v158, v135
	v_pk_add_f32 v[134:135], v[136:137], 0 op_sel_hi:[1,0]
	v_pk_mul_f32 v[160:161], v[136:137], s[38:39]
	v_pk_add_f32 v[162:163], v[138:139], 0 op_sel_hi:[1,0]
	v_pk_mul_f32 v[164:165], v[138:139], s[16:17]
	v_pk_add_f32 v[166:167], v[140:141], 0 op_sel_hi:[1,0]
	v_pk_mul_f32 v[168:169], v[140:141], s[36:37]
	v_pk_mul_f32 v[116:117], v[68:69], v[112:113] op_sel:[0,1] op_sel_hi:[1,0]
	v_pk_fma_f32 v[128:129], v[128:129], s[6:7], v[146:147] op_sel:[0,0,1] op_sel_hi:[1,0,0]
	v_pk_fma_f32 v[130:131], v[130:131], s[10:11], v[150:151] op_sel:[0,0,1] op_sel_hi:[1,0,0]
	v_pk_fma_f32 v[132:133], v[132:133], s[14:15], v[154:155] op_sel:[0,0,1] op_sel_hi:[1,0,0]
	v_pk_fma_f32 v[136:137], v[136:137], s[4:5], v[160:161] op_sel:[0,0,1] op_sel_hi:[1,0,0]
	v_pk_fma_f32 v[138:139], v[138:139], s[8:9], v[164:165] op_sel:[0,0,1] op_sel_hi:[1,0,0]
	v_pk_fma_f32 v[140:141], v[140:141], s[12:13], v[168:169] op_sel:[0,0,1] op_sel_hi:[1,0,0]
	v_pk_add_f32 v[146:147], v[142:143], v[156:157]
	v_pk_add_f32 v[150:151], v[144:145], v[134:135]
	v_pk_add_f32 v[134:135], v[144:145], v[134:135] neg_lo:[0,1] neg_hi:[0,1]
	v_pk_add_f32 v[144:145], v[148:149], v[162:163]
	v_pk_add_f32 v[160:161], v[148:149], v[162:163] op_sel:[1,1] op_sel_hi:[0,0] neg_lo:[0,1] neg_hi:[1,0]
	v_pk_add_f32 v[154:155], v[152:153], v[166:167]
	v_pk_add_f32 v[152:153], v[152:153], v[166:167] neg_lo:[0,1] neg_hi:[0,1]
	v_pk_fma_f32 v[116:117], v[112:113], v[66:67], v[116:117] op_sel_hi:[1,0,1]
	v_pk_add_f32 v[142:143], v[142:143], v[156:157] neg_lo:[0,1] neg_hi:[0,1]
	v_pk_add_f32 v[156:157], v[158:159], v[126:127]
	v_pk_add_f32 v[126:127], v[126:127], v[158:159] neg_lo:[0,1] neg_hi:[0,1]
	v_pk_mul_f32 v[158:159], v[134:135], s[16:17]
	v_pk_mul_f32 v[148:149], v[152:153], s[16:17]
	v_pk_add_f32 v[162:163], v[128:129], v[136:137]
	v_pk_add_f32 v[128:129], v[128:129], v[136:137] neg_lo:[0,1] neg_hi:[0,1]
	v_pk_add_f32 v[136:137], v[130:131], v[138:139]
	v_pk_add_f32 v[130:131], v[130:131], v[138:139] neg_lo:[0,1] neg_hi:[0,1]
	v_pk_add_f32 v[138:139], v[132:133], v[140:141]
	v_pk_add_f32 v[132:133], v[132:133], v[140:141] neg_lo:[0,1] neg_hi:[0,1]
	v_pk_add_f32 v[140:141], v[146:147], v[144:145]
	v_pk_add_f32 v[144:145], v[146:147], v[144:145] neg_lo:[0,1] neg_hi:[0,1]
	v_pk_add_f32 v[146:147], v[150:151], v[154:155]
	v_pk_add_f32 v[150:151], v[150:151], v[154:155] neg_lo:[0,1] neg_hi:[0,1]
	v_pk_mul_f32 v[120:121], v[68:69], v[116:117] op_sel:[0,1] op_sel_hi:[1,0]
	v_pk_fma_f32 v[134:135], v[134:135], s[10:11], v[158:159] op_sel:[0,0,1] op_sel_hi:[1,0,0]
	v_pk_fma_f32 v[148:149], v[152:153], s[8:9], v[148:149] op_sel:[0,0,1] op_sel_hi:[1,0,0]
	v_pk_mul_f32 v[152:153], v[128:129], s[16:17]
	v_xor_b32_e32 v155, 0x80000000, v130
	v_mov_b32_e32 v154, v131
	v_pk_mul_f32 v[130:131], v[132:133], s[16:17]
	v_xor_b32_e32 v159, 0x80000000, v150
	v_mov_b32_e32 v158, v151
	v_pk_add_f32 v[150:151], v[142:143], v[160:161]
	v_pk_add_f32 v[142:143], v[142:143], v[160:161] neg_lo:[0,1] neg_hi:[0,1]
	v_pk_add_f32 v[160:161], v[156:157], v[136:137]
	v_pk_add_f32 v[136:137], v[156:157], v[136:137] neg_lo:[0,1] neg_hi:[0,1]
	v_pk_add_f32 v[156:157], v[162:163], v[138:139]
	v_pk_add_f32 v[138:139], v[162:163], v[138:139] neg_lo:[0,1] neg_hi:[0,1]
	v_mov_b32_e32 v0, v67
	v_pk_fma_f32 v[120:121], v[116:117], v[66:67], v[120:121] op_sel_hi:[1,0,1]
	v_pk_add_f32 v[162:163], v[140:141], v[146:147]
	v_pk_add_f32 v[140:141], v[140:141], v[146:147] neg_lo:[0,1] neg_hi:[0,1]
	v_pk_fma_f32 v[128:129], v[128:129], s[10:11], v[152:153] op_sel:[0,0,1] op_sel_hi:[1,0,0]
	v_pk_fma_f32 v[130:131], v[132:133], s[8:9], v[130:131] op_sel:[0,0,1] op_sel_hi:[1,0,0]
	v_pk_add_f32 v[132:133], v[134:135], v[148:149]
	v_pk_add_f32 v[134:135], v[134:135], v[148:149] neg_lo:[0,1] neg_hi:[0,1]
	v_xor_b32_e32 v147, 0x80000000, v138
	v_mov_b32_e32 v146, v139
	v_pk_add_f32 v[152:153], v[160:161], v[156:157]
	v_pk_mul_f32 v[68:69], v[68:69], v[120:121] op_sel:[0,1] op_sel_hi:[1,0]
	v_pk_add_f32 v[138:139], v[126:127], v[154:155]
	v_pk_add_f32 v[126:127], v[126:127], v[154:155] neg_lo:[0,1] neg_hi:[0,1]
	v_pk_add_f32 v[148:149], v[144:145], v[158:159]
	v_pk_add_f32 v[144:145], v[144:145], v[158:159] neg_lo:[0,1] neg_hi:[0,1]
	v_pk_add_f32 v[154:155], v[160:161], v[156:157] neg_lo:[0,1] neg_hi:[0,1]
	v_pk_mul_f32 v[96:97], v[140:141], v[94:95] op_sel:[1,1] op_sel_hi:[0,1] neg_hi:[0,1]
	v_xor_b32_e32 v157, 0x80000000, v134
	v_mov_b32_e32 v156, v135
	v_pk_add_f32 v[134:135], v[128:129], v[130:131]
	v_pk_add_f32 v[128:129], v[128:129], v[130:131] neg_lo:[0,1] neg_hi:[0,1]
	v_pk_add_f32 v[130:131], v[150:151], v[132:133]
	v_pk_add_f32 v[132:133], v[150:151], v[132:133] neg_lo:[0,1] neg_hi:[0,1]
	v_pk_add_f32 v[150:151], v[136:137], v[146:147]
	v_pk_add_f32 v[136:137], v[136:137], v[146:147] neg_lo:[0,1] neg_hi:[0,1]
	v_pk_mul_f32 v[146:147], v[0:1], v[152:153] op_sel:[0,1] op_sel_hi:[0,0] neg_hi:[1,0]
	v_pk_add_f32 v[92:93], v[90:91], 0 neg_lo:[1,1] neg_hi:[1,1]
	v_pk_fma_f32 v[68:69], v[120:121], v[66:67], v[68:69] op_sel_hi:[1,0,1]
	v_pk_mul_f32 v[80:81], v[148:149], v[78:79] op_sel:[1,1] op_sel_hi:[0,1] neg_hi:[0,1]
	v_pk_fma_f32 v[94:95], v[140:141], v[94:95], v[96:97] op_sel_hi:[1,0,1]
	v_pk_mul_f32 v[96:97], v[154:155], v[98:99] op_sel:[1,1] op_sel_hi:[0,1] neg_hi:[0,1]
	v_pk_mul_f32 v[100:101], v[144:145], v[112:113] op_sel:[1,1] op_sel_hi:[0,1] neg_hi:[0,1]
	v_xor_b32_e32 v115, 0x80000000, v128
	v_mov_b32_e32 v114, v129
	v_pk_add_f32 v[128:129], v[142:143], v[156:157]
	v_pk_add_f32 v[140:141], v[142:143], v[156:157] neg_lo:[0,1] neg_hi:[0,1]
	v_pk_add_f32 v[142:143], v[138:139], v[134:135]
	v_pk_fma_f32 v[66:67], v[152:153], v[66:67], v[146:147] op_sel_hi:[1,0,1]
	v_pk_mul_f32 v[72:73], v[130:131], v[70:71] op_sel:[1,1] op_sel_hi:[0,1] neg_hi:[0,1]
	v_mov_b32_e32 v92, v91
	v_pk_add_f32 v[110:111], v[108:109], 0 neg_lo:[1,1] neg_hi:[1,1]
	v_pk_add_f32 v[118:119], v[116:117], 0 neg_lo:[1,1] neg_hi:[1,1]
	v_pk_add_f32 v[122:123], v[120:121], 0 neg_lo:[1,1] neg_hi:[1,1]
	v_pk_add_f32 v[124:125], v[68:69], 0 neg_lo:[1,1] neg_hi:[1,1]
	ds_write_b64 v171, v[162:163]
	v_pk_fma_f32 v[78:79], v[148:149], v[78:79], v[80:81] op_sel_hi:[1,0,1]
	v_pk_mul_f32 v[80:81], v[150:151], v[82:83] op_sel:[1,1] op_sel_hi:[0,1] neg_hi:[0,1]
	v_pk_fma_f32 v[84:85], v[154:155], v[98:99], v[96:97] op_sel_hi:[1,0,1]
	v_pk_mul_f32 v[96:97], v[132:133], v[102:103] op_sel:[1,1] op_sel_hi:[0,1] neg_hi:[0,1]
	v_pk_add_f32 v[106:107], v[126:127], v[114:115]
	ds_write_b64 v172, v[66:67] offset:8192
	v_pk_fma_f32 v[66:67], v[130:131], v[70:71], v[72:73] op_sel_hi:[1,0,1]
	v_pk_mul_f32 v[70:71], v[142:143], v[74:75] op_sel:[1,1] op_sel_hi:[0,1] neg_hi:[0,1]
	v_mov_b32_e32 v110, v109
	v_mov_b32_e32 v118, v117
	v_mov_b32_e32 v122, v121
	v_mov_b32_e32 v124, v69
	v_pk_add_f32 v[134:135], v[138:139], v[134:135] neg_lo:[0,1] neg_hi:[0,1]
	v_pk_fma_f32 v[98:99], v[144:145], v[112:113], v[100:101] op_sel_hi:[1,0,1]
	v_pk_add_f32 v[112:113], v[126:127], v[114:115] neg_lo:[0,1] neg_hi:[0,1]
	v_pk_mul_f32 v[76:77], v[128:129], v[86:87] op_sel:[1,1] op_sel_hi:[0,1] neg_hi:[0,1]
	ds_write_b64 v173, v[66:67] offset:16384
	v_pk_fma_f32 v[66:67], v[142:143], v[74:75], v[70:71] op_sel_hi:[1,0,1]
	v_pk_mul_f32 v[74:75], v[106:107], v[92:93] op_sel:[1,0] op_sel_hi:[0,1]
	s_mov_b64 s[48:49], 0
	s_and_b64 vcc, exec, vcc
	v_pk_mul_f32 v[100:101], v[136:137], v[118:119] op_sel:[1,0] op_sel_hi:[0,1]
	v_pk_fma_f32 v[72:73], v[150:151], v[82:83], v[80:81] op_sel_hi:[1,0,1]
	v_pk_fma_f32 v[80:81], v[132:133], v[102:103], v[96:97] op_sel_hi:[1,0,1]
	v_pk_mul_f32 v[82:83], v[134:135], v[110:111] op_sel:[1,0] op_sel_hi:[0,1]
	v_pk_mul_f32 v[96:97], v[140:141], v[122:123] op_sel:[1,0] op_sel_hi:[0,1]
	v_pk_fma_f32 v[70:71], v[128:129], v[86:87], v[76:77] op_sel_hi:[1,0,1]
	v_pk_mul_f32 v[86:87], v[112:113], v[124:125] op_sel:[1,0] op_sel_hi:[0,1]
	ds_write_b64 v174, v[66:67] offset:24576
	ds_write_b64 v175, v[78:79] offset:32768
	ds_write_b64 v176, v[72:73] offset:40960
	ds_write_b64 v177, v[70:71] offset:49152
	v_pk_fma_f32 v[66:67], v[106:107], v[90:91], v[74:75] op_sel_hi:[1,0,1]
	v_pk_fma_f32 v[88:89], v[136:137], v[116:117], v[100:101] op_sel_hi:[1,0,1]
	v_pk_fma_f32 v[76:77], v[134:135], v[108:109], v[82:83] op_sel_hi:[1,0,1]
	v_pk_fma_f32 v[82:83], v[140:141], v[120:121], v[96:97] op_sel_hi:[1,0,1]
	v_pk_fma_f32 v[68:69], v[112:113], v[68:69], v[86:87] op_sel_hi:[1,0,1]
	ds_write_b64 v178, v[66:67] offset:57344
	ds_write_b64 v179, v[94:95]
	ds_write_b64 v180, v[84:85]
	ds_write_b64 v181, v[80:81]
	ds_write_b64 v182, v[76:77]
	ds_write_b64 v183, v[98:99]
	ds_write_b64 v184, v[88:89]
	ds_write_b64 v185, v[82:83]
	ds_write_b64 v186, v[68:69]
	s_cbranch_vccz .LBB0_362
	s_waitcnt lgkmcnt(0)
	s_barrier
	v_mov_b32 v0, 0
	s_mov_b32 s5, s14
	v_add_u32_e32 v74, v0, v170
	v_lshlrev_b32_e32 v0, 5, v74
	v_and_b32_e32 v71, 0xfffffc00, v0
	v_or_b32_e32 v75, 0x80, v71
	v_and_b32_e32 v70, 31, v74
	v_ashrrev_i32_e32 v75, 2, v75
	v_lshlrev_b32_e32 v78, 3, v71
	v_lshlrev_b32_e32 v79, 3, v70
	v_add_u32_e32 v75, 0, v75
	v_add3_u32 v111, v75, v78, v79
	v_or_b32_e32 v75, 0xa0, v71
	v_ashrrev_i32_e32 v75, 2, v75
	v_add_u32_e32 v75, 0, v75
	v_add3_u32 v110, v75, v78, v79
	v_or_b32_e32 v75, 0xc0, v71
	v_ashrrev_i32_e32 v75, 2, v75
	v_add_u32_e32 v75, 0, v75
	v_add3_u32 v109, v75, v78, v79
	v_or_b32_e32 v75, 0xe0, v71
	v_ashrrev_i32_e32 v75, 2, v75
	v_add_u32_e32 v75, 0, v75
	v_add3_u32 v108, v75, v78, v79
	v_or_b32_e32 v75, 0x100, v71
	v_ashrrev_i32_e32 v75, 2, v75
	v_add_u32_e32 v75, 0, v75
	v_add3_u32 v107, v75, v78, v79
	v_or_b32_e32 v75, 0x120, v71
	v_ashrrev_i32_e32 v75, 2, v75
	v_add_u32_e32 v75, 0, v75
	v_add3_u32 v106, v75, v78, v79
	v_or_b32_e32 v75, 0x140, v71
	v_ashrrev_i32_e32 v75, 2, v75
	v_add_u32_e32 v75, 0, v75
	v_add3_u32 v105, v75, v78, v79
	v_or_b32_e32 v75, 0x160, v71
	v_ashrrev_i32_e32 v75, 2, v75
	v_add_u32_e32 v75, 0, v75
	v_add3_u32 v103, v75, v78, v79
	v_or_b32_e32 v75, 0x180, v71
	v_ashrrev_i32_e32 v75, 2, v75
	v_add_u32_e32 v75, 0, v75
	v_add3_u32 v102, v75, v78, v79
	v_or_b32_e32 v75, 0x1a0, v71
	v_ashrrev_i32_e32 v75, 2, v75
	v_add_u32_e32 v75, 0, v75
	v_add3_u32 v101, v75, v78, v79
	v_or_b32_e32 v75, 0x1c0, v71
	v_ashrrev_i32_e32 v75, 2, v75
	v_add_u32_e32 v75, 0, v75
	v_add3_u32 v100, v75, v78, v79
	v_or_b32_e32 v75, 0x1e0, v71
	v_ashrrev_i32_e32 v75, 2, v75
	v_add_u32_e32 v75, 0, v75
	v_add3_u32 v99, v75, v78, v79
	v_or_b32_e32 v75, 0x200, v71
	v_ashrrev_i32_e32 v75, 2, v75
	v_add_u32_e32 v75, 0, v75
	v_add3_u32 v98, v75, v78, v79
	v_or_b32_e32 v75, 0x220, v71
	v_ashrrev_i32_e32 v75, 2, v75
	v_add_u32_e32 v75, 0, v75
	v_add3_u32 v97, v75, v78, v79
	v_or_b32_e32 v75, 0x240, v71
	v_ashrrev_i32_e32 v75, 2, v75
	v_add_u32_e32 v75, 0, v75
	v_add3_u32 v96, v75, v78, v79
	v_or_b32_e32 v75, 0x260, v71
	v_ashrrev_i32_e32 v75, 2, v75
	v_add_u32_e32 v75, 0, v75
	v_add3_u32 v95, v75, v78, v79
	v_or_b32_e32 v75, 0x280, v71
	v_or_b32_e32 v67, 32, v71
	v_ashrrev_i32_e32 v75, 2, v75
	v_ashrrev_i32_e32 v67, 2, v67
	v_add_u32_e32 v75, 0, v75
	v_add_u32_e32 v67, 0, v67
	v_add3_u32 v94, v75, v78, v79
	v_or_b32_e32 v75, 0x2a0, v71
	v_add3_u32 v114, v67, v78, v79
	v_or_b32_e32 v67, 64, v71
	v_ashrrev_i32_e32 v75, 2, v75
	v_ashrrev_i32_e32 v67, 2, v67
	v_add_u32_e32 v75, 0, v75
	v_add_u32_e32 v67, 0, v67
	v_add3_u32 v93, v75, v78, v79
	v_or_b32_e32 v75, 0x2c0, v71
	v_ashrrev_i32_e32 v66, 2, v71
	v_add3_u32 v113, v67, v78, v79
	v_or_b32_e32 v67, 0x60, v71
	v_ashrrev_i32_e32 v75, 2, v75
	v_add_u32_e32 v66, 0, v66
	v_ashrrev_i32_e32 v67, 2, v67
	v_add_u32_e32 v75, 0, v75
	v_add3_u32 v66, v66, v78, v79
	v_add_u32_e32 v67, 0, v67
	v_add3_u32 v92, v75, v78, v79
	v_or_b32_e32 v75, 0x2e0, v71
	v_add3_u32 v112, v67, v78, v79
	ds_read_b64 v[66:67], v66
	ds_read_b64 v[68:69], v114 offset:256
	ds_read_b64 v[72:73], v113 offset:512
	ds_read_b64 v[76:77], v112 offset:768
	ds_read_b64 v[80:81], v111 offset:1024
	ds_read_b64 v[82:83], v110 offset:1280
	ds_read_b64 v[116:117], v109 offset:1536
	ds_read_b64 v[118:119], v108 offset:1792
	ds_read_b64 v[120:121], v107 offset:2048
	ds_read_b64 v[122:123], v106 offset:2304
	ds_read_b64 v[124:125], v105 offset:2560
	ds_read_b64 v[126:127], v103 offset:2816
	ds_read_b64 v[128:129], v102 offset:3072
	ds_read_b64 v[130:131], v101 offset:3328
	ds_read_b64 v[132:133], v100 offset:3584
	ds_read_b64 v[134:135], v99 offset:3840
	ds_read_b64 v[136:137], v98 offset:4096
	ds_read_b64 v[138:139], v97 offset:4352
	ds_read_b64 v[140:141], v96 offset:4608
	ds_read_b64 v[142:143], v95 offset:4864
	v_ashrrev_i32_e32 v75, 2, v75
	v_add_u32_e32 v75, 0, v75
	v_add3_u32 v91, v75, v78, v79
	v_or_b32_e32 v75, 0x300, v71
	v_ashrrev_i32_e32 v75, 2, v75
	s_waitcnt lgkmcnt(3)
	v_pk_add_f32 v[168:169], v[66:67], v[136:137]
	v_pk_add_f32 v[66:67], v[66:67], v[136:137] neg_lo:[0,1] neg_hi:[0,1]
	s_waitcnt lgkmcnt(2)
	v_pk_add_f32 v[136:137], v[68:69], v[138:139]
	v_pk_add_f32 v[68:69], v[68:69], v[138:139] neg_lo:[0,1] neg_hi:[0,1]
	v_add_u32_e32 v75, 0, v75
	v_pk_mul_f32 v[138:139], v[68:69], s[18:19]
	v_add3_u32 v90, v75, v78, v79
	v_or_b32_e32 v75, 0x320, v71
	v_pk_fma_f32 v[68:69], v[68:69], s[20:21], v[138:139] op_sel:[0,0,1] op_sel_hi:[1,0,0]
	s_waitcnt lgkmcnt(1)
	v_pk_add_f32 v[138:139], v[72:73], v[140:141]
	v_pk_add_f32 v[72:73], v[72:73], v[140:141] neg_lo:[0,1] neg_hi:[0,1]
	v_ashrrev_i32_e32 v75, 2, v75
	v_pk_mul_f32 v[140:141], v[72:73], s[4:5]
	ds_read_b64 v[144:145], v94 offset:5120
	ds_read_b64 v[146:147], v93 offset:5376
	ds_read_b64 v[148:149], v92 offset:5632
	ds_read_b64 v[150:151], v91 offset:5888
	v_add_u32_e32 v75, 0, v75
	v_pk_fma_f32 v[72:73], v[72:73], s[6:7], v[140:141] op_sel:[0,0,1] op_sel_hi:[1,0,0]
	s_waitcnt lgkmcnt(4)
	v_pk_add_f32 v[140:141], v[76:77], v[142:143]
	v_pk_add_f32 v[76:77], v[76:77], v[142:143] neg_lo:[0,1] neg_hi:[0,1]
	v_add3_u32 v89, v75, v78, v79
	v_or_b32_e32 v75, 0x340, v71
	v_pk_mul_f32 v[142:143], v[76:77], s[22:23]
	v_ashrrev_i32_e32 v75, 2, v75
	v_pk_fma_f32 v[76:77], v[76:77], s[24:25], v[142:143] op_sel:[0,0,1] op_sel_hi:[1,0,0]
	s_waitcnt lgkmcnt(3)
	v_pk_add_f32 v[142:143], v[80:81], v[144:145]
	v_pk_add_f32 v[80:81], v[80:81], v[144:145] neg_lo:[0,1] neg_hi:[0,1]
	s_mov_b32 s9, s10
	v_add_u32_e32 v75, 0, v75
	v_pk_mul_f32 v[144:145], v[80:81], s[8:9]
	v_add3_u32 v88, v75, v78, v79
	v_or_b32_e32 v75, 0x360, v71
	v_pk_fma_f32 v[80:81], v[80:81], s[10:11], v[144:145] op_sel:[0,0,1] op_sel_hi:[1,0,0]
	s_waitcnt lgkmcnt(2)
	v_pk_add_f32 v[144:145], v[82:83], v[146:147]
	v_pk_add_f32 v[82:83], v[82:83], v[146:147] neg_lo:[0,1] neg_hi:[0,1]
	s_mov_b32 s27, s24
	v_ashrrev_i32_e32 v75, 2, v75
	v_pk_mul_f32 v[146:147], v[82:83], s[26:27]
	s_mov_b32 s0, s23
	v_add_u32_e32 v75, 0, v75
	v_pk_fma_f32 v[82:83], v[82:83], s[0:1], v[146:147] op_sel:[0,0,1] op_sel_hi:[1,0,0]
	s_waitcnt lgkmcnt(1)
	v_pk_add_f32 v[146:147], v[116:117], v[148:149]
	v_pk_add_f32 v[116:117], v[116:117], v[148:149] neg_lo:[0,1] neg_hi:[0,1]
	s_mov_b32 s13, s6
	v_add3_u32 v87, v75, v78, v79
	v_or_b32_e32 v75, 0x380, v71
	v_pk_mul_f32 v[148:149], v[116:117], s[12:13]
	ds_read_b64 v[152:153], v90 offset:6144
	ds_read_b64 v[154:155], v89 offset:6400
	ds_read_b64 v[156:157], v88 offset:6656
	ds_read_b64 v[158:159], v87 offset:6912
	v_ashrrev_i32_e32 v75, 2, v75
	v_pk_fma_f32 v[116:117], v[116:117], s[14:15], v[148:149] op_sel:[0,0,1] op_sel_hi:[1,0,0]
	s_waitcnt lgkmcnt(4)
	v_pk_add_f32 v[148:149], v[118:119], v[150:151]
	v_pk_add_f32 v[118:119], v[118:119], v[150:151] neg_lo:[0,1] neg_hi:[0,1]
	s_mov_b32 s35, s20
	v_add_u32_e32 v75, 0, v75
	v_pk_mul_f32 v[150:151], v[118:119], s[34:35]
	s_mov_b32 s48, s19
	v_add3_u32 v86, v75, v78, v79
	v_or_b32_e32 v75, 0x3a0, v71
	v_or_b32_e32 v71, 0x3c0, v71
	v_pk_fma_f32 v[118:119], v[118:119], s[48:49], v[150:151] op_sel:[0,0,1] op_sel_hi:[1,0,0]
	s_waitcnt lgkmcnt(3)
	v_pk_add_f32 v[150:151], v[120:121], v[152:153]
	v_pk_add_f32 v[152:153], v[120:121], v[152:153] op_sel:[1,1] op_sel_hi:[0,0] neg_lo:[0,1] neg_hi:[1,0]
	v_ashrrev_i32_e32 v71, 2, v71
	s_waitcnt lgkmcnt(2)
	v_pk_add_f32 v[120:121], v[122:123], v[154:155]
	v_pk_add_f32 v[122:123], v[122:123], v[154:155] neg_lo:[0,1] neg_hi:[0,1]
	v_add_u32_e32 v71, 0, v71
	v_or_b32_e32 v0, 0x3e0, v0
	v_pk_mul_f32 v[154:155], v[122:123], s[34:35]
	v_ashrrev_i32_e32 v75, 2, v75
	v_add3_u32 v84, v71, v78, v79
	v_ashrrev_i32_e32 v71, 2, v0
	v_pk_fma_f32 v[122:123], v[122:123], s[18:19], v[154:155] op_sel:[0,0,1] op_sel_hi:[1,0,0]
	s_waitcnt lgkmcnt(1)
	v_pk_add_f32 v[154:155], v[124:125], v[156:157]
	v_pk_add_f32 v[124:125], v[124:125], v[156:157] neg_lo:[0,1] neg_hi:[0,1]
	v_add_u32_e32 v75, 0, v75
	v_add_u32_e32 v71, 0, v71
	v_lshlrev_b32_e32 v0, 3, v0
	v_pk_mul_f32 v[156:157], v[124:125], s[12:13]
	v_add3_u32 v85, v75, v78, v79
	v_add3_u32 v0, v71, v0, v79
	ds_read_b64 v[160:161], v86 offset:7168
	ds_read_b64 v[162:163], v85 offset:7424
	ds_read_b64 v[164:165], v84 offset:7680
	ds_read_b64 v[166:167], v0
	v_pk_fma_f32 v[124:125], v[124:125], s[4:5], v[156:157] op_sel:[0,0,1] op_sel_hi:[1,0,0]
	s_waitcnt lgkmcnt(4)
	v_pk_add_f32 v[156:157], v[126:127], v[158:159]
	v_pk_add_f32 v[126:127], v[126:127], v[158:159] neg_lo:[0,1] neg_hi:[0,1]
	v_lshlrev_b32_e32 v70, 4, v70
	v_pk_mul_f32 v[158:159], v[126:127], s[26:27]
	v_cvt_f32_u32_e32 v75, v70
	v_pk_fma_f32 v[126:127], v[126:127], s[22:23], v[158:159] op_sel:[0,0,1] op_sel_hi:[1,0,0]
	s_waitcnt lgkmcnt(3)
	v_pk_add_f32 v[158:159], v[128:129], v[160:161]
	v_pk_add_f32 v[128:129], v[128:129], v[160:161] neg_lo:[0,1] neg_hi:[0,1]
	v_and_b32_e32 v74, 0x1fffffe0, v74
	v_pk_mul_f32 v[160:161], v[128:129], s[8:9]
	v_mul_f32_e32 v115, 0x38800000, v75
	v_pk_fma_f32 v[128:129], v[128:129], s[8:9], v[160:161] op_sel:[0,0,1] op_sel_hi:[1,0,0]
	s_waitcnt lgkmcnt(2)
	v_pk_add_f32 v[160:161], v[130:131], v[162:163]
	v_pk_add_f32 v[130:131], v[130:131], v[162:163] neg_lo:[0,1] neg_hi:[0,1]
	v_lshl_add_u32 v74, v74, 3, 0
	v_pk_mul_f32 v[162:163], v[130:131], s[22:23]
	v_sin_f32_e32 v75, v115
	v_pk_fma_f32 v[130:131], v[130:131], s[26:27], v[162:163] op_sel:[0,0,1] op_sel_hi:[1,0,0]
	s_waitcnt lgkmcnt(1)
	v_pk_add_f32 v[162:163], v[132:133], v[164:165]
	v_pk_add_f32 v[132:133], v[132:133], v[164:165] neg_lo:[0,1] neg_hi:[0,1]
	v_add3_u32 v74, v74, v78, v79
	v_pk_mul_f32 v[164:165], v[132:133], s[4:5]
	v_xor_b32_e32 v78, 0x80000000, v75
	v_pk_fma_f32 v[132:133], v[132:133], s[12:13], v[164:165] op_sel:[0,0,1] op_sel_hi:[1,0,0]
	s_waitcnt lgkmcnt(0)
	v_pk_add_f32 v[164:165], v[134:135], v[166:167]
	v_pk_add_f32 v[134:135], v[134:135], v[166:167] neg_lo:[0,1] neg_hi:[0,1]
	v_mov_b32_e32 v79, v75
	v_pk_mul_f32 v[166:167], v[134:135], s[18:19]
	s_mov_b32 s50, s19
	v_pk_fma_f32 v[134:135], v[134:135], s[34:35], v[166:167] op_sel:[0,0,1] op_sel_hi:[1,0,0]
	v_pk_add_f32 v[166:167], v[168:169], v[150:151]
	v_pk_add_f32 v[150:151], v[168:169], v[150:151] neg_lo:[0,1] neg_hi:[0,1]
	v_pk_add_f32 v[168:169], v[136:137], v[120:121]
	v_pk_add_f32 v[120:121], v[136:137], v[120:121] neg_lo:[0,1] neg_hi:[0,1]
	s_mov_b32 s51, s18
	v_pk_mul_f32 v[136:137], v[120:121], s[4:5]
	s_mov_b32 s52, s23
	v_pk_fma_f32 v[120:121], v[120:121], s[6:7], v[136:137] op_sel:[0,0,1] op_sel_hi:[1,0,0]
	v_pk_add_f32 v[136:137], v[138:139], v[154:155]
	v_pk_add_f32 v[138:139], v[138:139], v[154:155] neg_lo:[0,1] neg_hi:[0,1]
	s_mov_b32 s53, s22
	v_pk_mul_f32 v[154:155], v[138:139], s[8:9]
	s_nop 0
	v_pk_fma_f32 v[138:139], v[138:139], s[10:11], v[154:155] op_sel:[0,0,1] op_sel_hi:[1,0,0]
	v_pk_add_f32 v[154:155], v[140:141], v[156:157]
	v_pk_add_f32 v[140:141], v[140:141], v[156:157] neg_lo:[0,1] neg_hi:[0,1]
	s_nop 0
	v_pk_mul_f32 v[156:157], v[140:141], s[12:13]
	s_nop 0
	v_pk_fma_f32 v[140:141], v[140:141], s[14:15], v[156:157] op_sel:[0,0,1] op_sel_hi:[1,0,0]
	v_pk_add_f32 v[156:157], v[142:143], v[158:159]
	v_pk_add_f32 v[158:159], v[142:143], v[158:159] op_sel:[1,1] op_sel_hi:[0,0] neg_lo:[0,1] neg_hi:[1,0]
	s_nop 0
	v_pk_add_f32 v[142:143], v[144:145], v[160:161]
	v_pk_add_f32 v[144:145], v[144:145], v[160:161] neg_lo:[0,1] neg_hi:[0,1]
	s_nop 0
	v_pk_mul_f32 v[160:161], v[144:145], s[12:13]
	s_nop 0
	v_pk_fma_f32 v[144:145], v[144:145], s[4:5], v[160:161] op_sel:[0,0,1] op_sel_hi:[1,0,0]
	v_pk_add_f32 v[160:161], v[146:147], v[162:163]
	v_pk_add_f32 v[146:147], v[146:147], v[162:163] neg_lo:[0,1] neg_hi:[0,1]
	s_nop 0
	v_pk_mul_f32 v[162:163], v[146:147], s[8:9]
	s_nop 0
	v_pk_fma_f32 v[146:147], v[146:147], s[8:9], v[162:163] op_sel:[0,0,1] op_sel_hi:[1,0,0]
	v_pk_add_f32 v[162:163], v[148:149], v[164:165]
	v_pk_add_f32 v[148:149], v[148:149], v[164:165] neg_lo:[0,1] neg_hi:[0,1]
	s_nop 0
	v_pk_mul_f32 v[164:165], v[148:149], s[4:5]
	s_nop 0
	v_pk_fma_f32 v[148:149], v[148:149], s[12:13], v[164:165] op_sel:[0,0,1] op_sel_hi:[1,0,0]
	v_pk_add_f32 v[164:165], v[66:67], v[152:153]
	v_pk_add_f32 v[66:67], v[66:67], v[152:153] neg_lo:[0,1] neg_hi:[0,1]
	v_pk_add_f32 v[152:153], v[68:69], v[122:123]
	v_pk_add_f32 v[68:69], v[68:69], v[122:123] neg_lo:[0,1] neg_hi:[0,1]
	s_nop 0
	v_pk_mul_f32 v[122:123], v[68:69], s[4:5]
	s_nop 0
	v_pk_fma_f32 v[68:69], v[68:69], s[6:7], v[122:123] op_sel:[0,0,1] op_sel_hi:[1,0,0]
	v_pk_add_f32 v[122:123], v[72:73], v[124:125]
	v_pk_add_f32 v[72:73], v[72:73], v[124:125] neg_lo:[0,1] neg_hi:[0,1]
	s_nop 0
	v_pk_mul_f32 v[124:125], v[72:73], s[8:9]
	s_nop 0
	v_pk_fma_f32 v[72:73], v[72:73], s[10:11], v[124:125] op_sel:[0,0,1] op_sel_hi:[1,0,0]
	v_pk_add_f32 v[124:125], v[76:77], v[126:127]
	v_pk_add_f32 v[76:77], v[76:77], v[126:127] neg_lo:[0,1] neg_hi:[0,1]
	s_nop 0
	v_pk_mul_f32 v[126:127], v[76:77], s[12:13]
	s_nop 0
	v_pk_fma_f32 v[76:77], v[76:77], s[14:15], v[126:127] op_sel:[0,0,1] op_sel_hi:[1,0,0]
	v_pk_add_f32 v[126:127], v[80:81], v[128:129]
	v_pk_add_f32 v[128:129], v[80:81], v[128:129] op_sel:[1,1] op_sel_hi:[0,0] neg_lo:[0,1] neg_hi:[1,0]
	s_nop 0
	v_pk_add_f32 v[80:81], v[82:83], v[130:131]
	v_pk_add_f32 v[82:83], v[82:83], v[130:131] neg_lo:[0,1] neg_hi:[0,1]
	s_nop 0
	v_pk_mul_f32 v[130:131], v[82:83], s[12:13]
	s_nop 0
	v_pk_fma_f32 v[82:83], v[82:83], s[4:5], v[130:131] op_sel:[0,0,1] op_sel_hi:[1,0,0]
	v_pk_add_f32 v[130:131], v[116:117], v[132:133]
	v_pk_add_f32 v[116:117], v[116:117], v[132:133] neg_lo:[0,1] neg_hi:[0,1]
	s_nop 0
	v_pk_mul_f32 v[132:133], v[116:117], s[8:9]
	s_nop 0
	v_pk_fma_f32 v[116:117], v[116:117], s[8:9], v[132:133] op_sel:[0,0,1] op_sel_hi:[1,0,0]
	v_pk_add_f32 v[132:133], v[118:119], v[134:135]
	v_pk_add_f32 v[118:119], v[118:119], v[134:135] neg_lo:[0,1] neg_hi:[0,1]
	s_nop 0
	v_pk_mul_f32 v[134:135], v[118:119], s[4:5]
	s_nop 0
	v_pk_fma_f32 v[118:119], v[118:119], s[12:13], v[134:135] op_sel:[0,0,1] op_sel_hi:[1,0,0]
	v_pk_add_f32 v[134:135], v[166:167], v[156:157]
	v_pk_add_f32 v[156:157], v[166:167], v[156:157] neg_lo:[0,1] neg_hi:[0,1]
	v_pk_add_f32 v[166:167], v[168:169], v[142:143]
	v_pk_add_f32 v[142:143], v[168:169], v[142:143] neg_lo:[0,1] neg_hi:[0,1]
	s_nop 0
	v_pk_mul_f32 v[168:169], v[142:143], s[8:9]
	s_nop 0
	v_pk_fma_f32 v[142:143], v[142:143], s[10:11], v[168:169] op_sel:[0,0,1] op_sel_hi:[1,0,0]
	v_pk_add_f32 v[168:169], v[136:137], v[160:161]
	v_pk_add_f32 v[160:161], v[136:137], v[160:161] op_sel:[1,1] op_sel_hi:[0,0] neg_lo:[0,1] neg_hi:[1,0]
	s_nop 0
	v_pk_add_f32 v[136:137], v[154:155], v[162:163]
	v_pk_add_f32 v[154:155], v[154:155], v[162:163] neg_lo:[0,1] neg_hi:[0,1]
	s_nop 0
	v_pk_mul_f32 v[162:163], v[154:155], s[8:9]
	s_nop 0
	v_pk_fma_f32 v[154:155], v[154:155], s[8:9], v[162:163] op_sel:[0,0,1] op_sel_hi:[1,0,0]
	v_pk_add_f32 v[162:163], v[150:151], v[158:159]
	v_pk_add_f32 v[150:151], v[150:151], v[158:159] neg_lo:[0,1] neg_hi:[0,1]
	v_pk_add_f32 v[158:159], v[120:121], v[144:145]
	v_pk_add_f32 v[120:121], v[120:121], v[144:145] neg_lo:[0,1] neg_hi:[0,1]
	s_nop 0
	v_pk_mul_f32 v[144:145], v[120:121], s[8:9]
	s_nop 0
	v_pk_fma_f32 v[120:121], v[120:121], s[10:11], v[144:145] op_sel:[0,0,1] op_sel_hi:[1,0,0]
	v_pk_add_f32 v[144:145], v[138:139], v[146:147]
	v_pk_add_f32 v[146:147], v[138:139], v[146:147] op_sel:[1,1] op_sel_hi:[0,0] neg_lo:[0,1] neg_hi:[1,0]
	s_nop 0
	v_pk_add_f32 v[138:139], v[140:141], v[148:149]
	v_pk_add_f32 v[140:141], v[140:141], v[148:149] neg_lo:[0,1] neg_hi:[0,1]
	s_nop 0
	v_pk_mul_f32 v[148:149], v[140:141], s[8:9]
	s_nop 0
	v_pk_fma_f32 v[140:141], v[140:141], s[8:9], v[148:149] op_sel:[0,0,1] op_sel_hi:[1,0,0]
	v_pk_add_f32 v[148:149], v[164:165], v[126:127]
	v_pk_add_f32 v[126:127], v[164:165], v[126:127] neg_lo:[0,1] neg_hi:[0,1]
	v_pk_add_f32 v[164:165], v[152:153], v[80:81]
	v_pk_add_f32 v[80:81], v[152:153], v[80:81] neg_lo:[0,1] neg_hi:[0,1]
	s_nop 0
	v_pk_mul_f32 v[152:153], v[80:81], s[8:9]
	s_nop 0
	v_pk_fma_f32 v[80:81], v[80:81], s[10:11], v[152:153] op_sel:[0,0,1] op_sel_hi:[1,0,0]
	v_pk_add_f32 v[152:153], v[122:123], v[130:131]
	v_pk_add_f32 v[130:131], v[122:123], v[130:131] op_sel:[1,1] op_sel_hi:[0,0] neg_lo:[0,1] neg_hi:[1,0]
	s_nop 0
	v_pk_add_f32 v[122:123], v[124:125], v[132:133]
	v_pk_add_f32 v[124:125], v[124:125], v[132:133] neg_lo:[0,1] neg_hi:[0,1]
	s_nop 0
	v_pk_mul_f32 v[132:133], v[124:125], s[8:9]
	s_nop 0
	v_pk_fma_f32 v[124:125], v[124:125], s[8:9], v[132:133] op_sel:[0,0,1] op_sel_hi:[1,0,0]
	v_pk_add_f32 v[132:133], v[66:67], v[128:129]
	v_pk_add_f32 v[66:67], v[66:67], v[128:129] neg_lo:[0,1] neg_hi:[0,1]
	v_pk_add_f32 v[128:129], v[68:69], v[82:83]
	v_pk_add_f32 v[68:69], v[68:69], v[82:83] neg_lo:[0,1] neg_hi:[0,1]
	s_nop 0
	v_pk_mul_f32 v[82:83], v[68:69], s[8:9]
	s_nop 0
	v_pk_fma_f32 v[68:69], v[68:69], s[10:11], v[82:83] op_sel:[0,0,1] op_sel_hi:[1,0,0]
	v_pk_add_f32 v[82:83], v[72:73], v[116:117]
	v_pk_add_f32 v[116:117], v[72:73], v[116:117] op_sel:[1,1] op_sel_hi:[0,0] neg_lo:[0,1] neg_hi:[1,0]
	s_nop 0
	v_pk_add_f32 v[72:73], v[76:77], v[118:119]
	v_pk_add_f32 v[76:77], v[76:77], v[118:119] neg_lo:[0,1] neg_hi:[0,1]
	v_pk_add_f32 v[174:175], v[66:67], v[116:117]
	v_pk_mul_f32 v[118:119], v[76:77], s[8:9]
	v_pk_add_f32 v[116:117], v[66:67], v[116:117] neg_lo:[0,1] neg_hi:[0,1]
	v_pk_fma_f32 v[76:77], v[76:77], s[8:9], v[118:119] op_sel:[0,0,1] op_sel_hi:[1,0,0]
	v_pk_add_f32 v[118:119], v[134:135], v[168:169]
	v_pk_add_f32 v[134:135], v[134:135], v[168:169] neg_lo:[0,1] neg_hi:[0,1]
	v_pk_add_f32 v[168:169], v[166:167], v[136:137]
	v_pk_add_f32 v[166:167], v[166:167], v[136:137] op_sel:[1,1] op_sel_hi:[0,0] neg_lo:[0,1] neg_hi:[1,0]
	v_pk_add_f32 v[180:181], v[118:119], v[168:169]
	v_pk_add_f32 v[136:137], v[156:157], v[160:161]
	v_pk_add_f32 v[156:157], v[156:157], v[160:161] neg_lo:[0,1] neg_hi:[0,1]
	v_pk_add_f32 v[160:161], v[142:143], v[154:155]
	v_pk_add_f32 v[154:155], v[142:143], v[154:155] op_sel:[1,1] op_sel_hi:[0,0] neg_lo:[0,1] neg_hi:[1,0]
	v_pk_add_f32 v[178:179], v[68:69], v[76:77] op_sel:[1,1] op_sel_hi:[0,0] neg_lo:[0,1] neg_hi:[1,0]
	v_pk_add_f32 v[142:143], v[162:163], v[144:145]
	v_pk_add_f32 v[144:145], v[162:163], v[144:145] neg_lo:[0,1] neg_hi:[0,1]
	v_pk_add_f32 v[162:163], v[158:159], v[138:139]
	v_pk_add_f32 v[158:159], v[158:159], v[138:139] op_sel:[1,1] op_sel_hi:[0,0] neg_lo:[0,1] neg_hi:[1,0]
	ds_write_b64 v74, v[180:181]
	v_pk_add_f32 v[138:139], v[150:151], v[146:147]
	v_pk_add_f32 v[146:147], v[150:151], v[146:147] neg_lo:[0,1] neg_hi:[0,1]
	v_pk_add_f32 v[150:151], v[120:121], v[140:141]
	v_pk_add_f32 v[140:141], v[120:121], v[140:141] op_sel:[1,1] op_sel_hi:[0,0] neg_lo:[0,1] neg_hi:[1,0]
	v_cos_f32_e32 v74, v115
	v_pk_add_f32 v[120:121], v[148:149], v[152:153]
	v_pk_add_f32 v[148:149], v[148:149], v[152:153] neg_lo:[0,1] neg_hi:[0,1]
	v_pk_add_f32 v[152:153], v[164:165], v[122:123]
	v_pk_add_f32 v[164:165], v[164:165], v[122:123] op_sel:[1,1] op_sel_hi:[0,0] neg_lo:[0,1] neg_hi:[1,0]
	v_pk_add_f32 v[122:123], v[126:127], v[130:131]
	v_pk_add_f32 v[126:127], v[126:127], v[130:131] neg_lo:[0,1] neg_hi:[0,1]
	v_pk_add_f32 v[130:131], v[80:81], v[124:125]
	v_pk_add_f32 v[124:125], v[80:81], v[124:125] op_sel:[1,1] op_sel_hi:[0,0] neg_lo:[0,1] neg_hi:[1,0]
	v_pk_add_f32 v[80:81], v[132:133], v[82:83]
	v_pk_add_f32 v[132:133], v[132:133], v[82:83] neg_lo:[0,1] neg_hi:[0,1]
	v_pk_add_f32 v[176:177], v[68:69], v[76:77]
	v_pk_add_f32 v[118:119], v[118:119], v[168:169] neg_lo:[0,1] neg_hi:[0,1]
	v_pk_add_f32 v[168:169], v[134:135], v[166:167]
	v_pk_add_f32 v[82:83], v[134:135], v[166:167] neg_lo:[0,1] neg_hi:[0,1]
	v_pk_add_f32 v[134:135], v[136:137], v[160:161]
	v_pk_add_f32 v[136:137], v[136:137], v[160:161] neg_lo:[0,1] neg_hi:[0,1]
	v_pk_add_f32 v[160:161], v[156:157], v[154:155]
	v_pk_add_f32 v[68:69], v[156:157], v[154:155] neg_lo:[0,1] neg_hi:[0,1]
	v_pk_add_f32 v[154:155], v[142:143], v[162:163]
	v_pk_add_f32 v[142:143], v[142:143], v[162:163] neg_lo:[0,1] neg_hi:[0,1]
	v_pk_add_f32 v[156:157], v[144:145], v[158:159]
	v_pk_add_f32 v[76:77], v[144:145], v[158:159] neg_lo:[0,1] neg_hi:[0,1]
	v_pk_add_f32 v[144:145], v[138:139], v[150:151]
	v_pk_add_f32 v[138:139], v[138:139], v[150:151] neg_lo:[0,1] neg_hi:[0,1]
	v_pk_add_f32 v[150:151], v[146:147], v[140:141]
	v_pk_add_f32 v[66:67], v[146:147], v[140:141] neg_lo:[0,1] neg_hi:[0,1]
	v_pk_add_f32 v[140:141], v[120:121], v[152:153]
	v_pk_add_f32 v[162:163], v[116:117], v[178:179]
	v_pk_add_f32 v[70:71], v[116:117], v[178:179] neg_lo:[0,1] neg_hi:[0,1]
	v_mov_b32_e32 v116, v75
	v_pk_mul_f32 v[116:117], v[116:117], v[140:141] op_sel:[0,1] op_sel_hi:[0,0] neg_hi:[1,0]
	v_pk_fma_f32 v[116:117], v[140:141], v[74:75], v[116:117] op_sel_hi:[1,0,1]
	ds_write_b64 v114, v[116:117] offset:256
	v_pk_mul_f32 v[114:115], v[78:79], v[74:75] op_sel:[0,1] op_sel_hi:[1,0]
	v_pk_add_f32 v[172:173], v[128:129], v[72:73]
	v_pk_fma_f32 v[114:115], v[74:75], v[74:75], v[114:115] op_sel_hi:[1,0,1]
	v_pk_add_f32 v[128:129], v[128:129], v[72:73] op_sel:[1,1] op_sel_hi:[0,0] neg_lo:[0,1] neg_hi:[1,0]
	v_pk_mul_f32 v[116:117], v[154:155], v[114:115] op_sel:[1,1] op_sel_hi:[0,1] neg_hi:[0,1]
	v_pk_fma_f32 v[116:117], v[154:155], v[114:115], v[116:117] op_sel_hi:[1,0,1]
	ds_write_b64 v113, v[116:117] offset:512
	v_pk_mul_f32 v[116:117], v[78:79], v[114:115] op_sel:[0,1] op_sel_hi:[1,0]
	v_pk_add_f32 v[120:121], v[120:121], v[152:153] neg_lo:[0,1] neg_hi:[0,1]
	v_pk_fma_f32 v[114:115], v[114:115], v[74:75], v[116:117] op_sel_hi:[1,0,1]
	v_pk_add_f32 v[152:153], v[122:123], v[130:131]
	v_pk_add_f32 v[122:123], v[122:123], v[130:131] neg_lo:[0,1] neg_hi:[0,1]
	v_pk_add_f32 v[130:131], v[126:127], v[124:125]
	v_pk_add_f32 v[72:73], v[126:127], v[124:125] neg_lo:[0,1] neg_hi:[0,1]
	v_pk_add_f32 v[124:125], v[80:81], v[172:173]
	v_pk_mul_f32 v[116:117], v[124:125], v[114:115] op_sel:[1,1] op_sel_hi:[0,1] neg_hi:[0,1]
	v_pk_add_f32 v[126:127], v[80:81], v[172:173] neg_lo:[0,1] neg_hi:[0,1]
	v_pk_fma_f32 v[116:117], v[124:125], v[114:115], v[116:117] op_sel_hi:[1,0,1]
	ds_write_b64 v112, v[116:117] offset:768
	v_pk_mul_f32 v[112:113], v[78:79], v[114:115] op_sel:[0,1] op_sel_hi:[1,0]
	v_pk_add_f32 v[158:159], v[132:133], v[128:129]
	v_pk_fma_f32 v[112:113], v[114:115], v[74:75], v[112:113] op_sel_hi:[1,0,1]
	v_pk_add_f32 v[80:81], v[132:133], v[128:129] neg_lo:[0,1] neg_hi:[0,1]
	v_pk_add_f32 v[128:129], v[174:175], v[176:177]
	v_pk_mul_f32 v[114:115], v[134:135], v[112:113] op_sel:[1,1] op_sel_hi:[0,1] neg_hi:[0,1]
	v_pk_add_f32 v[146:147], v[148:149], v[164:165]
	v_pk_fma_f32 v[114:115], v[134:135], v[112:113], v[114:115] op_sel_hi:[1,0,1]
	ds_write_b64 v111, v[114:115] offset:1024
	v_pk_mul_f32 v[114:115], v[78:79], v[112:113] op_sel:[0,1] op_sel_hi:[1,0]
	v_pk_add_f32 v[132:133], v[174:175], v[176:177] neg_lo:[0,1] neg_hi:[0,1]
	v_pk_fma_f32 v[112:113], v[112:113], v[74:75], v[114:115] op_sel_hi:[1,0,1]
	v_pk_add_f32 v[148:149], v[148:149], v[164:165] neg_lo:[0,1] neg_hi:[0,1]
	s_nop 0
	v_pk_mul_f32 v[114:115], v[152:153], v[112:113] op_sel:[1,1] op_sel_hi:[0,1] neg_hi:[0,1]
	s_nop 0
	v_pk_fma_f32 v[114:115], v[152:153], v[112:113], v[114:115] op_sel_hi:[1,0,1]
	ds_write_b64 v110, v[114:115] offset:1280
	v_pk_mul_f32 v[110:111], v[78:79], v[112:113] op_sel:[0,1] op_sel_hi:[1,0]
	s_nop 0
	v_pk_fma_f32 v[110:111], v[112:113], v[74:75], v[110:111] op_sel_hi:[1,0,1]
	s_nop 0
	s_nop 0
	v_pk_mul_f32 v[112:113], v[144:145], v[110:111] op_sel:[1,1] op_sel_hi:[0,1] neg_hi:[0,1]
	s_nop 0
	v_pk_fma_f32 v[112:113], v[144:145], v[110:111], v[112:113] op_sel_hi:[1,0,1]
	ds_write_b64 v109, v[112:113] offset:1536
	v_pk_mul_f32 v[112:113], v[78:79], v[110:111] op_sel:[0,1] op_sel_hi:[1,0]
	s_nop 0
	v_pk_fma_f32 v[110:111], v[110:111], v[74:75], v[112:113] op_sel_hi:[1,0,1]
	s_nop 0
	s_nop 0
	v_pk_mul_f32 v[112:113], v[128:129], v[110:111] op_sel:[1,1] op_sel_hi:[0,1] neg_hi:[0,1]
	s_nop 0
	v_pk_fma_f32 v[112:113], v[128:129], v[110:111], v[112:113] op_sel_hi:[1,0,1]
	ds_write_b64 v108, v[112:113] offset:1792
	v_pk_mul_f32 v[108:109], v[78:79], v[110:111] op_sel:[0,1] op_sel_hi:[1,0]
	s_nop 0
	v_pk_fma_f32 v[108:109], v[110:111], v[74:75], v[108:109] op_sel_hi:[1,0,1]
	s_nop 0
	s_nop 0
	v_pk_mul_f32 v[110:111], v[168:169], v[108:109] op_sel:[1,1] op_sel_hi:[0,1] neg_hi:[0,1]
	s_nop 0
	v_pk_fma_f32 v[110:111], v[168:169], v[108:109], v[110:111] op_sel_hi:[1,0,1]
	ds_write_b64 v107, v[110:111] offset:2048
	v_pk_mul_f32 v[110:111], v[78:79], v[108:109] op_sel:[0,1] op_sel_hi:[1,0]
	s_nop 0
	v_pk_fma_f32 v[108:109], v[108:109], v[74:75], v[110:111] op_sel_hi:[1,0,1]
	s_nop 0
	s_nop 0
	v_pk_mul_f32 v[110:111], v[146:147], v[108:109] op_sel:[1,1] op_sel_hi:[0,1] neg_hi:[0,1]
	s_nop 0
	v_pk_fma_f32 v[110:111], v[146:147], v[108:109], v[110:111] op_sel_hi:[1,0,1]
	ds_write_b64 v106, v[110:111] offset:2304
	v_pk_mul_f32 v[106:107], v[78:79], v[108:109] op_sel:[0,1] op_sel_hi:[1,0]
	s_nop 0
	v_pk_fma_f32 v[106:107], v[108:109], v[74:75], v[106:107] op_sel_hi:[1,0,1]
	s_nop 0
	s_nop 0
	v_pk_mul_f32 v[108:109], v[156:157], v[106:107] op_sel:[1,1] op_sel_hi:[0,1] neg_hi:[0,1]
	s_nop 0
	v_pk_fma_f32 v[108:109], v[156:157], v[106:107], v[108:109] op_sel_hi:[1,0,1]
	ds_write_b64 v105, v[108:109] offset:2560
	v_pk_mul_f32 v[108:109], v[78:79], v[106:107] op_sel:[0,1] op_sel_hi:[1,0]
	s_nop 0
	v_pk_fma_f32 v[106:107], v[106:107], v[74:75], v[108:109] op_sel_hi:[1,0,1]
	s_nop 0
	s_nop 0
	v_pk_mul_f32 v[108:109], v[158:159], v[106:107] op_sel:[1,1] op_sel_hi:[0,1] neg_hi:[0,1]
	s_nop 0
	v_pk_fma_f32 v[108:109], v[158:159], v[106:107], v[108:109] op_sel_hi:[1,0,1]
	ds_write_b64 v103, v[108:109] offset:2816
	v_pk_mul_f32 v[108:109], v[78:79], v[106:107] op_sel:[0,1] op_sel_hi:[1,0]
	s_nop 0
	v_pk_fma_f32 v[106:107], v[106:107], v[74:75], v[108:109] op_sel_hi:[1,0,1]
	s_nop 0
	s_nop 0
	v_pk_mul_f32 v[108:109], v[160:161], v[106:107] op_sel:[1,1] op_sel_hi:[0,1] neg_hi:[0,1]
	s_nop 0
	v_pk_fma_f32 v[108:109], v[160:161], v[106:107], v[108:109] op_sel_hi:[1,0,1]
	ds_write_b64 v102, v[108:109] offset:3072
	v_pk_mul_f32 v[102:103], v[78:79], v[106:107] op_sel:[0,1] op_sel_hi:[1,0]
	s_nop 0
	v_pk_fma_f32 v[102:103], v[106:107], v[74:75], v[102:103] op_sel_hi:[1,0,1]
	s_nop 0
	s_nop 0
	v_pk_mul_f32 v[106:107], v[130:131], v[102:103] op_sel:[1,1] op_sel_hi:[0,1] neg_hi:[0,1]
	s_nop 0
	v_pk_fma_f32 v[106:107], v[130:131], v[102:103], v[106:107] op_sel_hi:[1,0,1]
	ds_write_b64 v101, v[106:107] offset:3328
	v_pk_mul_f32 v[106:107], v[78:79], v[102:103] op_sel:[0,1] op_sel_hi:[1,0]
	s_nop 0
	v_pk_fma_f32 v[102:103], v[102:103], v[74:75], v[106:107] op_sel_hi:[1,0,1]
	s_nop 0
	s_nop 0
	v_pk_mul_f32 v[106:107], v[150:151], v[102:103] op_sel:[1,1] op_sel_hi:[0,1] neg_hi:[0,1]
	v_pk_fma_f32 v[106:107], v[150:151], v[102:103], v[106:107] op_sel_hi:[1,0,1]
	ds_write_b64 v100, v[106:107] offset:3584
	v_pk_mul_f32 v[100:101], v[78:79], v[102:103] op_sel:[0,1] op_sel_hi:[1,0]
	s_nop 0
	v_pk_fma_f32 v[100:101], v[102:103], v[74:75], v[100:101] op_sel_hi:[1,0,1]
	s_nop 0
	s_nop 0
	v_pk_mul_f32 v[102:103], v[162:163], v[100:101] op_sel:[1,1] op_sel_hi:[0,1] neg_hi:[0,1]
	v_pk_fma_f32 v[102:103], v[162:163], v[100:101], v[102:103] op_sel_hi:[1,0,1]
	ds_write_b64 v99, v[102:103] offset:3840
	v_pk_mul_f32 v[102:103], v[78:79], v[100:101] op_sel:[0,1] op_sel_hi:[1,0]
	s_nop 0
	v_pk_fma_f32 v[100:101], v[100:101], v[74:75], v[102:103] op_sel_hi:[1,0,1]
	s_nop 0
	s_nop 0
	v_pk_mul_f32 v[102:103], v[118:119], v[100:101] op_sel:[1,1] op_sel_hi:[0,1] neg_hi:[0,1]
	v_pk_fma_f32 v[102:103], v[118:119], v[100:101], v[102:103] op_sel_hi:[1,0,1]
	ds_write_b64 v98, v[102:103] offset:4096
	v_pk_mul_f32 v[98:99], v[78:79], v[100:101] op_sel:[0,1] op_sel_hi:[1,0]
	s_nop 0
	v_pk_fma_f32 v[98:99], v[100:101], v[74:75], v[98:99] op_sel_hi:[1,0,1]
	s_nop 0
	s_nop 0
	v_pk_mul_f32 v[100:101], v[120:121], v[98:99] op_sel:[1,1] op_sel_hi:[0,1] neg_hi:[0,1]
	v_pk_fma_f32 v[100:101], v[120:121], v[98:99], v[100:101] op_sel_hi:[1,0,1]
	ds_write_b64 v97, v[100:101] offset:4352
	v_pk_mul_f32 v[100:101], v[78:79], v[98:99] op_sel:[0,1] op_sel_hi:[1,0]
	s_nop 0
	v_pk_fma_f32 v[98:99], v[98:99], v[74:75], v[100:101] op_sel_hi:[1,0,1]
	s_nop 0
	s_nop 0
	v_pk_mul_f32 v[100:101], v[142:143], v[98:99] op_sel:[1,1] op_sel_hi:[0,1] neg_hi:[0,1]
	v_pk_fma_f32 v[100:101], v[142:143], v[98:99], v[100:101] op_sel_hi:[1,0,1]
	ds_write_b64 v96, v[100:101] offset:4608
	v_pk_mul_f32 v[96:97], v[78:79], v[98:99] op_sel:[0,1] op_sel_hi:[1,0]
	s_nop 0
	v_pk_fma_f32 v[96:97], v[98:99], v[74:75], v[96:97] op_sel_hi:[1,0,1]
	s_nop 0
	s_nop 0
	v_pk_mul_f32 v[98:99], v[126:127], v[96:97] op_sel:[1,1] op_sel_hi:[0,1] neg_hi:[0,1]
	v_pk_fma_f32 v[98:99], v[126:127], v[96:97], v[98:99] op_sel_hi:[1,0,1]
	ds_write_b64 v95, v[98:99] offset:4864
	v_pk_mul_f32 v[98:99], v[78:79], v[96:97] op_sel:[0,1] op_sel_hi:[1,0]
	s_nop 0
	v_pk_fma_f32 v[96:97], v[96:97], v[74:75], v[98:99] op_sel_hi:[1,0,1]
	s_nop 0
	s_nop 0
	v_pk_mul_f32 v[98:99], v[136:137], v[96:97] op_sel:[1,1] op_sel_hi:[0,1] neg_hi:[0,1]
	v_pk_fma_f32 v[98:99], v[136:137], v[96:97], v[98:99] op_sel_hi:[1,0,1]
	ds_write_b64 v94, v[98:99] offset:5120
	v_pk_mul_f32 v[94:95], v[78:79], v[96:97] op_sel:[0,1] op_sel_hi:[1,0]
	s_nop 0
	v_pk_fma_f32 v[94:95], v[96:97], v[74:75], v[94:95] op_sel_hi:[1,0,1]
	s_nop 0
	s_nop 0
	v_pk_mul_f32 v[96:97], v[122:123], v[94:95] op_sel:[1,1] op_sel_hi:[0,1] neg_hi:[0,1]
	v_pk_fma_f32 v[96:97], v[122:123], v[94:95], v[96:97] op_sel_hi:[1,0,1]
	ds_write_b64 v93, v[96:97] offset:5376
	v_pk_mul_f32 v[96:97], v[78:79], v[94:95] op_sel:[0,1] op_sel_hi:[1,0]
	s_nop 0
	v_pk_fma_f32 v[94:95], v[94:95], v[74:75], v[96:97] op_sel_hi:[1,0,1]
	s_nop 0
	s_nop 0
	v_pk_mul_f32 v[96:97], v[138:139], v[94:95] op_sel:[1,1] op_sel_hi:[0,1] neg_hi:[0,1]
	v_pk_fma_f32 v[96:97], v[138:139], v[94:95], v[96:97] op_sel_hi:[1,0,1]
	ds_write_b64 v92, v[96:97] offset:5632
	v_pk_mul_f32 v[92:93], v[78:79], v[94:95] op_sel:[0,1] op_sel_hi:[1,0]
	s_nop 0
	v_pk_fma_f32 v[92:93], v[94:95], v[74:75], v[92:93] op_sel_hi:[1,0,1]
	s_nop 0
	s_nop 0
	v_pk_mul_f32 v[94:95], v[132:133], v[92:93] op_sel:[1,1] op_sel_hi:[0,1] neg_hi:[0,1]
	v_pk_fma_f32 v[94:95], v[132:133], v[92:93], v[94:95] op_sel_hi:[1,0,1]
	ds_write_b64 v91, v[94:95] offset:5888
	v_pk_mul_f32 v[94:95], v[78:79], v[92:93] op_sel:[0,1] op_sel_hi:[1,0]
	s_nop 0
	v_pk_fma_f32 v[92:93], v[92:93], v[74:75], v[94:95] op_sel_hi:[1,0,1]
	s_nop 0
	s_nop 0
	v_pk_mul_f32 v[94:95], v[82:83], v[92:93] op_sel:[1,1] op_sel_hi:[0,1] neg_hi:[0,1]
	v_pk_fma_f32 v[82:83], v[82:83], v[92:93], v[94:95] op_sel_hi:[1,0,1]
	ds_write_b64 v90, v[82:83] offset:6144
	v_pk_mul_f32 v[82:83], v[78:79], v[92:93] op_sel:[0,1] op_sel_hi:[1,0]
	s_nop 0
	v_pk_fma_f32 v[82:83], v[92:93], v[74:75], v[82:83] op_sel_hi:[1,0,1]
	s_nop 0
	s_nop 0
	v_pk_mul_f32 v[90:91], v[148:149], v[82:83] op_sel:[1,1] op_sel_hi:[0,1] neg_hi:[0,1]
	v_pk_fma_f32 v[90:91], v[148:149], v[82:83], v[90:91] op_sel_hi:[1,0,1]
	ds_write_b64 v89, v[90:91] offset:6400
	v_pk_mul_f32 v[90:91], v[78:79], v[82:83] op_sel:[0,1] op_sel_hi:[1,0]
	s_nop 0
	v_pk_fma_f32 v[82:83], v[82:83], v[74:75], v[90:91] op_sel_hi:[1,0,1]
	s_nop 0
	s_nop 0
	v_pk_mul_f32 v[90:91], v[76:77], v[82:83] op_sel:[1,1] op_sel_hi:[0,1] neg_hi:[0,1]
	v_pk_fma_f32 v[76:77], v[76:77], v[82:83], v[90:91] op_sel_hi:[1,0,1]
	ds_write_b64 v88, v[76:77] offset:6656
	v_pk_mul_f32 v[76:77], v[78:79], v[82:83] op_sel:[0,1] op_sel_hi:[1,0]
	s_nop 0
	v_pk_fma_f32 v[76:77], v[82:83], v[74:75], v[76:77] op_sel_hi:[1,0,1]
	s_nop 0
	s_nop 0
	v_pk_mul_f32 v[82:83], v[80:81], v[76:77] op_sel:[1,1] op_sel_hi:[0,1] neg_hi:[0,1]
	v_pk_fma_f32 v[80:81], v[80:81], v[76:77], v[82:83] op_sel_hi:[1,0,1]
	ds_write_b64 v87, v[80:81] offset:6912
	v_pk_mul_f32 v[80:81], v[78:79], v[76:77] op_sel:[0,1] op_sel_hi:[1,0]
	s_nop 0
	v_pk_fma_f32 v[76:77], v[76:77], v[74:75], v[80:81] op_sel_hi:[1,0,1]
	s_nop 0
	s_nop 0
	v_pk_mul_f32 v[80:81], v[68:69], v[76:77] op_sel:[1,1] op_sel_hi:[0,1] neg_hi:[0,1]
	v_pk_fma_f32 v[68:69], v[68:69], v[76:77], v[80:81] op_sel_hi:[1,0,1]
	ds_write_b64 v86, v[68:69] offset:7168
	v_pk_mul_f32 v[68:69], v[78:79], v[76:77] op_sel:[0,1] op_sel_hi:[1,0]
	s_nop 0
	v_pk_fma_f32 v[68:69], v[76:77], v[74:75], v[68:69] op_sel_hi:[1,0,1]
	s_nop 0
	s_nop 0
	v_pk_mul_f32 v[76:77], v[72:73], v[68:69] op_sel:[1,1] op_sel_hi:[0,1] neg_hi:[0,1]
	v_pk_fma_f32 v[72:73], v[72:73], v[68:69], v[76:77] op_sel_hi:[1,0,1]
	ds_write_b64 v85, v[72:73] offset:7424
	v_pk_mul_f32 v[72:73], v[78:79], v[68:69] op_sel:[0,1] op_sel_hi:[1,0]
	s_nop 0
	v_pk_fma_f32 v[68:69], v[68:69], v[74:75], v[72:73] op_sel_hi:[1,0,1]
	s_nop 0
	s_nop 0
	v_pk_mul_f32 v[72:73], v[66:67], v[68:69] op_sel:[1,1] op_sel_hi:[0,1] neg_hi:[0,1]
	v_pk_fma_f32 v[66:67], v[66:67], v[68:69], v[72:73] op_sel_hi:[1,0,1]
	ds_write_b64 v84, v[66:67] offset:7680
	v_pk_mul_f32 v[66:67], v[78:79], v[68:69] op_sel:[0,1] op_sel_hi:[1,0]
	s_nop 0
	v_pk_fma_f32 v[66:67], v[68:69], v[74:75], v[66:67] op_sel_hi:[1,0,1]
	s_nop 0
	s_nop 0
	v_pk_mul_f32 v[68:69], v[70:71], v[66:67] op_sel:[1,1] op_sel_hi:[0,1] neg_hi:[0,1]
	v_pk_fma_f32 v[66:67], v[70:71], v[66:67], v[68:69] op_sel_hi:[1,0,1]
	ds_write_b64 v0, v[66:67]
	s_waitcnt lgkmcnt(0)
	s_barrier
	ds_read2_b64 v[66:69], v104 offset1:1
	ds_read2_b64 v[70:73], v104 offset0:2 offset1:3
	ds_read2_b64 v[74:77], v104 offset0:4 offset1:5
	ds_read2_b64 v[78:81], v104 offset0:6 offset1:7
	ds_read2_b64 v[82:85], v104 offset0:8 offset1:9
	ds_read2_b64 v[86:89], v104 offset0:10 offset1:11
	ds_read2_b64 v[90:93], v104 offset0:12 offset1:13
	ds_read2_b64 v[94:97], v104 offset0:14 offset1:15
	ds_read2_b64 v[98:101], v104 offset0:16 offset1:17
	ds_read2_b64 v[106:109], v104 offset0:18 offset1:19
	ds_read2_b64 v[110:113], v104 offset0:20 offset1:21
	ds_read2_b64 v[114:117], v104 offset0:22 offset1:23
	ds_read2_b64 v[118:121], v104 offset0:24 offset1:25
	ds_read2_b64 v[122:125], v104 offset0:26 offset1:27
	ds_read2_b64 v[126:129], v104 offset0:28 offset1:29
	ds_read2_b64 v[130:133], v104 offset0:30 offset1:31
	s_waitcnt lgkmcnt(7)
	v_pk_add_f32 v[102:103], v[66:67], v[98:99]
	v_pk_add_f32 v[66:67], v[66:67], v[98:99] neg_lo:[0,1] neg_hi:[0,1]
	v_pk_add_f32 v[98:99], v[68:69], v[100:101]
	v_pk_add_f32 v[68:69], v[68:69], v[100:101] neg_lo:[0,1] neg_hi:[0,1]
	global_load_dwordx2 v[134:135], v[2:3], off
	global_load_dwordx2 v[136:137], v[4:5], off
	global_load_dwordx2 v[138:139], v[6:7], off
	v_pk_mul_f32 v[100:101], v[68:69], s[18:19]
	global_load_dwordx2 v[148:149], v[14:15], off
	global_load_dwordx2 v[154:155], v[16:17], off
	v_pk_fma_f32 v[68:69], v[68:69], s[20:21], v[100:101] op_sel:[0,0,1] op_sel_hi:[1,0,0]
	s_waitcnt lgkmcnt(6)
	v_pk_add_f32 v[100:101], v[70:71], v[106:107]
	v_pk_add_f32 v[70:71], v[70:71], v[106:107] neg_lo:[0,1] neg_hi:[0,1]
	global_load_dwordx2 v[158:159], v[18:19], off
	v_pk_mul_f32 v[106:107], v[70:71], s[4:5]
	global_load_dwordx2 v[160:161], v[28:29], off
	global_load_dwordx2 v[164:165], v[32:33], off
	v_pk_fma_f32 v[70:71], v[70:71], s[6:7], v[106:107] op_sel:[0,0,1] op_sel_hi:[1,0,0]
	v_pk_add_f32 v[106:107], v[72:73], v[108:109]
	v_pk_add_f32 v[72:73], v[72:73], v[108:109] neg_lo:[0,1] neg_hi:[0,1]
	global_load_dwordx2 v[168:169], v[36:37], off
	v_pk_mul_f32 v[108:109], v[72:73], s[22:23]
	global_load_dwordx2 v[172:173], v[44:45], off
	v_pk_fma_f32 v[72:73], v[72:73], s[24:25], v[108:109] op_sel:[0,0,1] op_sel_hi:[1,0,0]
	s_waitcnt lgkmcnt(5)
	v_pk_add_f32 v[108:109], v[74:75], v[110:111]
	v_pk_add_f32 v[74:75], v[74:75], v[110:111] neg_lo:[0,1] neg_hi:[0,1]
	global_load_dwordx2 v[174:175], v[52:53], off
	v_pk_mul_f32 v[110:111], v[74:75], s[8:9]
	global_load_dwordx2 v[176:177], v[60:61], off
	v_pk_fma_f32 v[74:75], v[74:75], s[10:11], v[110:111] op_sel:[0,0,1] op_sel_hi:[1,0,0]
	v_pk_add_f32 v[110:111], v[76:77], v[112:113]
	v_pk_add_f32 v[76:77], v[76:77], v[112:113] neg_lo:[0,1] neg_hi:[0,1]
	s_nop 0
	v_pk_mul_f32 v[112:113], v[76:77], s[26:27]
	s_nop 0
	v_pk_fma_f32 v[76:77], v[76:77], s[0:1], v[112:113] op_sel:[0,0,1] op_sel_hi:[1,0,0]
	s_waitcnt lgkmcnt(4)
	v_pk_add_f32 v[112:113], v[78:79], v[114:115]
	v_pk_add_f32 v[78:79], v[78:79], v[114:115] neg_lo:[0,1] neg_hi:[0,1]
	s_nop 0
	v_pk_mul_f32 v[114:115], v[78:79], s[12:13]
	s_nop 0
	v_pk_fma_f32 v[78:79], v[78:79], s[14:15], v[114:115] op_sel:[0,0,1] op_sel_hi:[1,0,0]
	v_pk_add_f32 v[114:115], v[80:81], v[116:117]
	v_pk_add_f32 v[80:81], v[80:81], v[116:117] neg_lo:[0,1] neg_hi:[0,1]
	s_nop 0
	v_pk_mul_f32 v[116:117], v[80:81], s[34:35]
	s_nop 0
	v_pk_fma_f32 v[80:81], v[80:81], s[48:49], v[116:117] op_sel:[0,0,1] op_sel_hi:[1,0,0]
	s_waitcnt lgkmcnt(3)
	v_pk_add_f32 v[116:117], v[82:83], v[118:119]
	v_pk_add_f32 v[118:119], v[82:83], v[118:119] op_sel:[1,1] op_sel_hi:[0,0] neg_lo:[0,1] neg_hi:[1,0]
	s_nop 0
	v_pk_add_f32 v[82:83], v[84:85], v[120:121]
	v_pk_add_f32 v[84:85], v[84:85], v[120:121] neg_lo:[0,1] neg_hi:[0,1]
	s_nop 0
	v_pk_mul_f32 v[120:121], v[84:85], s[34:35]
	s_nop 0
	v_pk_fma_f32 v[84:85], v[84:85], s[18:19], v[120:121] op_sel:[0,0,1] op_sel_hi:[1,0,0]
	s_waitcnt lgkmcnt(2)
	v_pk_add_f32 v[120:121], v[86:87], v[122:123]
	v_pk_add_f32 v[86:87], v[86:87], v[122:123] neg_lo:[0,1] neg_hi:[0,1]
	s_nop 0
	v_pk_mul_f32 v[122:123], v[86:87], s[12:13]
	s_nop 0
	v_pk_fma_f32 v[86:87], v[86:87], s[4:5], v[122:123] op_sel:[0,0,1] op_sel_hi:[1,0,0]
	v_pk_add_f32 v[122:123], v[88:89], v[124:125]
	v_pk_add_f32 v[88:89], v[88:89], v[124:125] neg_lo:[0,1] neg_hi:[0,1]
	s_nop 0
	v_pk_mul_f32 v[124:125], v[88:89], s[26:27]
	s_nop 0
	v_pk_fma_f32 v[88:89], v[88:89], s[22:23], v[124:125] op_sel:[0,0,1] op_sel_hi:[1,0,0]
	s_waitcnt lgkmcnt(1)
	v_pk_add_f32 v[124:125], v[90:91], v[126:127]
	v_pk_add_f32 v[90:91], v[90:91], v[126:127] neg_lo:[0,1] neg_hi:[0,1]
	s_nop 0
	v_pk_mul_f32 v[126:127], v[90:91], s[8:9]
	s_nop 0
	v_pk_fma_f32 v[90:91], v[90:91], s[8:9], v[126:127] op_sel:[0,0,1] op_sel_hi:[1,0,0]
	v_pk_add_f32 v[126:127], v[92:93], v[128:129]
	v_pk_add_f32 v[92:93], v[92:93], v[128:129] neg_lo:[0,1] neg_hi:[0,1]
	s_nop 0
	v_pk_mul_f32 v[128:129], v[92:93], s[22:23]
	s_nop 0
	v_pk_fma_f32 v[92:93], v[92:93], s[26:27], v[128:129] op_sel:[0,0,1] op_sel_hi:[1,0,0]
	s_waitcnt lgkmcnt(0)
	v_pk_add_f32 v[128:129], v[94:95], v[130:131]
	v_pk_add_f32 v[94:95], v[94:95], v[130:131] neg_lo:[0,1] neg_hi:[0,1]
	s_nop 0
	v_pk_mul_f32 v[130:131], v[94:95], s[4:5]
	s_nop 0
	v_pk_fma_f32 v[94:95], v[94:95], s[12:13], v[130:131] op_sel:[0,0,1] op_sel_hi:[1,0,0]
	v_pk_add_f32 v[130:131], v[96:97], v[132:133]
	v_pk_add_f32 v[96:97], v[96:97], v[132:133] neg_lo:[0,1] neg_hi:[0,1]
	s_nop 0
	v_pk_mul_f32 v[132:133], v[96:97], s[18:19]
	s_nop 0
	v_pk_fma_f32 v[96:97], v[96:97], s[34:35], v[132:133] op_sel:[0,0,1] op_sel_hi:[1,0,0]
	v_pk_add_f32 v[132:133], v[102:103], v[116:117]
	v_pk_add_f32 v[102:103], v[102:103], v[116:117] neg_lo:[0,1] neg_hi:[0,1]
	v_pk_add_f32 v[116:117], v[98:99], v[82:83]
	v_pk_add_f32 v[82:83], v[98:99], v[82:83] neg_lo:[0,1] neg_hi:[0,1]
	s_nop 0
	v_pk_mul_f32 v[98:99], v[82:83], s[4:5]
	s_nop 0
	v_pk_fma_f32 v[82:83], v[82:83], s[6:7], v[98:99] op_sel:[0,0,1] op_sel_hi:[1,0,0]
	v_pk_add_f32 v[98:99], v[100:101], v[120:121]
	v_pk_add_f32 v[100:101], v[100:101], v[120:121] neg_lo:[0,1] neg_hi:[0,1]
	s_nop 0
	v_pk_mul_f32 v[120:121], v[100:101], s[8:9]
	s_nop 0
	v_pk_fma_f32 v[100:101], v[100:101], s[10:11], v[120:121] op_sel:[0,0,1] op_sel_hi:[1,0,0]
	v_pk_add_f32 v[120:121], v[106:107], v[122:123]
	v_pk_add_f32 v[106:107], v[106:107], v[122:123] neg_lo:[0,1] neg_hi:[0,1]
	s_nop 0
	v_pk_mul_f32 v[122:123], v[106:107], s[12:13]
	s_nop 0
	v_pk_fma_f32 v[106:107], v[106:107], s[14:15], v[122:123] op_sel:[0,0,1] op_sel_hi:[1,0,0]
	v_pk_add_f32 v[122:123], v[108:109], v[124:125]
	v_pk_add_f32 v[124:125], v[108:109], v[124:125] op_sel:[1,1] op_sel_hi:[0,0] neg_lo:[0,1] neg_hi:[1,0]
	s_nop 0
	v_pk_add_f32 v[108:109], v[110:111], v[126:127]
	v_pk_add_f32 v[110:111], v[110:111], v[126:127] neg_lo:[0,1] neg_hi:[0,1]
	s_nop 0
	v_pk_mul_f32 v[126:127], v[110:111], s[12:13]
	s_nop 0
	v_pk_fma_f32 v[110:111], v[110:111], s[4:5], v[126:127] op_sel:[0,0,1] op_sel_hi:[1,0,0]
	v_pk_add_f32 v[126:127], v[112:113], v[128:129]
	v_pk_add_f32 v[112:113], v[112:113], v[128:129] neg_lo:[0,1] neg_hi:[0,1]
	s_nop 0
	v_pk_mul_f32 v[128:129], v[112:113], s[8:9]
	s_nop 0
	v_pk_fma_f32 v[112:113], v[112:113], s[8:9], v[128:129] op_sel:[0,0,1] op_sel_hi:[1,0,0]
	v_pk_add_f32 v[128:129], v[114:115], v[130:131]
	v_pk_add_f32 v[114:115], v[114:115], v[130:131] neg_lo:[0,1] neg_hi:[0,1]
	s_nop 0
	v_pk_mul_f32 v[130:131], v[114:115], s[4:5]
	s_nop 0
	v_pk_fma_f32 v[114:115], v[114:115], s[12:13], v[130:131] op_sel:[0,0,1] op_sel_hi:[1,0,0]
	v_pk_add_f32 v[130:131], v[66:67], v[118:119]
	v_pk_add_f32 v[66:67], v[66:67], v[118:119] neg_lo:[0,1] neg_hi:[0,1]
	v_pk_add_f32 v[118:119], v[68:69], v[84:85]
	v_pk_add_f32 v[68:69], v[68:69], v[84:85] neg_lo:[0,1] neg_hi:[0,1]
	s_nop 0
	v_pk_mul_f32 v[84:85], v[68:69], s[4:5]
	s_nop 0
	v_pk_fma_f32 v[68:69], v[68:69], s[6:7], v[84:85] op_sel:[0,0,1] op_sel_hi:[1,0,0]
	v_pk_add_f32 v[84:85], v[70:71], v[86:87]
	v_pk_add_f32 v[70:71], v[70:71], v[86:87] neg_lo:[0,1] neg_hi:[0,1]
	s_nop 0
	v_pk_mul_f32 v[86:87], v[70:71], s[8:9]
	s_nop 0
	v_pk_fma_f32 v[70:71], v[70:71], s[10:11], v[86:87] op_sel:[0,0,1] op_sel_hi:[1,0,0]
	v_pk_add_f32 v[86:87], v[72:73], v[88:89]
	v_pk_add_f32 v[72:73], v[72:73], v[88:89] neg_lo:[0,1] neg_hi:[0,1]
	s_nop 0
	v_pk_mul_f32 v[88:89], v[72:73], s[12:13]
	s_nop 0
	v_pk_fma_f32 v[72:73], v[72:73], s[14:15], v[88:89] op_sel:[0,0,1] op_sel_hi:[1,0,0]
	v_pk_add_f32 v[88:89], v[74:75], v[90:91]
	v_pk_add_f32 v[90:91], v[74:75], v[90:91] op_sel:[1,1] op_sel_hi:[0,0] neg_lo:[0,1] neg_hi:[1,0]
	s_mov_b32 s15, s4
	v_pk_add_f32 v[74:75], v[76:77], v[92:93]
	v_pk_add_f32 v[76:77], v[76:77], v[92:93] neg_lo:[0,1] neg_hi:[0,1]
	s_nop 0
	v_pk_mul_f32 v[92:93], v[76:77], s[12:13]
	s_nop 0
	v_pk_fma_f32 v[76:77], v[76:77], s[4:5], v[92:93] op_sel:[0,0,1] op_sel_hi:[1,0,0]
	v_pk_add_f32 v[92:93], v[78:79], v[94:95]
	v_pk_add_f32 v[78:79], v[78:79], v[94:95] neg_lo:[0,1] neg_hi:[0,1]
	s_nop 0
	v_pk_mul_f32 v[94:95], v[78:79], s[8:9]
	s_nop 0
	v_pk_fma_f32 v[78:79], v[78:79], s[8:9], v[94:95] op_sel:[0,0,1] op_sel_hi:[1,0,0]
	v_pk_add_f32 v[94:95], v[80:81], v[96:97]
	v_pk_add_f32 v[80:81], v[80:81], v[96:97] neg_lo:[0,1] neg_hi:[0,1]
	s_nop 0
	v_pk_mul_f32 v[96:97], v[80:81], s[4:5]
	s_nop 0
	v_pk_fma_f32 v[80:81], v[80:81], s[12:13], v[96:97] op_sel:[0,0,1] op_sel_hi:[1,0,0]
	v_pk_add_f32 v[96:97], v[132:133], v[122:123]
	v_pk_add_f32 v[122:123], v[132:133], v[122:123] neg_lo:[0,1] neg_hi:[0,1]
	v_pk_add_f32 v[132:133], v[116:117], v[108:109]
	v_pk_add_f32 v[108:109], v[116:117], v[108:109] neg_lo:[0,1] neg_hi:[0,1]
	s_nop 0
	v_pk_mul_f32 v[116:117], v[108:109], s[8:9]
	s_nop 0
	v_pk_fma_f32 v[108:109], v[108:109], s[10:11], v[116:117] op_sel:[0,0,1] op_sel_hi:[1,0,0]
	v_pk_add_f32 v[116:117], v[98:99], v[126:127]
	v_pk_add_f32 v[126:127], v[98:99], v[126:127] op_sel:[1,1] op_sel_hi:[0,0] neg_lo:[0,1] neg_hi:[1,0]
	s_nop 0
	v_pk_add_f32 v[98:99], v[120:121], v[128:129]
	v_pk_add_f32 v[120:121], v[120:121], v[128:129] neg_lo:[0,1] neg_hi:[0,1]
	s_nop 0
	v_pk_mul_f32 v[128:129], v[120:121], s[8:9]
	s_nop 0
	v_pk_fma_f32 v[120:121], v[120:121], s[8:9], v[128:129] op_sel:[0,0,1] op_sel_hi:[1,0,0]
	v_pk_add_f32 v[128:129], v[102:103], v[124:125]
	v_pk_add_f32 v[102:103], v[102:103], v[124:125] neg_lo:[0,1] neg_hi:[0,1]
	v_pk_add_f32 v[124:125], v[82:83], v[110:111]
	v_pk_add_f32 v[82:83], v[82:83], v[110:111] neg_lo:[0,1] neg_hi:[0,1]
	s_nop 0
	v_pk_mul_f32 v[110:111], v[82:83], s[8:9]
	s_nop 0
	v_pk_fma_f32 v[82:83], v[82:83], s[10:11], v[110:111] op_sel:[0,0,1] op_sel_hi:[1,0,0]
	v_pk_add_f32 v[110:111], v[100:101], v[112:113]
	v_pk_add_f32 v[112:113], v[100:101], v[112:113] op_sel:[1,1] op_sel_hi:[0,0] neg_lo:[0,1] neg_hi:[1,0]
	s_nop 0
	v_pk_add_f32 v[100:101], v[106:107], v[114:115]
	v_pk_add_f32 v[106:107], v[106:107], v[114:115] neg_lo:[0,1] neg_hi:[0,1]
	s_nop 0
	v_pk_mul_f32 v[114:115], v[106:107], s[8:9]
	s_nop 0
	v_pk_fma_f32 v[106:107], v[106:107], s[8:9], v[114:115] op_sel:[0,0,1] op_sel_hi:[1,0,0]
	v_pk_add_f32 v[114:115], v[130:131], v[88:89]
	v_pk_add_f32 v[88:89], v[130:131], v[88:89] neg_lo:[0,1] neg_hi:[0,1]
	v_pk_add_f32 v[130:131], v[118:119], v[74:75]
	v_pk_add_f32 v[74:75], v[118:119], v[74:75] neg_lo:[0,1] neg_hi:[0,1]
	s_nop 0
	v_pk_mul_f32 v[118:119], v[74:75], s[8:9]
	s_nop 0
	v_pk_fma_f32 v[74:75], v[74:75], s[10:11], v[118:119] op_sel:[0,0,1] op_sel_hi:[1,0,0]
	v_pk_add_f32 v[118:119], v[84:85], v[92:93]
	v_pk_add_f32 v[92:93], v[84:85], v[92:93] op_sel:[1,1] op_sel_hi:[0,0] neg_lo:[0,1] neg_hi:[1,0]
	s_nop 0
	v_pk_add_f32 v[84:85], v[86:87], v[94:95]
	v_pk_add_f32 v[86:87], v[86:87], v[94:95] neg_lo:[0,1] neg_hi:[0,1]
	v_pk_add_f32 v[140:141], v[88:89], v[92:93]
	v_pk_mul_f32 v[94:95], v[86:87], s[8:9]
	v_pk_add_f32 v[88:89], v[88:89], v[92:93] neg_lo:[0,1] neg_hi:[0,1]
	v_pk_fma_f32 v[86:87], v[86:87], s[8:9], v[94:95] op_sel:[0,0,1] op_sel_hi:[1,0,0]
	v_pk_add_f32 v[94:95], v[66:67], v[90:91]
	v_pk_add_f32 v[66:67], v[66:67], v[90:91] neg_lo:[0,1] neg_hi:[0,1]
	v_pk_add_f32 v[90:91], v[68:69], v[76:77]
	v_pk_add_f32 v[68:69], v[68:69], v[76:77] neg_lo:[0,1] neg_hi:[0,1]
	v_pk_add_f32 v[92:93], v[74:75], v[86:87]
	v_pk_mul_f32 v[76:77], v[68:69], s[8:9]
	v_pk_add_f32 v[142:143], v[74:75], v[86:87] op_sel:[1,1] op_sel_hi:[0,0] neg_lo:[0,1] neg_hi:[1,0]
	v_pk_fma_f32 v[68:69], v[68:69], s[10:11], v[76:77] op_sel:[0,0,1] op_sel_hi:[1,0,0]
	v_pk_add_f32 v[76:77], v[70:71], v[78:79]
	v_pk_add_f32 v[78:79], v[70:71], v[78:79] op_sel:[1,1] op_sel_hi:[0,0] neg_lo:[0,1] neg_hi:[1,0]
	global_load_dwordx2 v[86:87], v[10:11], off
	v_pk_add_f32 v[70:71], v[72:73], v[80:81]
	v_pk_add_f32 v[72:73], v[72:73], v[80:81] neg_lo:[0,1] neg_hi:[0,1]
	v_pk_mul_f32 v[80:81], v[72:73], s[8:9]
	v_pk_fma_f32 v[72:73], v[72:73], s[8:9], v[80:81] op_sel:[0,0,1] op_sel_hi:[1,0,0]
	v_pk_add_f32 v[80:81], v[96:97], v[116:117]
	v_pk_add_f32 v[96:97], v[96:97], v[116:117] neg_lo:[0,1] neg_hi:[0,1]
	v_pk_add_f32 v[116:117], v[132:133], v[98:99]
	v_pk_add_f32 v[132:133], v[132:133], v[98:99] op_sel:[1,1] op_sel_hi:[0,0] neg_lo:[0,1] neg_hi:[1,0]
	v_pk_add_f32 v[74:75], v[94:95], v[76:77]
	v_pk_add_f32 v[98:99], v[122:123], v[126:127]
	v_pk_add_f32 v[122:123], v[122:123], v[126:127] neg_lo:[0,1] neg_hi:[0,1]
	v_pk_add_f32 v[126:127], v[108:109], v[120:121]
	v_pk_add_f32 v[120:121], v[108:109], v[120:121] op_sel:[1,1] op_sel_hi:[0,0] neg_lo:[0,1] neg_hi:[1,0]
	v_pk_add_f32 v[76:77], v[94:95], v[76:77] neg_lo:[0,1] neg_hi:[0,1]
	v_pk_add_f32 v[108:109], v[128:129], v[110:111]
	v_pk_add_f32 v[110:111], v[128:129], v[110:111] neg_lo:[0,1] neg_hi:[0,1]
	v_pk_add_f32 v[128:129], v[124:125], v[100:101]
	v_pk_add_f32 v[124:125], v[124:125], v[100:101] op_sel:[1,1] op_sel_hi:[0,0] neg_lo:[0,1] neg_hi:[1,0]
	global_load_dwordx2 v[94:95], v[12:13], off
	v_pk_add_f32 v[100:101], v[102:103], v[112:113]
	v_pk_add_f32 v[102:103], v[102:103], v[112:113] neg_lo:[0,1] neg_hi:[0,1]
	v_pk_add_f32 v[112:113], v[82:83], v[106:107]
	v_pk_add_f32 v[106:107], v[82:83], v[106:107] op_sel:[1,1] op_sel_hi:[0,0] neg_lo:[0,1] neg_hi:[1,0]
	v_pk_add_f32 v[146:147], v[66:67], v[78:79]
	v_pk_add_f32 v[82:83], v[114:115], v[118:119]
	v_pk_add_f32 v[114:115], v[114:115], v[118:119] neg_lo:[0,1] neg_hi:[0,1]
	v_pk_add_f32 v[118:119], v[130:131], v[84:85]
	v_pk_add_f32 v[130:131], v[130:131], v[84:85] op_sel:[1,1] op_sel_hi:[0,0] neg_lo:[0,1] neg_hi:[1,0]
	v_pk_add_f32 v[78:79], v[66:67], v[78:79] neg_lo:[0,1] neg_hi:[0,1]
	global_load_dwordx2 v[84:85], v[8:9], off
	v_pk_add_f32 v[152:153], v[68:69], v[72:73] op_sel:[1,1] op_sel_hi:[0,0] neg_lo:[0,1] neg_hi:[1,0]
	v_pk_add_f32 v[150:151], v[68:69], v[72:73]
	v_pk_add_f32 v[156:157], v[80:81], v[116:117]
	v_pk_add_f32 v[80:81], v[80:81], v[116:117] neg_lo:[0,1] neg_hi:[0,1]
	v_pk_add_f32 v[116:117], v[96:97], v[132:133]
	v_pk_add_f32 v[68:69], v[96:97], v[132:133] neg_lo:[0,1] neg_hi:[0,1]
	v_pk_add_f32 v[96:97], v[98:99], v[126:127]
	v_pk_add_f32 v[98:99], v[98:99], v[126:127] neg_lo:[0,1] neg_hi:[0,1]
	v_pk_add_f32 v[126:127], v[122:123], v[120:121]
	v_pk_add_f32 v[66:67], v[122:123], v[120:121] neg_lo:[0,1] neg_hi:[0,1]
	global_load_dwordx2 v[120:121], v[20:21], off
	v_pk_add_f32 v[122:123], v[108:109], v[128:129]
	v_pk_add_f32 v[108:109], v[108:109], v[128:129] neg_lo:[0,1] neg_hi:[0,1]
	v_pk_add_f32 v[128:129], v[110:111], v[124:125]
	v_pk_add_f32 v[72:73], v[110:111], v[124:125] neg_lo:[0,1] neg_hi:[0,1]
	global_load_dwordx2 v[110:111], v[22:23], off
	v_pk_add_f32 v[144:145], v[90:91], v[70:71]
	v_pk_add_f32 v[90:91], v[90:91], v[70:71] op_sel:[1,1] op_sel_hi:[0,0] neg_lo:[0,1] neg_hi:[1,0]
	v_pk_add_f32 v[124:125], v[100:101], v[112:113]
	v_pk_add_f32 v[100:101], v[100:101], v[112:113] neg_lo:[0,1] neg_hi:[0,1]
	v_pk_add_f32 v[112:113], v[102:103], v[106:107]
	v_pk_add_f32 v[70:71], v[102:103], v[106:107] neg_lo:[0,1] neg_hi:[0,1]
	global_load_dwordx2 v[102:103], v[24:25], off
	v_pk_add_f32 v[106:107], v[82:83], v[118:119]
	v_pk_add_f32 v[82:83], v[82:83], v[118:119] neg_lo:[0,1] neg_hi:[0,1]
	v_pk_add_f32 v[118:119], v[114:115], v[130:131]
	v_pk_add_f32 v[114:115], v[114:115], v[130:131] neg_lo:[0,1] neg_hi:[0,1]
	global_load_dwordx2 v[130:131], v[26:27], off
	v_pk_add_f32 v[162:163], v[76:77], v[90:91]
	v_pk_add_f32 v[76:77], v[76:77], v[90:91] neg_lo:[0,1] neg_hi:[0,1]
	v_pk_add_f32 v[90:91], v[146:147], v[150:151]
	v_pk_add_f32 v[146:147], v[146:147], v[150:151] neg_lo:[0,1] neg_hi:[0,1]
	v_pk_add_f32 v[150:151], v[78:79], v[152:153]
	v_pk_add_f32 v[78:79], v[78:79], v[152:153] neg_lo:[0,1] neg_hi:[0,1]
	global_load_dwordx2 v[152:153], v[34:35], off
	s_waitcnt vmcnt(19)
	v_pk_mul_f32 v[166:167], v[156:157], v[134:135] op_sel:[1,1] op_sel_hi:[0,1] neg_lo:[0,1]
	v_pk_add_f32 v[132:133], v[140:141], v[92:93]
	v_pk_fma_f32 v[134:135], v[156:157], v[134:135], v[166:167] op_sel_hi:[1,0,1]
	s_waitcnt vmcnt(18)
	global_load_dwordx2 v[166:167], v[38:39], off
	v_pk_mul_f32 v[156:157], v[106:107], v[136:137] op_sel:[1,1] op_sel_hi:[0,1] neg_lo:[0,1]
	v_pk_add_f32 v[92:93], v[140:141], v[92:93] neg_lo:[0,1] neg_hi:[0,1]
	v_pk_fma_f32 v[106:107], v[106:107], v[136:137], v[156:157] op_sel_hi:[1,0,1]
	s_waitcnt vmcnt(18)
	global_load_dwordx2 v[156:157], v[40:41], off
	v_pk_mul_f32 v[136:137], v[122:123], v[138:139] op_sel:[1,1] op_sel_hi:[0,1] neg_lo:[0,1]
	v_pk_add_f32 v[140:141], v[88:89], v[142:143]
	v_pk_fma_f32 v[122:123], v[122:123], v[138:139], v[136:137] op_sel_hi:[1,0,1]
	global_load_dwordx2 v[136:137], v[42:43], off
	v_pk_add_f32 v[88:89], v[88:89], v[142:143] neg_lo:[0,1] neg_hi:[0,1]
	v_pk_add_f32 v[142:143], v[74:75], v[144:145]
	v_pk_add_f32 v[74:75], v[74:75], v[144:145] neg_lo:[0,1] neg_hi:[0,1]
	global_load_dwordx2 v[144:145], v[30:31], off
	s_mov_b32 s11, s8
	s_waitcnt vmcnt(9)
	v_pk_mul_f32 v[138:139], v[142:143], v[84:85] op_sel:[1,1] op_sel_hi:[0,1] neg_lo:[0,1]
	s_nop 0
	v_pk_fma_f32 v[84:85], v[142:143], v[84:85], v[138:139] op_sel_hi:[1,0,1]
	global_load_dwordx2 v[142:143], v[46:47], off
	v_pk_mul_f32 v[138:139], v[96:97], v[86:87] op_sel:[1,1] op_sel_hi:[0,1] neg_lo:[0,1]
	s_nop 0
	v_pk_fma_f32 v[86:87], v[96:97], v[86:87], v[138:139] op_sel_hi:[1,0,1]
	global_load_dwordx2 v[138:139], v[48:49], off
	v_pk_mul_f32 v[96:97], v[132:133], v[94:95] op_sel:[1,1] op_sel_hi:[0,1] neg_lo:[0,1]
	s_nop 0
	v_pk_fma_f32 v[94:95], v[132:133], v[94:95], v[96:97] op_sel_hi:[1,0,1]
	global_load_dwordx2 v[96:97], v[50:51], off
	v_pk_mul_f32 v[132:133], v[124:125], v[148:149] op_sel:[1,1] op_sel_hi:[0,1] neg_lo:[0,1]
	s_nop 0
	v_pk_fma_f32 v[124:125], v[124:125], v[148:149], v[132:133] op_sel_hi:[1,0,1]
	global_load_dwordx2 v[148:149], v[54:55], off
	v_pk_mul_f32 v[132:133], v[90:91], v[154:155] op_sel:[1,1] op_sel_hi:[0,1] neg_lo:[0,1]
	s_nop 0
	v_pk_fma_f32 v[90:91], v[90:91], v[154:155], v[132:133] op_sel_hi:[1,0,1]
	global_load_dwordx2 v[154:155], v[56:57], off
	v_pk_mul_f32 v[132:133], v[116:117], v[158:159] op_sel:[1,1] op_sel_hi:[0,1] neg_lo:[0,1]
	v_pk_fma_f32 v[116:117], v[116:117], v[158:159], v[132:133] op_sel_hi:[1,0,1]
	global_load_dwordx2 v[132:133], v[58:59], off
	s_waitcnt vmcnt(14)
	v_pk_mul_f32 v[158:159], v[118:119], v[120:121] op_sel:[1,1] op_sel_hi:[0,1] neg_lo:[0,1]
	v_pk_fma_f32 v[118:119], v[118:119], v[120:121], v[158:159] op_sel_hi:[1,0,1]
	s_waitcnt vmcnt(13)
	global_load_dwordx2 v[158:159], v[62:63], off
	v_pk_mul_f32 v[120:121], v[128:129], v[110:111] op_sel:[1,1] op_sel_hi:[0,1] neg_lo:[0,1]
	v_pk_fma_f32 v[110:111], v[128:129], v[110:111], v[120:121] op_sel_hi:[1,0,1]
	global_load_dwordx2 v[128:129], v[64:65], off
	s_waitcnt vmcnt(14)
	v_pk_mul_f32 v[120:121], v[162:163], v[102:103] op_sel:[1,1] op_sel_hi:[0,1] neg_lo:[0,1]
	v_mov_b32 v0, 0
	s_nop 0
	v_pk_fma_f32 v[102:103], v[162:163], v[102:103], v[120:121] op_sel_hi:[1,0,1]
	s_waitcnt vmcnt(13)
	v_pk_mul_f32 v[120:121], v[126:127], v[130:131] op_sel:[1,1] op_sel_hi:[0,1] neg_lo:[0,1]
	v_pk_fma_f32 v[120:121], v[126:127], v[130:131], v[120:121] op_sel_hi:[1,0,1]
	v_pk_mul_f32 v[126:127], v[140:141], v[160:161] op_sel:[1,1] op_sel_hi:[0,1] neg_lo:[0,1]
	v_pk_fma_f32 v[126:127], v[140:141], v[160:161], v[126:127] op_sel_hi:[1,0,1]
	s_waitcnt vmcnt(12)
	v_pk_mul_f32 v[140:141], v[80:81], v[152:153] op_sel:[1,1] op_sel_hi:[0,1] neg_lo:[0,1]
	v_pk_fma_f32 v[80:81], v[80:81], v[152:153], v[140:141] op_sel_hi:[1,0,1]
	v_pk_mul_f32 v[140:141], v[82:83], v[168:169] op_sel:[1,1] op_sel_hi:[0,1] neg_lo:[0,1]
	v_pk_fma_f32 v[82:83], v[82:83], v[168:169], v[140:141] op_sel_hi:[1,0,1]
	s_waitcnt vmcnt(11)
	v_pk_mul_f32 v[140:141], v[108:109], v[166:167] op_sel:[1,1] op_sel_hi:[0,1] neg_lo:[0,1]
	v_pk_fma_f32 v[108:109], v[108:109], v[166:167], v[140:141] op_sel_hi:[1,0,1]
	s_waitcnt vmcnt(10)
	v_pk_mul_f32 v[140:141], v[74:75], v[156:157] op_sel:[1,1] op_sel_hi:[0,1] neg_lo:[0,1]
	v_pk_fma_f32 v[74:75], v[74:75], v[156:157], v[140:141] op_sel_hi:[1,0,1]
	s_waitcnt vmcnt(9)
	v_pk_mul_f32 v[140:141], v[98:99], v[136:137] op_sel:[1,1] op_sel_hi:[0,1] neg_lo:[0,1]
	v_pk_fma_f32 v[98:99], v[98:99], v[136:137], v[140:141] op_sel_hi:[1,0,1]
	v_pk_mul_f32 v[136:137], v[92:93], v[172:173] op_sel:[1,1] op_sel_hi:[0,1] neg_lo:[0,1]
	v_pk_fma_f32 v[92:93], v[92:93], v[172:173], v[136:137] op_sel_hi:[1,0,1]
	s_waitcnt vmcnt(8)
	v_pk_mul_f32 v[130:131], v[112:113], v[144:145] op_sel:[1,1] op_sel_hi:[0,1] neg_lo:[0,1]
	v_pk_fma_f32 v[112:113], v[112:113], v[144:145], v[130:131] op_sel_hi:[1,0,1]
	s_waitcnt vmcnt(7)
	v_pk_mul_f32 v[136:137], v[100:101], v[142:143] op_sel:[1,1] op_sel_hi:[0,1] neg_lo:[0,1]
	v_pk_fma_f32 v[100:101], v[100:101], v[142:143], v[136:137] op_sel_hi:[1,0,1]
	s_waitcnt vmcnt(6)
	v_pk_mul_f32 v[136:137], v[146:147], v[138:139] op_sel:[1,1] op_sel_hi:[0,1] neg_lo:[0,1]
	v_pk_fma_f32 v[136:137], v[146:147], v[138:139], v[136:137] op_sel_hi:[1,0,1]
	s_waitcnt vmcnt(5)
	v_pk_mul_f32 v[138:139], v[68:69], v[96:97] op_sel:[1,1] op_sel_hi:[0,1] neg_lo:[0,1]
	v_pk_fma_f32 v[68:69], v[68:69], v[96:97], v[138:139] op_sel_hi:[1,0,1]
	v_pk_mul_f32 v[96:97], v[114:115], v[174:175] op_sel:[1,1] op_sel_hi:[0,1] neg_lo:[0,1]
	v_pk_fma_f32 v[96:97], v[114:115], v[174:175], v[96:97] op_sel_hi:[1,0,1]
	s_waitcnt vmcnt(4)
	v_pk_mul_f32 v[114:115], v[72:73], v[148:149] op_sel:[1,1] op_sel_hi:[0,1] neg_lo:[0,1]
	v_pk_fma_f32 v[72:73], v[72:73], v[148:149], v[114:115] op_sel_hi:[1,0,1]
	v_pk_mul_f32 v[130:131], v[150:151], v[164:165] op_sel:[1,1] op_sel_hi:[0,1] neg_lo:[0,1]
	s_waitcnt vmcnt(3)
	v_pk_mul_f32 v[114:115], v[76:77], v[154:155] op_sel:[1,1] op_sel_hi:[0,1] neg_lo:[0,1]
	v_pk_fma_f32 v[76:77], v[76:77], v[154:155], v[114:115] op_sel_hi:[1,0,1]
	s_waitcnt vmcnt(2)
	v_pk_mul_f32 v[114:115], v[66:67], v[132:133] op_sel:[1,1] op_sel_hi:[0,1] neg_lo:[0,1]
	v_pk_fma_f32 v[66:67], v[66:67], v[132:133], v[114:115] op_sel_hi:[1,0,1]
	v_pk_mul_f32 v[114:115], v[88:89], v[176:177] op_sel:[1,1] op_sel_hi:[0,1] neg_lo:[0,1]
	v_pk_fma_f32 v[88:89], v[88:89], v[176:177], v[114:115] op_sel_hi:[1,0,1]
	s_waitcnt vmcnt(1)
	v_pk_mul_f32 v[114:115], v[70:71], v[158:159] op_sel:[1,1] op_sel_hi:[0,1] neg_lo:[0,1]
	v_pk_fma_f32 v[70:71], v[70:71], v[158:159], v[114:115] op_sel_hi:[1,0,1]
	s_waitcnt vmcnt(0)
	v_pk_mul_f32 v[114:115], v[78:79], v[128:129] op_sel:[1,1] op_sel_hi:[0,1] neg_lo:[0,1]
	v_pk_fma_f32 v[78:79], v[78:79], v[128:129], v[114:115] op_sel_hi:[1,0,1]
	v_pk_add_f32 v[128:129], v[106:107], v[82:83]
	v_pk_add_f32 v[82:83], v[106:107], v[82:83] neg_lo:[0,1] neg_hi:[0,1]
	v_pk_fma_f32 v[130:131], v[150:151], v[164:165], v[130:131] op_sel_hi:[1,0,1]
	v_pk_mul_f32 v[106:107], v[82:83], s[50:51]
	v_pk_add_f32 v[114:115], v[134:135], v[80:81]
	v_pk_fma_f32 v[82:83], v[82:83], s[20:21], v[106:107] op_sel:[0,0,1] op_sel_hi:[1,0,0]
	v_pk_add_f32 v[106:107], v[122:123], v[108:109]
	v_pk_add_f32 v[108:109], v[122:123], v[108:109] neg_lo:[0,1] neg_hi:[0,1]
	s_mov_b32 s21, s34
	v_pk_mul_f32 v[122:123], v[108:109], s[14:15]
	v_pk_add_f32 v[80:81], v[134:135], v[80:81] neg_lo:[0,1] neg_hi:[0,1]
	v_pk_fma_f32 v[108:109], v[108:109], s[6:7], v[122:123] op_sel:[0,0,1] op_sel_hi:[1,0,0]
	v_pk_add_f32 v[122:123], v[84:85], v[74:75]
	v_pk_add_f32 v[74:75], v[84:85], v[74:75] neg_lo:[0,1] neg_hi:[0,1]
	s_mov_b32 s7, s12
	v_pk_mul_f32 v[84:85], v[74:75], s[52:53]
	v_add_u32_e32 v0, v0, v170
	v_pk_fma_f32 v[74:75], v[74:75], s[24:25], v[84:85] op_sel:[0,0,1] op_sel_hi:[1,0,0]
	v_pk_add_f32 v[84:85], v[86:87], v[98:99]
	v_pk_add_f32 v[86:87], v[86:87], v[98:99] neg_lo:[0,1] neg_hi:[0,1]
	s_mov_b32 s25, s26
	v_pk_mul_f32 v[98:99], v[86:87], s[10:11]
	v_lshlrev_b32_e32 v105, 5, v0
	v_pk_fma_f32 v[86:87], v[86:87], s[10:11], v[98:99] op_sel:[0,0,1] op_sel_hi:[1,0,0]
	v_pk_add_f32 v[98:99], v[94:95], v[92:93]
	v_pk_add_f32 v[92:93], v[94:95], v[92:93] neg_lo:[0,1] neg_hi:[0,1]
	s_nop 0
	v_pk_mul_f32 v[94:95], v[92:93], s[24:25]
	s_nop 0
	v_pk_fma_f32 v[92:93], v[92:93], s[0:1], v[94:95] op_sel:[0,0,1] op_sel_hi:[1,0,0]
	v_pk_add_f32 v[94:95], v[124:125], v[100:101]
	v_pk_add_f32 v[100:101], v[124:125], v[100:101] neg_lo:[0,1] neg_hi:[0,1]
	s_nop 0
	v_pk_mul_f32 v[124:125], v[100:101], s[6:7]
	s_nop 0
	v_pk_fma_f32 v[100:101], v[100:101], s[14:15], v[124:125] op_sel:[0,0,1] op_sel_hi:[1,0,0]
	v_pk_add_f32 v[124:125], v[90:91], v[136:137]
	v_pk_add_f32 v[90:91], v[90:91], v[136:137] neg_lo:[0,1] neg_hi:[0,1]
	s_nop 0
	v_pk_mul_f32 v[132:133], v[90:91], s[20:21]
	s_nop 0
	v_pk_fma_f32 v[90:91], v[90:91], s[48:49], v[132:133] op_sel:[0,0,1] op_sel_hi:[1,0,0]
	v_pk_add_f32 v[132:133], v[116:117], v[68:69]
	v_pk_add_f32 v[116:117], v[116:117], v[68:69] op_sel:[1,1] op_sel_hi:[0,0] neg_lo:[1,0] neg_hi:[0,1]
	s_nop 0
	v_pk_add_f32 v[68:69], v[118:119], v[96:97]
	v_pk_add_f32 v[96:97], v[118:119], v[96:97] neg_lo:[0,1] neg_hi:[0,1]
	s_nop 0
	v_pk_mul_f32 v[118:119], v[96:97], s[20:21]
	s_nop 0
	v_pk_fma_f32 v[96:97], v[96:97], s[18:19], v[118:119] op_sel:[0,0,1] op_sel_hi:[1,0,0]
	v_pk_add_f32 v[118:119], v[110:111], v[72:73]
	v_pk_add_f32 v[72:73], v[110:111], v[72:73] neg_lo:[0,1] neg_hi:[0,1]
	s_nop 0
	v_pk_mul_f32 v[110:111], v[72:73], s[6:7]
	s_nop 0
	v_pk_fma_f32 v[72:73], v[72:73], s[4:5], v[110:111] op_sel:[0,0,1] op_sel_hi:[1,0,0]
	v_pk_add_f32 v[110:111], v[102:103], v[76:77]
	v_pk_add_f32 v[76:77], v[102:103], v[76:77] neg_lo:[0,1] neg_hi:[0,1]
	s_nop 0
	v_pk_mul_f32 v[102:103], v[76:77], s[24:25]
	s_nop 0
	v_pk_fma_f32 v[76:77], v[76:77], s[22:23], v[102:103] op_sel:[0,0,1] op_sel_hi:[1,0,0]
	v_pk_add_f32 v[102:103], v[120:121], v[66:67]
	v_pk_add_f32 v[66:67], v[120:121], v[66:67] neg_lo:[0,1] neg_hi:[0,1]
	s_nop 0
	v_pk_mul_f32 v[120:121], v[66:67], s[10:11]
	s_nop 0
	v_pk_fma_f32 v[66:67], v[66:67], s[8:9], v[120:121] op_sel:[0,0,1] op_sel_hi:[1,0,0]
	v_pk_add_f32 v[120:121], v[126:127], v[88:89]
	v_pk_add_f32 v[88:89], v[126:127], v[88:89] neg_lo:[0,1] neg_hi:[0,1]
	s_nop 0
	v_pk_mul_f32 v[126:127], v[88:89], s[52:53]
	s_nop 0
	v_pk_fma_f32 v[88:89], v[88:89], s[26:27], v[126:127] op_sel:[0,0,1] op_sel_hi:[1,0,0]
	v_pk_add_f32 v[126:127], v[112:113], v[70:71]
	v_pk_add_f32 v[70:71], v[112:113], v[70:71] neg_lo:[0,1] neg_hi:[0,1]
	s_nop 0
	v_pk_mul_f32 v[112:113], v[70:71], s[14:15]
	s_nop 0
	v_pk_fma_f32 v[70:71], v[70:71], s[12:13], v[112:113] op_sel:[0,0,1] op_sel_hi:[1,0,0]
	v_pk_add_f32 v[112:113], v[130:131], v[78:79]
	v_pk_add_f32 v[78:79], v[130:131], v[78:79] neg_lo:[0,1] neg_hi:[0,1]
	s_nop 0
	v_pk_mul_f32 v[130:131], v[78:79], s[50:51]
	s_nop 0
	v_pk_fma_f32 v[78:79], v[78:79], s[34:35], v[130:131] op_sel:[0,0,1] op_sel_hi:[1,0,0]
	v_pk_add_f32 v[130:131], v[114:115], v[132:133]
	v_pk_add_f32 v[114:115], v[114:115], v[132:133] neg_lo:[0,1] neg_hi:[0,1]
	v_pk_add_f32 v[132:133], v[128:129], v[68:69]
	v_pk_add_f32 v[68:69], v[128:129], v[68:69] neg_lo:[0,1] neg_hi:[0,1]
	s_nop 0
	v_pk_mul_f32 v[128:129], v[68:69], s[14:15]
	s_nop 0
	v_pk_fma_f32 v[68:69], v[68:69], s[6:7], v[128:129] op_sel:[0,0,1] op_sel_hi:[1,0,0]
	v_pk_add_f32 v[128:129], v[106:107], v[118:119]
	v_pk_add_f32 v[106:107], v[106:107], v[118:119] neg_lo:[0,1] neg_hi:[0,1]
	s_nop 0
	v_pk_mul_f32 v[118:119], v[106:107], s[10:11]
	s_nop 0
	v_pk_fma_f32 v[106:107], v[106:107], s[10:11], v[118:119] op_sel:[0,0,1] op_sel_hi:[1,0,0]
	v_pk_add_f32 v[118:119], v[122:123], v[110:111]
	v_pk_add_f32 v[110:111], v[122:123], v[110:111] neg_lo:[0,1] neg_hi:[0,1]
	s_nop 0
	v_pk_mul_f32 v[122:123], v[110:111], s[6:7]
	s_nop 0
	v_pk_fma_f32 v[110:111], v[110:111], s[14:15], v[122:123] op_sel:[0,0,1] op_sel_hi:[1,0,0]
	v_pk_add_f32 v[122:123], v[84:85], v[102:103]
	v_pk_add_f32 v[102:103], v[84:85], v[102:103] op_sel:[1,1] op_sel_hi:[0,0] neg_lo:[1,0] neg_hi:[0,1]
	s_nop 0
	v_pk_add_f32 v[84:85], v[98:99], v[120:121]
	v_pk_add_f32 v[98:99], v[98:99], v[120:121] neg_lo:[0,1] neg_hi:[0,1]
	s_nop 0
	v_pk_mul_f32 v[120:121], v[98:99], s[6:7]
	s_nop 0
	v_pk_fma_f32 v[98:99], v[98:99], s[4:5], v[120:121] op_sel:[0,0,1] op_sel_hi:[1,0,0]
	v_pk_add_f32 v[120:121], v[94:95], v[126:127]
	v_pk_add_f32 v[94:95], v[94:95], v[126:127] neg_lo:[0,1] neg_hi:[0,1]
	s_nop 0
	v_pk_mul_f32 v[126:127], v[94:95], s[10:11]
	s_nop 0
	v_pk_fma_f32 v[94:95], v[94:95], s[8:9], v[126:127] op_sel:[0,0,1] op_sel_hi:[1,0,0]
	v_pk_add_f32 v[126:127], v[124:125], v[112:113]
	v_pk_add_f32 v[112:113], v[124:125], v[112:113] neg_lo:[0,1] neg_hi:[0,1]
	s_nop 0
	v_pk_mul_f32 v[124:125], v[112:113], s[14:15]
	s_nop 0
	v_pk_fma_f32 v[112:113], v[112:113], s[12:13], v[124:125] op_sel:[0,0,1] op_sel_hi:[1,0,0]
	v_pk_add_f32 v[124:125], v[80:81], v[116:117]
	v_pk_add_f32 v[80:81], v[80:81], v[116:117] neg_lo:[0,1] neg_hi:[0,1]
	v_pk_add_f32 v[116:117], v[82:83], v[96:97]
	v_pk_add_f32 v[82:83], v[82:83], v[96:97] neg_lo:[0,1] neg_hi:[0,1]
	s_nop 0
	v_pk_mul_f32 v[96:97], v[82:83], s[14:15]
	s_nop 0
	v_pk_fma_f32 v[82:83], v[82:83], s[6:7], v[96:97] op_sel:[0,0,1] op_sel_hi:[1,0,0]
	v_pk_add_f32 v[96:97], v[108:109], v[72:73]
	v_pk_add_f32 v[72:73], v[108:109], v[72:73] neg_lo:[0,1] neg_hi:[0,1]
	s_nop 0
	v_pk_mul_f32 v[108:109], v[72:73], s[10:11]
	s_nop 0
	v_pk_fma_f32 v[72:73], v[72:73], s[10:11], v[108:109] op_sel:[0,0,1] op_sel_hi:[1,0,0]
	v_pk_add_f32 v[108:109], v[74:75], v[76:77]
	v_pk_add_f32 v[74:75], v[74:75], v[76:77] neg_lo:[0,1] neg_hi:[0,1]
	s_nop 0
	v_pk_mul_f32 v[76:77], v[74:75], s[6:7]
	s_nop 0
	v_pk_fma_f32 v[74:75], v[74:75], s[14:15], v[76:77] op_sel:[0,0,1] op_sel_hi:[1,0,0]
	v_pk_add_f32 v[76:77], v[86:87], v[66:67]
	v_pk_add_f32 v[86:87], v[86:87], v[66:67] op_sel:[1,1] op_sel_hi:[0,0] neg_lo:[1,0] neg_hi:[0,1]
	s_nop 0
	v_pk_add_f32 v[66:67], v[92:93], v[88:89]
	v_pk_add_f32 v[88:89], v[92:93], v[88:89] neg_lo:[0,1] neg_hi:[0,1]
	s_nop 0
	v_pk_mul_f32 v[92:93], v[88:89], s[6:7]
	s_nop 0
	v_pk_fma_f32 v[88:89], v[88:89], s[4:5], v[92:93] op_sel:[0,0,1] op_sel_hi:[1,0,0]
	v_pk_add_f32 v[92:93], v[100:101], v[70:71]
	v_pk_add_f32 v[70:71], v[100:101], v[70:71] neg_lo:[0,1] neg_hi:[0,1]
	s_nop 0
	v_pk_mul_f32 v[100:101], v[70:71], s[10:11]
	s_nop 0
	v_pk_fma_f32 v[70:71], v[70:71], s[8:9], v[100:101] op_sel:[0,0,1] op_sel_hi:[1,0,0]
	v_pk_add_f32 v[100:101], v[90:91], v[78:79]
	v_pk_add_f32 v[78:79], v[90:91], v[78:79] neg_lo:[0,1] neg_hi:[0,1]
	s_nop 0
	v_pk_mul_f32 v[90:91], v[78:79], s[14:15]
	s_nop 0
	v_pk_fma_f32 v[78:79], v[78:79], s[12:13], v[90:91] op_sel:[0,0,1] op_sel_hi:[1,0,0]
	v_pk_add_f32 v[90:91], v[130:131], v[122:123]
	v_pk_add_f32 v[122:123], v[130:131], v[122:123] neg_lo:[0,1] neg_hi:[0,1]
	v_pk_add_f32 v[130:131], v[132:133], v[84:85]
	v_pk_add_f32 v[84:85], v[132:133], v[84:85] neg_lo:[0,1] neg_hi:[0,1]
	s_nop 0
	v_pk_mul_f32 v[132:133], v[84:85], s[10:11]
	s_nop 0
	v_pk_fma_f32 v[84:85], v[84:85], s[10:11], v[132:133] op_sel:[0,0,1] op_sel_hi:[1,0,0]
	v_pk_add_f32 v[132:133], v[128:129], v[120:121]
	v_pk_add_f32 v[128:129], v[128:129], v[120:121] op_sel:[1,1] op_sel_hi:[0,0] neg_lo:[1,0] neg_hi:[0,1]
	s_nop 0
	v_pk_add_f32 v[120:121], v[118:119], v[126:127]
	v_pk_add_f32 v[118:119], v[118:119], v[126:127] neg_lo:[0,1] neg_hi:[0,1]
	s_nop 0
	v_pk_mul_f32 v[126:127], v[118:119], s[10:11]
	s_nop 0
	v_pk_fma_f32 v[118:119], v[118:119], s[8:9], v[126:127] op_sel:[0,0,1] op_sel_hi:[1,0,0]
	v_pk_add_f32 v[126:127], v[114:115], v[102:103]
	v_pk_add_f32 v[102:103], v[114:115], v[102:103] neg_lo:[0,1] neg_hi:[0,1]
	v_pk_add_f32 v[114:115], v[68:69], v[98:99]
	v_pk_add_f32 v[68:69], v[68:69], v[98:99] neg_lo:[0,1] neg_hi:[0,1]
	s_nop 0
	v_pk_mul_f32 v[98:99], v[68:69], s[10:11]
	s_nop 0
	v_pk_fma_f32 v[68:69], v[68:69], s[10:11], v[98:99] op_sel:[0,0,1] op_sel_hi:[1,0,0]
	v_pk_add_f32 v[98:99], v[106:107], v[94:95]
	v_pk_add_f32 v[106:107], v[106:107], v[94:95] op_sel:[1,1] op_sel_hi:[0,0] neg_lo:[1,0] neg_hi:[0,1]
	s_nop 0
	v_pk_add_f32 v[94:95], v[110:111], v[112:113]
	v_pk_add_f32 v[110:111], v[110:111], v[112:113] neg_lo:[0,1] neg_hi:[0,1]
	s_nop 0
	v_pk_mul_f32 v[112:113], v[110:111], s[10:11]
	s_nop 0
	v_pk_fma_f32 v[110:111], v[110:111], s[8:9], v[112:113] op_sel:[0,0,1] op_sel_hi:[1,0,0]
	v_pk_add_f32 v[112:113], v[124:125], v[76:77]
	v_pk_add_f32 v[76:77], v[124:125], v[76:77] neg_lo:[0,1] neg_hi:[0,1]
	v_pk_add_f32 v[124:125], v[116:117], v[66:67]
	v_pk_add_f32 v[66:67], v[116:117], v[66:67] neg_lo:[0,1] neg_hi:[0,1]
	s_nop 0
	v_pk_mul_f32 v[116:117], v[66:67], s[10:11]
	s_nop 0
	v_pk_fma_f32 v[66:67], v[66:67], s[10:11], v[116:117] op_sel:[0,0,1] op_sel_hi:[1,0,0]
	v_pk_add_f32 v[116:117], v[96:97], v[92:93]
	v_pk_add_f32 v[96:97], v[96:97], v[92:93] op_sel:[1,1] op_sel_hi:[0,0] neg_lo:[1,0] neg_hi:[0,1]
	v_pk_add_f32 v[134:135], v[112:113], v[116:117]
	v_pk_add_f32 v[92:93], v[108:109], v[100:101]
	v_pk_add_f32 v[100:101], v[108:109], v[100:101] neg_lo:[0,1] neg_hi:[0,1]
	v_pk_add_f32 v[112:113], v[112:113], v[116:117] neg_lo:[0,1] neg_hi:[0,1]
	v_pk_mul_f32 v[108:109], v[100:101], s[10:11]
	v_pk_add_f32 v[116:117], v[124:125], v[92:93]
	v_pk_fma_f32 v[100:101], v[100:101], s[8:9], v[108:109] op_sel:[0,0,1] op_sel_hi:[1,0,0]
	v_pk_add_f32 v[108:109], v[80:81], v[86:87]
	v_pk_add_f32 v[80:81], v[80:81], v[86:87] neg_lo:[0,1] neg_hi:[0,1]
	v_pk_add_f32 v[86:87], v[82:83], v[88:89]
	v_pk_add_f32 v[82:83], v[82:83], v[88:89] neg_lo:[0,1] neg_hi:[0,1]
	s_nop 0
	v_pk_mul_f32 v[88:89], v[82:83], s[10:11]
	s_nop 0
	v_pk_fma_f32 v[82:83], v[82:83], s[10:11], v[88:89] op_sel:[0,0,1] op_sel_hi:[1,0,0]
	v_pk_add_f32 v[88:89], v[72:73], v[70:71]
	v_pk_add_f32 v[72:73], v[72:73], v[70:71] op_sel:[1,1] op_sel_hi:[0,0] neg_lo:[1,0] neg_hi:[0,1]
	v_pk_add_f32 v[136:137], v[108:109], v[88:89]
	v_pk_add_f32 v[70:71], v[74:75], v[78:79]
	v_pk_add_f32 v[74:75], v[74:75], v[78:79] neg_lo:[0,1] neg_hi:[0,1]
	v_pk_add_f32 v[88:89], v[108:109], v[88:89] neg_lo:[0,1] neg_hi:[0,1]
	v_pk_mul_f32 v[78:79], v[74:75], s[10:11]
	v_pk_add_f32 v[108:109], v[86:87], v[70:71]
	v_pk_fma_f32 v[74:75], v[74:75], s[8:9], v[78:79] op_sel:[0,0,1] op_sel_hi:[1,0,0]
	v_pk_add_f32 v[78:79], v[90:91], v[132:133]
	v_pk_add_f32 v[90:91], v[90:91], v[132:133] neg_lo:[0,1] neg_hi:[0,1]
	v_pk_add_f32 v[132:133], v[130:131], v[120:121]
	v_pk_add_f32 v[130:131], v[130:131], v[120:121] op_sel:[1,1] op_sel_hi:[0,0] neg_lo:[1,0] neg_hi:[0,1]
	v_pk_add_f32 v[138:139], v[80:81], v[72:73] neg_lo:[0,1] neg_hi:[0,1]
	v_pk_add_f32 v[120:121], v[122:123], v[128:129]
	v_pk_add_f32 v[122:123], v[122:123], v[128:129] neg_lo:[0,1] neg_hi:[0,1]
	v_pk_add_f32 v[128:129], v[84:85], v[118:119]
	v_pk_add_f32 v[118:119], v[84:85], v[118:119] op_sel:[1,1] op_sel_hi:[0,0] neg_lo:[1,0] neg_hi:[0,1]
	v_pk_add_f32 v[140:141], v[82:83], v[74:75]
	v_pk_add_f32 v[84:85], v[126:127], v[98:99]
	v_pk_add_f32 v[98:99], v[126:127], v[98:99] neg_lo:[0,1] neg_hi:[0,1]
	v_pk_add_f32 v[126:127], v[114:115], v[94:95]
	v_pk_add_f32 v[114:115], v[114:115], v[94:95] op_sel:[1,1] op_sel_hi:[0,0] neg_lo:[1,0] neg_hi:[0,1]
	v_pk_add_f32 v[142:143], v[78:79], v[132:133]
	v_pk_add_f32 v[94:95], v[102:103], v[106:107]
	v_pk_add_f32 v[102:103], v[102:103], v[106:107] neg_lo:[0,1] neg_hi:[0,1]
	v_pk_add_f32 v[106:107], v[68:69], v[110:111]
	v_pk_add_f32 v[110:111], v[68:69], v[110:111] op_sel:[1,1] op_sel_hi:[0,0] neg_lo:[1,0] neg_hi:[0,1]
	v_pk_add_f32 v[132:133], v[78:79], v[132:133] neg_lo:[0,1] neg_hi:[0,1]
	v_pk_add_f32 v[92:93], v[124:125], v[92:93] op_sel:[1,1] op_sel_hi:[0,0] neg_lo:[1,0] neg_hi:[0,1]
	v_pk_add_f32 v[124:125], v[76:77], v[96:97]
	v_pk_add_f32 v[76:77], v[76:77], v[96:97] neg_lo:[0,1] neg_hi:[0,1]
	v_pk_add_f32 v[96:97], v[66:67], v[100:101]
	v_pk_add_f32 v[100:101], v[66:67], v[100:101] op_sel:[1,1] op_sel_hi:[0,0] neg_lo:[1,0] neg_hi:[0,1]
	v_pk_add_f32 v[70:71], v[86:87], v[70:71] op_sel:[1,1] op_sel_hi:[0,0] neg_lo:[1,0] neg_hi:[0,1]
	v_pk_add_f32 v[74:75], v[82:83], v[74:75] op_sel:[1,1] op_sel_hi:[0,0] neg_lo:[1,0] neg_hi:[0,1]
	v_pk_add_f32 v[86:87], v[80:81], v[72:73]
	v_pk_add_f32 v[144:145], v[90:91], v[130:131]
	v_pk_add_f32 v[82:83], v[90:91], v[130:131] neg_lo:[0,1] neg_hi:[0,1]
	v_pk_add_f32 v[90:91], v[120:121], v[128:129]
	v_pk_add_f32 v[120:121], v[120:121], v[128:129] neg_lo:[0,1] neg_hi:[0,1]
	v_pk_add_f32 v[128:129], v[122:123], v[118:119]
	v_pk_add_f32 v[68:69], v[122:123], v[118:119] neg_lo:[0,1] neg_hi:[0,1]
	v_pk_add_f32 v[118:119], v[84:85], v[126:127]
	v_pk_add_f32 v[122:123], v[84:85], v[126:127] neg_lo:[0,1] neg_hi:[0,1]
	v_pk_add_f32 v[126:127], v[98:99], v[114:115]
	v_pk_add_f32 v[78:79], v[98:99], v[114:115] neg_lo:[0,1] neg_hi:[0,1]
	v_pk_add_f32 v[98:99], v[94:95], v[106:107]
	v_pk_add_f32 v[94:95], v[94:95], v[106:107] neg_lo:[0,1] neg_hi:[0,1]
	v_pk_add_f32 v[106:107], v[102:103], v[110:111]
	v_pk_add_f32 v[66:67], v[102:103], v[110:111] neg_lo:[0,1] neg_hi:[0,1]
	v_pk_add_f32 v[102:103], v[134:135], v[116:117]
	v_pk_add_f32 v[110:111], v[134:135], v[116:117] neg_lo:[0,1] neg_hi:[0,1]
	v_pk_add_f32 v[116:117], v[88:89], v[70:71]
	v_pk_add_f32 v[80:81], v[88:89], v[70:71] neg_lo:[0,1] neg_hi:[0,1]
	v_lshlrev_b32_e32 v70, 4, v0
	v_and_b32_e32 v70, 0x1f0, v70
	v_pk_add_f32 v[114:115], v[112:113], v[92:93]
	v_pk_add_f32 v[84:85], v[112:113], v[92:93] neg_lo:[0,1] neg_hi:[0,1]
	v_pk_add_f32 v[112:113], v[76:77], v[100:101]
	v_pk_add_f32 v[72:73], v[76:77], v[100:101] neg_lo:[0,1] neg_hi:[0,1]
	v_cvt_f32_u32_e32 v76, v70
	v_pk_add_f32 v[92:93], v[124:125], v[96:97]
	v_pk_add_f32 v[96:97], v[124:125], v[96:97] neg_lo:[0,1] neg_hi:[0,1]
	v_pk_add_f32 v[124:125], v[138:139], v[74:75]
	v_mul_f32_e32 v76, 0x38800000, v76
	v_pk_add_f32 v[70:71], v[138:139], v[74:75] neg_lo:[0,1] neg_hi:[0,1]
	v_sin_f32_e32 v75, v76
	v_ashrrev_i32_e32 v74, 2, v105
	v_lshlrev_b32_e32 v0, 8, v0
	v_add3_u32 v0, 0, v74, v0
	v_cos_f32_e32 v74, v76
	v_xor_b32_e32 v76, 0x80000000, v75
	v_mov_b32_e32 v77, v75
	v_pk_mul_f32 v[130:131], v[76:77], v[102:103] op_sel:[0,1] op_sel_hi:[1,0]
	v_pk_add_f32 v[100:101], v[136:137], v[108:109]
	v_pk_fma_f32 v[102:103], v[102:103], v[74:75], v[130:131] op_sel_hi:[1,0,1]
	ds_write2_b64 v0, v[142:143], v[102:103] offset1:1
	v_pk_mul_f32 v[102:103], v[76:77], v[74:75] op_sel:[0,1] op_sel_hi:[1,0]
	v_pk_add_f32 v[88:89], v[86:87], v[140:141]
	v_pk_fma_f32 v[102:103], v[74:75], v[74:75], v[102:103] op_sel_hi:[1,0,1]
	v_pk_add_f32 v[108:109], v[136:137], v[108:109] neg_lo:[0,1] neg_hi:[0,1]
	v_pk_mul_f32 v[130:131], v[118:119], v[102:103] op_sel:[1,1] op_sel_hi:[0,1] neg_lo:[0,1]
	v_pk_fma_f32 v[118:119], v[118:119], v[102:103], v[130:131] op_sel_hi:[1,0,1]
	v_pk_mul_f32 v[130:131], v[76:77], v[102:103] op_sel:[0,1] op_sel_hi:[1,0]
	v_pk_add_f32 v[86:87], v[86:87], v[140:141] neg_lo:[0,1] neg_hi:[0,1]
	v_pk_fma_f32 v[102:103], v[102:103], v[74:75], v[130:131] op_sel_hi:[1,0,1]
	s_nop 0
	v_pk_mul_f32 v[130:131], v[100:101], v[102:103] op_sel:[1,1] op_sel_hi:[0,1] neg_lo:[0,1]
	v_pk_fma_f32 v[100:101], v[100:101], v[102:103], v[130:131] op_sel_hi:[1,0,1]
	ds_write2_b64 v0, v[118:119], v[100:101] offset0:2 offset1:3
	v_pk_mul_f32 v[100:101], v[76:77], v[102:103] op_sel:[0,1] op_sel_hi:[1,0]
	s_nop 0
	v_pk_fma_f32 v[100:101], v[102:103], v[74:75], v[100:101] op_sel_hi:[1,0,1]
	s_nop 0
	v_pk_mul_f32 v[102:103], v[90:91], v[100:101] op_sel:[1,1] op_sel_hi:[0,1] neg_lo:[0,1]
	v_pk_fma_f32 v[90:91], v[90:91], v[100:101], v[102:103] op_sel_hi:[1,0,1]
	v_pk_mul_f32 v[102:103], v[76:77], v[100:101] op_sel:[0,1] op_sel_hi:[1,0]
	s_nop 0
	v_pk_fma_f32 v[100:101], v[100:101], v[74:75], v[102:103] op_sel_hi:[1,0,1]
	s_nop 0
	v_pk_mul_f32 v[102:103], v[92:93], v[100:101] op_sel:[1,1] op_sel_hi:[0,1] neg_lo:[0,1]
	v_pk_fma_f32 v[92:93], v[92:93], v[100:101], v[102:103] op_sel_hi:[1,0,1]
	ds_write2_b64 v0, v[90:91], v[92:93] offset0:4 offset1:5
	v_pk_mul_f32 v[90:91], v[76:77], v[100:101] op_sel:[0,1] op_sel_hi:[1,0]
	s_nop 0
	v_pk_fma_f32 v[90:91], v[100:101], v[74:75], v[90:91] op_sel_hi:[1,0,1]
	s_nop 0
	v_pk_mul_f32 v[92:93], v[98:99], v[90:91] op_sel:[1,1] op_sel_hi:[0,1] neg_lo:[0,1]
	v_pk_fma_f32 v[92:93], v[98:99], v[90:91], v[92:93] op_sel_hi:[1,0,1]
	v_pk_mul_f32 v[98:99], v[76:77], v[90:91] op_sel:[0,1] op_sel_hi:[1,0]
	s_nop 0
	v_pk_fma_f32 v[90:91], v[90:91], v[74:75], v[98:99] op_sel_hi:[1,0,1]
	s_nop 0
	v_pk_mul_f32 v[98:99], v[88:89], v[90:91] op_sel:[1,1] op_sel_hi:[0,1] neg_lo:[0,1]
	v_pk_fma_f32 v[88:89], v[88:89], v[90:91], v[98:99] op_sel_hi:[1,0,1]
	ds_write2_b64 v0, v[92:93], v[88:89] offset0:6 offset1:7
	v_pk_mul_f32 v[88:89], v[76:77], v[90:91] op_sel:[0,1] op_sel_hi:[1,0]
	s_nop 0
	v_pk_fma_f32 v[88:89], v[90:91], v[74:75], v[88:89] op_sel_hi:[1,0,1]
	s_nop 0
	v_pk_mul_f32 v[90:91], v[144:145], v[88:89] op_sel:[1,1] op_sel_hi:[0,1] neg_lo:[0,1]
	v_pk_mul_f32 v[92:93], v[76:77], v[88:89] op_sel:[0,1] op_sel_hi:[1,0]
	v_pk_fma_f32 v[90:91], v[144:145], v[88:89], v[90:91] op_sel_hi:[1,0,1]
	v_pk_fma_f32 v[88:89], v[88:89], v[74:75], v[92:93] op_sel_hi:[1,0,1]
	s_nop 0
	v_pk_mul_f32 v[92:93], v[114:115], v[88:89] op_sel:[1,1] op_sel_hi:[0,1] neg_lo:[0,1]
	v_pk_fma_f32 v[92:93], v[114:115], v[88:89], v[92:93] op_sel_hi:[1,0,1]
	ds_write2_b64 v0, v[90:91], v[92:93] offset0:8 offset1:9
	v_pk_mul_f32 v[90:91], v[76:77], v[88:89] op_sel:[0,1] op_sel_hi:[1,0]
	s_nop 0
	v_pk_fma_f32 v[88:89], v[88:89], v[74:75], v[90:91] op_sel_hi:[1,0,1]
	s_nop 0
	v_pk_mul_f32 v[90:91], v[126:127], v[88:89] op_sel:[1,1] op_sel_hi:[0,1] neg_lo:[0,1]
	v_pk_mul_f32 v[92:93], v[76:77], v[88:89] op_sel:[0,1] op_sel_hi:[1,0]
	v_pk_fma_f32 v[90:91], v[126:127], v[88:89], v[90:91] op_sel_hi:[1,0,1]
	v_pk_fma_f32 v[88:89], v[88:89], v[74:75], v[92:93] op_sel_hi:[1,0,1]
	s_nop 0
	v_pk_mul_f32 v[92:93], v[116:117], v[88:89] op_sel:[1,1] op_sel_hi:[0,1] neg_lo:[0,1]
	v_pk_fma_f32 v[92:93], v[116:117], v[88:89], v[92:93] op_sel_hi:[1,0,1]
	ds_write2_b64 v0, v[90:91], v[92:93] offset0:10 offset1:11
	v_pk_mul_f32 v[90:91], v[76:77], v[88:89] op_sel:[0,1] op_sel_hi:[1,0]
	s_nop 0
	v_pk_fma_f32 v[88:89], v[88:89], v[74:75], v[90:91] op_sel_hi:[1,0,1]
	s_nop 0
	v_pk_mul_f32 v[90:91], v[128:129], v[88:89] op_sel:[1,1] op_sel_hi:[0,1] neg_lo:[0,1]
	v_pk_mul_f32 v[92:93], v[76:77], v[88:89] op_sel:[0,1] op_sel_hi:[1,0]
	v_pk_fma_f32 v[90:91], v[128:129], v[88:89], v[90:91] op_sel_hi:[1,0,1]
	v_pk_fma_f32 v[88:89], v[88:89], v[74:75], v[92:93] op_sel_hi:[1,0,1]
	s_nop 0
	v_pk_mul_f32 v[92:93], v[112:113], v[88:89] op_sel:[1,1] op_sel_hi:[0,1] neg_lo:[0,1]
	v_pk_fma_f32 v[92:93], v[112:113], v[88:89], v[92:93] op_sel_hi:[1,0,1]
	ds_write2_b64 v0, v[90:91], v[92:93] offset0:12 offset1:13
	v_pk_mul_f32 v[90:91], v[76:77], v[88:89] op_sel:[0,1] op_sel_hi:[1,0]
	s_nop 0
	v_pk_fma_f32 v[88:89], v[88:89], v[74:75], v[90:91] op_sel_hi:[1,0,1]
	s_nop 0
	v_pk_mul_f32 v[90:91], v[106:107], v[88:89] op_sel:[1,1] op_sel_hi:[0,1] neg_lo:[0,1]
	v_pk_mul_f32 v[92:93], v[76:77], v[88:89] op_sel:[0,1] op_sel_hi:[1,0]
	v_pk_fma_f32 v[90:91], v[106:107], v[88:89], v[90:91] op_sel_hi:[1,0,1]
	v_pk_fma_f32 v[88:89], v[88:89], v[74:75], v[92:93] op_sel_hi:[1,0,1]
	s_nop 0
	v_pk_mul_f32 v[92:93], v[124:125], v[88:89] op_sel:[1,1] op_sel_hi:[0,1] neg_lo:[0,1]
	v_pk_fma_f32 v[92:93], v[124:125], v[88:89], v[92:93] op_sel_hi:[1,0,1]
	ds_write2_b64 v0, v[90:91], v[92:93] offset0:14 offset1:15
	v_pk_mul_f32 v[90:91], v[76:77], v[88:89] op_sel:[0,1] op_sel_hi:[1,0]
	s_nop 0
	v_pk_fma_f32 v[88:89], v[88:89], v[74:75], v[90:91] op_sel_hi:[1,0,1]
	s_nop 0
	v_pk_mul_f32 v[90:91], v[132:133], v[88:89] op_sel:[1,1] op_sel_hi:[0,1] neg_lo:[0,1]
	v_pk_mul_f32 v[92:93], v[76:77], v[88:89] op_sel:[0,1] op_sel_hi:[1,0]
	v_pk_fma_f32 v[90:91], v[132:133], v[88:89], v[90:91] op_sel_hi:[1,0,1]
	v_pk_fma_f32 v[88:89], v[88:89], v[74:75], v[92:93] op_sel_hi:[1,0,1]
	s_nop 0
	v_pk_mul_f32 v[92:93], v[110:111], v[88:89] op_sel:[1,1] op_sel_hi:[0,1] neg_lo:[0,1]
	v_pk_fma_f32 v[92:93], v[110:111], v[88:89], v[92:93] op_sel_hi:[1,0,1]
	ds_write2_b64 v0, v[90:91], v[92:93] offset0:16 offset1:17
	v_pk_mul_f32 v[90:91], v[76:77], v[88:89] op_sel:[0,1] op_sel_hi:[1,0]
	s_nop 0
	v_pk_fma_f32 v[88:89], v[88:89], v[74:75], v[90:91] op_sel_hi:[1,0,1]
	s_nop 0
	v_pk_mul_f32 v[90:91], v[122:123], v[88:89] op_sel:[1,1] op_sel_hi:[0,1] neg_lo:[0,1]
	v_pk_mul_f32 v[92:93], v[76:77], v[88:89] op_sel:[0,1] op_sel_hi:[1,0]
	v_pk_fma_f32 v[90:91], v[122:123], v[88:89], v[90:91] op_sel_hi:[1,0,1]
	v_pk_fma_f32 v[88:89], v[88:89], v[74:75], v[92:93] op_sel_hi:[1,0,1]
	s_nop 0
	v_pk_mul_f32 v[92:93], v[108:109], v[88:89] op_sel:[1,1] op_sel_hi:[0,1] neg_lo:[0,1]
	v_pk_fma_f32 v[92:93], v[108:109], v[88:89], v[92:93] op_sel_hi:[1,0,1]
	ds_write2_b64 v0, v[90:91], v[92:93] offset0:18 offset1:19
	v_pk_mul_f32 v[90:91], v[76:77], v[88:89] op_sel:[0,1] op_sel_hi:[1,0]
	s_nop 0
	v_pk_fma_f32 v[88:89], v[88:89], v[74:75], v[90:91] op_sel_hi:[1,0,1]
	s_nop 0
	v_pk_mul_f32 v[90:91], v[120:121], v[88:89] op_sel:[1,1] op_sel_hi:[0,1] neg_lo:[0,1]
	v_pk_mul_f32 v[92:93], v[76:77], v[88:89] op_sel:[0,1] op_sel_hi:[1,0]
	v_pk_fma_f32 v[90:91], v[120:121], v[88:89], v[90:91] op_sel_hi:[1,0,1]
	v_pk_fma_f32 v[88:89], v[88:89], v[74:75], v[92:93] op_sel_hi:[1,0,1]
	s_nop 0
	v_pk_mul_f32 v[92:93], v[96:97], v[88:89] op_sel:[1,1] op_sel_hi:[0,1] neg_lo:[0,1]
	v_pk_fma_f32 v[92:93], v[96:97], v[88:89], v[92:93] op_sel_hi:[1,0,1]
	ds_write2_b64 v0, v[90:91], v[92:93] offset0:20 offset1:21
	v_pk_mul_f32 v[90:91], v[76:77], v[88:89] op_sel:[0,1] op_sel_hi:[1,0]
	s_nop 0
	v_pk_fma_f32 v[88:89], v[88:89], v[74:75], v[90:91] op_sel_hi:[1,0,1]
	s_nop 0
	v_pk_mul_f32 v[90:91], v[94:95], v[88:89] op_sel:[1,1] op_sel_hi:[0,1] neg_lo:[0,1]
	v_pk_mul_f32 v[92:93], v[76:77], v[88:89] op_sel:[0,1] op_sel_hi:[1,0]
	v_pk_fma_f32 v[90:91], v[94:95], v[88:89], v[90:91] op_sel_hi:[1,0,1]
	v_pk_fma_f32 v[88:89], v[88:89], v[74:75], v[92:93] op_sel_hi:[1,0,1]
	s_nop 0
	v_pk_mul_f32 v[92:93], v[86:87], v[88:89] op_sel:[1,1] op_sel_hi:[0,1] neg_lo:[0,1]
	v_pk_fma_f32 v[86:87], v[86:87], v[88:89], v[92:93] op_sel_hi:[1,0,1]
	ds_write2_b64 v0, v[90:91], v[86:87] offset0:22 offset1:23
	v_pk_mul_f32 v[86:87], v[76:77], v[88:89] op_sel:[0,1] op_sel_hi:[1,0]
	s_nop 0
	v_pk_fma_f32 v[86:87], v[88:89], v[74:75], v[86:87] op_sel_hi:[1,0,1]
	s_nop 0
	v_pk_mul_f32 v[88:89], v[82:83], v[86:87] op_sel:[1,1] op_sel_hi:[0,1] neg_lo:[0,1]
	v_pk_fma_f32 v[82:83], v[82:83], v[86:87], v[88:89] op_sel_hi:[1,0,1]
	v_pk_mul_f32 v[88:89], v[76:77], v[86:87] op_sel:[0,1] op_sel_hi:[1,0]
	s_nop 0
	v_pk_fma_f32 v[86:87], v[86:87], v[74:75], v[88:89] op_sel_hi:[1,0,1]
	s_nop 0
	v_pk_mul_f32 v[88:89], v[84:85], v[86:87] op_sel:[1,1] op_sel_hi:[0,1] neg_lo:[0,1]
	v_pk_fma_f32 v[84:85], v[84:85], v[86:87], v[88:89] op_sel_hi:[1,0,1]
	ds_write2_b64 v0, v[82:83], v[84:85] offset0:24 offset1:25
	v_pk_mul_f32 v[82:83], v[76:77], v[86:87] op_sel:[0,1] op_sel_hi:[1,0]
	s_nop 0
	v_pk_fma_f32 v[82:83], v[86:87], v[74:75], v[82:83] op_sel_hi:[1,0,1]
	s_nop 0
	v_pk_mul_f32 v[84:85], v[78:79], v[82:83] op_sel:[1,1] op_sel_hi:[0,1] neg_lo:[0,1]
	v_pk_fma_f32 v[78:79], v[78:79], v[82:83], v[84:85] op_sel_hi:[1,0,1]
	v_pk_mul_f32 v[84:85], v[76:77], v[82:83] op_sel:[0,1] op_sel_hi:[1,0]
	s_nop 0
	v_pk_fma_f32 v[82:83], v[82:83], v[74:75], v[84:85] op_sel_hi:[1,0,1]
	s_nop 0
	v_pk_mul_f32 v[84:85], v[80:81], v[82:83] op_sel:[1,1] op_sel_hi:[0,1] neg_lo:[0,1]
	v_pk_fma_f32 v[80:81], v[80:81], v[82:83], v[84:85] op_sel_hi:[1,0,1]
	ds_write2_b64 v0, v[78:79], v[80:81] offset0:26 offset1:27
	v_pk_mul_f32 v[78:79], v[76:77], v[82:83] op_sel:[0,1] op_sel_hi:[1,0]
	s_nop 0
	v_pk_fma_f32 v[78:79], v[82:83], v[74:75], v[78:79] op_sel_hi:[1,0,1]
	s_nop 0
	v_pk_mul_f32 v[80:81], v[68:69], v[78:79] op_sel:[1,1] op_sel_hi:[0,1] neg_lo:[0,1]
	v_pk_fma_f32 v[68:69], v[68:69], v[78:79], v[80:81] op_sel_hi:[1,0,1]
	v_pk_mul_f32 v[80:81], v[76:77], v[78:79] op_sel:[0,1] op_sel_hi:[1,0]
	s_nop 0
	v_pk_fma_f32 v[78:79], v[78:79], v[74:75], v[80:81] op_sel_hi:[1,0,1]
	s_nop 0
	v_pk_mul_f32 v[80:81], v[72:73], v[78:79] op_sel:[1,1] op_sel_hi:[0,1] neg_lo:[0,1]
	v_pk_fma_f32 v[72:73], v[72:73], v[78:79], v[80:81] op_sel_hi:[1,0,1]
	ds_write2_b64 v0, v[68:69], v[72:73] offset0:28 offset1:29
	v_pk_mul_f32 v[68:69], v[76:77], v[78:79] op_sel:[0,1] op_sel_hi:[1,0]
	s_nop 0
	v_pk_fma_f32 v[68:69], v[78:79], v[74:75], v[68:69] op_sel_hi:[1,0,1]
	s_nop 0
	v_pk_mul_f32 v[72:73], v[66:67], v[68:69] op_sel:[1,1] op_sel_hi:[0,1] neg_lo:[0,1]
	v_pk_fma_f32 v[66:67], v[66:67], v[68:69], v[72:73] op_sel_hi:[1,0,1]
	v_pk_mul_f32 v[72:73], v[76:77], v[68:69] op_sel:[0,1] op_sel_hi:[1,0]
	s_nop 0
	v_pk_fma_f32 v[68:69], v[68:69], v[74:75], v[72:73] op_sel_hi:[1,0,1]
	s_nop 0
	v_pk_mul_f32 v[72:73], v[70:71], v[68:69] op_sel:[1,1] op_sel_hi:[0,1] neg_lo:[0,1]
	v_pk_fma_f32 v[68:69], v[70:71], v[68:69], v[72:73] op_sel_hi:[1,0,1]
	ds_write2_b64 v0, v[66:67], v[68:69] offset0:30 offset1:31
	s_waitcnt lgkmcnt(0)
	s_barrier
	v_mov_b32 v0, 0
	s_nop 0
	v_add_u32_e32 v71, v0, v170
	v_ashrrev_i32_e32 v105, 5, v71
	v_lshlrev_b32_e32 v0, 10, v105
	v_and_b32_e32 v140, 31, v71
	v_ashrrev_i32_e32 v0, 2, v0
	v_lshlrev_b32_e32 v67, 13, v105
	v_lshlrev_b32_e32 v68, 3, v140
	v_add_u32_e32 v0, 0, v0
	v_lshl_add_u32 v66, v105, 8, 0
	v_add3_u32 v0, v0, v67, v68
	v_add3_u32 v142, v66, v67, v68
	v_add_u32_e32 v143, 0x400, v0
	v_add_u32_e32 v144, 0x800, v0
	v_add_u32_e32 v145, 0xc00, v0
	ds_read_b64 v[130:131], v142
	ds_read2_b64 v[66:69], v0 offset0:33 offset1:66
	ds_read2_b64 v[72:75], v0 offset0:99 offset1:132
	ds_read2_b64 v[76:79], v0 offset0:165 offset1:198
	ds_read2_b64 v[80:83], v143 offset0:103 offset1:136
	ds_read2_b64 v[84:87], v144 offset0:41 offset1:74
	ds_read2_b64 v[88:91], v144 offset0:107 offset1:140
	ds_read2_b64 v[92:95], v144 offset0:173 offset1:206
	ds_read2_b64 v[96:99], v145 offset0:111 offset1:144
	v_add_u32_e32 v146, 0x1000, v0
	ds_read2_b64 v[100:103], v146 offset0:49 offset1:82
	ds_read2_b64 v[106:109], v146 offset0:115 offset1:148
	ds_read2_b64 v[110:113], v146 offset0:181 offset1:214
	v_add_u32_e32 v147, 0x1400, v0
	ds_read2_b64 v[114:117], v147 offset0:119 offset1:152
	s_waitcnt lgkmcnt(4)
	v_pk_add_f32 v[134:135], v[130:131], v[98:99]
	v_pk_add_f32 v[98:99], v[130:131], v[98:99] neg_lo:[0,1] neg_hi:[0,1]
	s_waitcnt lgkmcnt(3)
	v_pk_add_f32 v[130:131], v[66:67], v[100:101]
	v_pk_add_f32 v[66:67], v[66:67], v[100:101] neg_lo:[0,1] neg_hi:[0,1]
	v_add_u32_e32 v70, 0x1800, v0
	v_pk_mul_f32 v[100:101], v[66:67], s[50:51]
	ds_read2_b64 v[118:121], v70 offset0:57 offset1:90
	ds_read2_b64 v[122:125], v70 offset0:123 offset1:156
	ds_read2_b64 v[126:129], v70 offset0:189 offset1:222
	ds_read_b64 v[132:133], v0 offset:8184
	v_pk_fma_f32 v[66:67], v[66:67], s[20:21], v[100:101] op_sel:[0,0,1] op_sel_hi:[1,0,0]
	v_pk_add_f32 v[100:101], v[68:69], v[102:103]
	v_pk_add_f32 v[68:69], v[68:69], v[102:103] neg_lo:[0,1] neg_hi:[0,1]
	v_mul_lo_u32 v105, v140, v105
	v_pk_mul_f32 v[102:103], v[68:69], s[14:15]
	v_cvt_f32_i32_e32 v105, v105
	v_pk_fma_f32 v[68:69], v[68:69], s[6:7], v[102:103] op_sel:[0,0,1] op_sel_hi:[1,0,0]
	s_waitcnt lgkmcnt(6)
	v_pk_add_f32 v[102:103], v[72:73], v[106:107]
	v_pk_add_f32 v[72:73], v[72:73], v[106:107] neg_lo:[0,1] neg_hi:[0,1]
	v_and_b32_e32 v71, 0xffffffe0, v71
	v_pk_mul_f32 v[106:107], v[72:73], s[52:53]
	v_cvt_f32_i32_e32 v71, v71
	v_pk_fma_f32 v[72:73], v[72:73], s[24:25], v[106:107] op_sel:[0,0,1] op_sel_hi:[1,0,0]
	v_pk_add_f32 v[106:107], v[74:75], v[108:109]
	v_pk_add_f32 v[74:75], v[74:75], v[108:109] neg_lo:[0,1] neg_hi:[0,1]
	v_mul_f32_e32 v71, 0x38800000, v71
	v_pk_mul_f32 v[108:109], v[74:75], s[10:11]
	s_nop 0
	v_pk_fma_f32 v[74:75], v[74:75], s[10:11], v[108:109] op_sel:[0,0,1] op_sel_hi:[1,0,0]
	s_waitcnt lgkmcnt(5)
	v_pk_add_f32 v[108:109], v[76:77], v[110:111]
	v_pk_add_f32 v[76:77], v[76:77], v[110:111] neg_lo:[0,1] neg_hi:[0,1]
	s_nop 0
	v_pk_mul_f32 v[110:111], v[76:77], s[24:25]
	s_nop 0
	v_pk_fma_f32 v[76:77], v[76:77], s[0:1], v[110:111] op_sel:[0,0,1] op_sel_hi:[1,0,0]
	v_pk_add_f32 v[110:111], v[78:79], v[112:113]
	v_pk_add_f32 v[78:79], v[78:79], v[112:113] neg_lo:[0,1] neg_hi:[0,1]
	s_nop 0
	v_pk_mul_f32 v[112:113], v[78:79], s[6:7]
	s_nop 0
	v_pk_fma_f32 v[78:79], v[78:79], s[14:15], v[112:113] op_sel:[0,0,1] op_sel_hi:[1,0,0]
	s_waitcnt lgkmcnt(4)
	v_pk_add_f32 v[112:113], v[80:81], v[114:115]
	v_pk_add_f32 v[80:81], v[80:81], v[114:115] neg_lo:[0,1] neg_hi:[0,1]
	s_nop 0
	v_pk_mul_f32 v[114:115], v[80:81], s[20:21]
	s_nop 0
	v_pk_fma_f32 v[80:81], v[80:81], s[48:49], v[114:115] op_sel:[0,0,1] op_sel_hi:[1,0,0]
	v_pk_add_f32 v[114:115], v[82:83], v[116:117]
	v_pk_add_f32 v[116:117], v[82:83], v[116:117] op_sel:[1,1] op_sel_hi:[0,0] neg_lo:[1,0] neg_hi:[0,1]
	s_mov_b64 s[48:49], -1
	s_waitcnt lgkmcnt(3)
	v_pk_add_f32 v[82:83], v[84:85], v[118:119]
	v_pk_add_f32 v[84:85], v[84:85], v[118:119] neg_lo:[0,1] neg_hi:[0,1]
	s_nop 0
	v_pk_mul_f32 v[118:119], v[84:85], s[20:21]
	s_nop 0
	v_pk_fma_f32 v[84:85], v[84:85], s[18:19], v[118:119] op_sel:[0,0,1] op_sel_hi:[1,0,0]
	v_pk_add_f32 v[118:119], v[86:87], v[120:121]
	v_pk_add_f32 v[86:87], v[86:87], v[120:121] neg_lo:[0,1] neg_hi:[0,1]
	s_nop 0
	v_pk_mul_f32 v[120:121], v[86:87], s[6:7]
	s_nop 0
	v_pk_fma_f32 v[86:87], v[86:87], s[4:5], v[120:121] op_sel:[0,0,1] op_sel_hi:[1,0,0]
	s_waitcnt lgkmcnt(2)
	v_pk_add_f32 v[120:121], v[88:89], v[122:123]
	v_pk_add_f32 v[88:89], v[88:89], v[122:123] neg_lo:[0,1] neg_hi:[0,1]
	s_nop 0
	v_pk_mul_f32 v[122:123], v[88:89], s[24:25]
	s_nop 0
	v_pk_fma_f32 v[88:89], v[88:89], s[22:23], v[122:123] op_sel:[0,0,1] op_sel_hi:[1,0,0]
	v_pk_add_f32 v[122:123], v[90:91], v[124:125]
	v_pk_add_f32 v[90:91], v[90:91], v[124:125] neg_lo:[0,1] neg_hi:[0,1]
	s_nop 0
	v_pk_mul_f32 v[124:125], v[90:91], s[10:11]
	s_nop 0
	v_pk_fma_f32 v[90:91], v[90:91], s[8:9], v[124:125] op_sel:[0,0,1] op_sel_hi:[1,0,0]
	s_waitcnt lgkmcnt(1)
	v_pk_add_f32 v[124:125], v[92:93], v[126:127]
	v_pk_add_f32 v[92:93], v[92:93], v[126:127] neg_lo:[0,1] neg_hi:[0,1]
	s_nop 0
	v_pk_mul_f32 v[126:127], v[92:93], s[52:53]
	s_nop 0
	v_pk_fma_f32 v[92:93], v[92:93], s[26:27], v[126:127] op_sel:[0,0,1] op_sel_hi:[1,0,0]
	v_pk_add_f32 v[126:127], v[94:95], v[128:129]
	v_pk_add_f32 v[94:95], v[94:95], v[128:129] neg_lo:[0,1] neg_hi:[0,1]
	s_nop 0
	v_pk_mul_f32 v[128:129], v[94:95], s[14:15]
	s_nop 0
	v_pk_fma_f32 v[94:95], v[94:95], s[12:13], v[128:129] op_sel:[0,0,1] op_sel_hi:[1,0,0]
	s_waitcnt lgkmcnt(0)
	v_pk_add_f32 v[128:129], v[96:97], v[132:133]
	v_pk_add_f32 v[96:97], v[96:97], v[132:133] neg_lo:[0,1] neg_hi:[0,1]
	s_nop 0
	v_pk_mul_f32 v[132:133], v[96:97], s[50:51]
	s_nop 0
	v_pk_fma_f32 v[96:97], v[96:97], s[34:35], v[132:133] op_sel:[0,0,1] op_sel_hi:[1,0,0]
	v_pk_add_f32 v[132:133], v[134:135], v[114:115]
	v_pk_add_f32 v[114:115], v[134:135], v[114:115] neg_lo:[0,1] neg_hi:[0,1]
	v_pk_add_f32 v[134:135], v[130:131], v[82:83]
	v_pk_add_f32 v[82:83], v[130:131], v[82:83] neg_lo:[0,1] neg_hi:[0,1]
	s_nop 0
	v_pk_mul_f32 v[130:131], v[82:83], s[14:15]
	s_nop 0
	v_pk_fma_f32 v[82:83], v[82:83], s[6:7], v[130:131] op_sel:[0,0,1] op_sel_hi:[1,0,0]
	v_pk_add_f32 v[130:131], v[100:101], v[118:119]
	v_pk_add_f32 v[100:101], v[100:101], v[118:119] neg_lo:[0,1] neg_hi:[0,1]
	s_nop 0
	v_pk_mul_f32 v[118:119], v[100:101], s[10:11]
	s_nop 0
	v_pk_fma_f32 v[100:101], v[100:101], s[10:11], v[118:119] op_sel:[0,0,1] op_sel_hi:[1,0,0]
	v_pk_add_f32 v[118:119], v[102:103], v[120:121]
	v_pk_add_f32 v[102:103], v[102:103], v[120:121] neg_lo:[0,1] neg_hi:[0,1]
	s_nop 0
	v_pk_mul_f32 v[120:121], v[102:103], s[6:7]
	s_nop 0
	v_pk_fma_f32 v[102:103], v[102:103], s[14:15], v[120:121] op_sel:[0,0,1] op_sel_hi:[1,0,0]
	v_pk_add_f32 v[120:121], v[106:107], v[122:123]
	v_pk_add_f32 v[122:123], v[106:107], v[122:123] op_sel:[1,1] op_sel_hi:[0,0] neg_lo:[1,0] neg_hi:[0,1]
	s_nop 0
	v_pk_add_f32 v[106:107], v[108:109], v[124:125]
	v_pk_add_f32 v[108:109], v[108:109], v[124:125] neg_lo:[0,1] neg_hi:[0,1]
	s_nop 0
	v_pk_mul_f32 v[124:125], v[108:109], s[6:7]
	s_nop 0
	v_pk_fma_f32 v[108:109], v[108:109], s[4:5], v[124:125] op_sel:[0,0,1] op_sel_hi:[1,0,0]
	v_pk_add_f32 v[124:125], v[110:111], v[126:127]
	v_pk_add_f32 v[110:111], v[110:111], v[126:127] neg_lo:[0,1] neg_hi:[0,1]
	s_nop 0
	v_pk_mul_f32 v[126:127], v[110:111], s[10:11]
	s_nop 0
	v_pk_fma_f32 v[110:111], v[110:111], s[8:9], v[126:127] op_sel:[0,0,1] op_sel_hi:[1,0,0]
	v_pk_add_f32 v[126:127], v[112:113], v[128:129]
	v_pk_add_f32 v[112:113], v[112:113], v[128:129] neg_lo:[0,1] neg_hi:[0,1]
	s_nop 0
	v_pk_mul_f32 v[128:129], v[112:113], s[14:15]
	s_nop 0
	v_pk_fma_f32 v[112:113], v[112:113], s[12:13], v[128:129] op_sel:[0,0,1] op_sel_hi:[1,0,0]
	v_pk_add_f32 v[128:129], v[98:99], v[116:117]
	v_pk_add_f32 v[98:99], v[98:99], v[116:117] neg_lo:[0,1] neg_hi:[0,1]
	v_pk_add_f32 v[116:117], v[66:67], v[84:85]
	v_pk_add_f32 v[66:67], v[66:67], v[84:85] neg_lo:[0,1] neg_hi:[0,1]
	s_nop 0
	v_pk_mul_f32 v[84:85], v[66:67], s[14:15]
	s_nop 0
	v_pk_fma_f32 v[66:67], v[66:67], s[6:7], v[84:85] op_sel:[0,0,1] op_sel_hi:[1,0,0]
	v_pk_add_f32 v[84:85], v[68:69], v[86:87]
	v_pk_add_f32 v[68:69], v[68:69], v[86:87] neg_lo:[0,1] neg_hi:[0,1]
	s_nop 0
	v_pk_mul_f32 v[86:87], v[68:69], s[10:11]
	s_nop 0
	v_pk_fma_f32 v[68:69], v[68:69], s[10:11], v[86:87] op_sel:[0,0,1] op_sel_hi:[1,0,0]
	v_pk_add_f32 v[86:87], v[72:73], v[88:89]
	v_pk_add_f32 v[72:73], v[72:73], v[88:89] neg_lo:[0,1] neg_hi:[0,1]
	s_nop 0
	v_pk_mul_f32 v[88:89], v[72:73], s[6:7]
	s_nop 0
	v_pk_fma_f32 v[72:73], v[72:73], s[14:15], v[88:89] op_sel:[0,0,1] op_sel_hi:[1,0,0]
	v_pk_add_f32 v[88:89], v[74:75], v[90:91]
	v_pk_add_f32 v[90:91], v[74:75], v[90:91] op_sel:[1,1] op_sel_hi:[0,0] neg_lo:[1,0] neg_hi:[0,1]
	s_nop 0
	v_pk_add_f32 v[74:75], v[76:77], v[92:93]
	v_pk_add_f32 v[76:77], v[76:77], v[92:93] neg_lo:[0,1] neg_hi:[0,1]
	s_nop 0
	v_pk_mul_f32 v[92:93], v[76:77], s[6:7]
	s_nop 0
	v_pk_fma_f32 v[76:77], v[76:77], s[4:5], v[92:93] op_sel:[0,0,1] op_sel_hi:[1,0,0]
	v_pk_add_f32 v[92:93], v[78:79], v[94:95]
	v_pk_add_f32 v[78:79], v[78:79], v[94:95] neg_lo:[0,1] neg_hi:[0,1]
	s_mov_b32 s5, 0
	v_pk_mul_f32 v[94:95], v[78:79], s[10:11]
	s_nop 0
	v_pk_fma_f32 v[78:79], v[78:79], s[8:9], v[94:95] op_sel:[0,0,1] op_sel_hi:[1,0,0]
	v_pk_add_f32 v[94:95], v[80:81], v[96:97]
	v_pk_add_f32 v[80:81], v[80:81], v[96:97] neg_lo:[0,1] neg_hi:[0,1]
	s_nop 0
	v_pk_mul_f32 v[96:97], v[80:81], s[14:15]
	s_nop 0
	v_pk_fma_f32 v[80:81], v[80:81], s[12:13], v[96:97] op_sel:[0,0,1] op_sel_hi:[1,0,0]
	v_pk_add_f32 v[96:97], v[132:133], v[120:121]
	v_pk_add_f32 v[120:121], v[132:133], v[120:121] neg_lo:[0,1] neg_hi:[0,1]
	v_pk_add_f32 v[132:133], v[134:135], v[106:107]
	v_pk_add_f32 v[106:107], v[134:135], v[106:107] neg_lo:[0,1] neg_hi:[0,1]
	s_nop 0
	v_pk_mul_f32 v[134:135], v[106:107], s[10:11]
	s_nop 0
	v_pk_fma_f32 v[106:107], v[106:107], s[10:11], v[134:135] op_sel:[0,0,1] op_sel_hi:[1,0,0]
	v_pk_add_f32 v[134:135], v[130:131], v[124:125]
	v_pk_add_f32 v[130:131], v[130:131], v[124:125] op_sel:[1,1] op_sel_hi:[0,0] neg_lo:[1,0] neg_hi:[0,1]
	s_nop 0
	v_pk_add_f32 v[124:125], v[118:119], v[126:127]
	v_pk_add_f32 v[118:119], v[118:119], v[126:127] neg_lo:[0,1] neg_hi:[0,1]
	s_nop 0
	v_pk_mul_f32 v[126:127], v[118:119], s[10:11]
	s_nop 0
	v_pk_fma_f32 v[118:119], v[118:119], s[8:9], v[126:127] op_sel:[0,0,1] op_sel_hi:[1,0,0]
	v_pk_add_f32 v[126:127], v[114:115], v[122:123]
	v_pk_add_f32 v[114:115], v[114:115], v[122:123] neg_lo:[0,1] neg_hi:[0,1]
	v_pk_add_f32 v[122:123], v[82:83], v[108:109]
	v_pk_add_f32 v[82:83], v[82:83], v[108:109] neg_lo:[0,1] neg_hi:[0,1]
	s_nop 0
	v_pk_mul_f32 v[108:109], v[82:83], s[10:11]
	s_nop 0
	v_pk_fma_f32 v[82:83], v[82:83], s[10:11], v[108:109] op_sel:[0,0,1] op_sel_hi:[1,0,0]
	v_pk_add_f32 v[108:109], v[100:101], v[110:111]
	v_pk_add_f32 v[110:111], v[100:101], v[110:111] op_sel:[1,1] op_sel_hi:[0,0] neg_lo:[1,0] neg_hi:[0,1]
	s_nop 0
	v_pk_add_f32 v[100:101], v[102:103], v[112:113]
	v_pk_add_f32 v[102:103], v[102:103], v[112:113] neg_lo:[0,1] neg_hi:[0,1]
	s_nop 0
	v_pk_mul_f32 v[112:113], v[102:103], s[10:11]
	s_nop 0
	v_pk_fma_f32 v[102:103], v[102:103], s[8:9], v[112:113] op_sel:[0,0,1] op_sel_hi:[1,0,0]
	v_pk_add_f32 v[112:113], v[128:129], v[88:89]
	v_pk_add_f32 v[88:89], v[128:129], v[88:89] neg_lo:[0,1] neg_hi:[0,1]
	v_pk_add_f32 v[128:129], v[116:117], v[74:75]
	v_pk_add_f32 v[74:75], v[116:117], v[74:75] neg_lo:[0,1] neg_hi:[0,1]
	s_nop 0
	v_pk_mul_f32 v[116:117], v[74:75], s[10:11]
	s_nop 0
	v_pk_fma_f32 v[74:75], v[74:75], s[10:11], v[116:117] op_sel:[0,0,1] op_sel_hi:[1,0,0]
	v_pk_add_f32 v[116:117], v[84:85], v[92:93]
	v_pk_add_f32 v[92:93], v[84:85], v[92:93] op_sel:[1,1] op_sel_hi:[0,0] neg_lo:[1,0] neg_hi:[0,1]
	s_nop 0
	v_pk_add_f32 v[84:85], v[86:87], v[94:95]
	v_pk_add_f32 v[86:87], v[86:87], v[94:95] neg_lo:[0,1] neg_hi:[0,1]
	s_nop 0
	v_pk_mul_f32 v[94:95], v[86:87], s[10:11]
	s_nop 0
	v_pk_fma_f32 v[86:87], v[86:87], s[8:9], v[94:95] op_sel:[0,0,1] op_sel_hi:[1,0,0]
	v_pk_add_f32 v[94:95], v[98:99], v[90:91]
	v_pk_add_f32 v[90:91], v[98:99], v[90:91] neg_lo:[0,1] neg_hi:[0,1]
	v_pk_add_f32 v[98:99], v[66:67], v[76:77]
	v_pk_add_f32 v[66:67], v[66:67], v[76:77] neg_lo:[0,1] neg_hi:[0,1]
	s_nop 0
	v_pk_mul_f32 v[76:77], v[66:67], s[10:11]
	s_nop 0
	v_pk_fma_f32 v[66:67], v[66:67], s[10:11], v[76:77] op_sel:[0,0,1] op_sel_hi:[1,0,0]
	v_pk_add_f32 v[76:77], v[68:69], v[78:79]
	v_pk_add_f32 v[78:79], v[68:69], v[78:79] op_sel:[1,1] op_sel_hi:[0,0] neg_lo:[1,0] neg_hi:[0,1]
	s_nop 0
	v_pk_add_f32 v[68:69], v[72:73], v[80:81]
	v_pk_add_f32 v[72:73], v[72:73], v[80:81] neg_lo:[0,1] neg_hi:[0,1]
	v_pk_add_f32 v[136:137], v[90:91], v[78:79]
	v_pk_mul_f32 v[80:81], v[72:73], s[10:11]
	v_pk_add_f32 v[78:79], v[90:91], v[78:79] neg_lo:[0,1] neg_hi:[0,1]
	v_pk_fma_f32 v[72:73], v[72:73], s[8:9], v[80:81] op_sel:[0,0,1] op_sel_hi:[1,0,0]
	v_pk_add_f32 v[80:81], v[96:97], v[134:135]
	v_pk_add_f32 v[96:97], v[96:97], v[134:135] neg_lo:[0,1] neg_hi:[0,1]
	v_pk_add_f32 v[134:135], v[132:133], v[124:125]
	v_pk_add_f32 v[132:133], v[132:133], v[124:125] op_sel:[1,1] op_sel_hi:[0,0] neg_lo:[1,0] neg_hi:[0,1]
	v_pk_add_f32 v[90:91], v[66:67], v[72:73]
	v_pk_add_f32 v[124:125], v[120:121], v[130:131]
	v_pk_add_f32 v[120:121], v[120:121], v[130:131] neg_lo:[0,1] neg_hi:[0,1]
	v_pk_add_f32 v[130:131], v[106:107], v[118:119]
	v_pk_add_f32 v[118:119], v[106:107], v[118:119] op_sel:[1,1] op_sel_hi:[0,0] neg_lo:[1,0] neg_hi:[0,1]
	v_pk_add_f32 v[72:73], v[66:67], v[72:73] op_sel:[1,1] op_sel_hi:[0,0] neg_lo:[1,0] neg_hi:[0,1]
	v_pk_add_f32 v[106:107], v[126:127], v[108:109]
	v_pk_add_f32 v[108:109], v[126:127], v[108:109] neg_lo:[0,1] neg_hi:[0,1]
	v_pk_add_f32 v[126:127], v[122:123], v[100:101]
	v_pk_add_f32 v[122:123], v[122:123], v[100:101] op_sel:[1,1] op_sel_hi:[0,0] neg_lo:[1,0] neg_hi:[0,1]
	v_pk_add_f32 v[100:101], v[114:115], v[110:111]
	v_pk_add_f32 v[110:111], v[114:115], v[110:111] neg_lo:[0,1] neg_hi:[0,1]
	v_pk_add_f32 v[114:115], v[82:83], v[102:103]
	v_pk_add_f32 v[102:103], v[82:83], v[102:103] op_sel:[1,1] op_sel_hi:[0,0] neg_lo:[1,0] neg_hi:[0,1]
	v_pk_add_f32 v[82:83], v[112:113], v[116:117]
	v_pk_add_f32 v[112:113], v[112:113], v[116:117] neg_lo:[0,1] neg_hi:[0,1]
	v_pk_add_f32 v[116:117], v[128:129], v[84:85]
	v_pk_add_f32 v[128:129], v[128:129], v[84:85] op_sel:[1,1] op_sel_hi:[0,0] neg_lo:[1,0] neg_hi:[0,1]
	v_pk_add_f32 v[138:139], v[80:81], v[134:135]
	v_pk_add_f32 v[84:85], v[88:89], v[92:93]
	v_pk_add_f32 v[88:89], v[88:89], v[92:93] neg_lo:[0,1] neg_hi:[0,1]
	v_pk_add_f32 v[92:93], v[74:75], v[86:87]
	v_pk_add_f32 v[86:87], v[74:75], v[86:87] op_sel:[1,1] op_sel_hi:[0,0] neg_lo:[1,0] neg_hi:[0,1]
	v_pk_add_f32 v[80:81], v[80:81], v[134:135] neg_lo:[0,1] neg_hi:[0,1]
	v_pk_add_f32 v[74:75], v[94:95], v[76:77]
	v_pk_add_f32 v[76:77], v[94:95], v[76:77] neg_lo:[0,1] neg_hi:[0,1]
	v_pk_add_f32 v[94:95], v[98:99], v[68:69]
	v_pk_add_f32 v[98:99], v[98:99], v[68:69] op_sel:[1,1] op_sel_hi:[0,0] neg_lo:[1,0] neg_hi:[0,1]
	v_pk_add_f32 v[134:135], v[96:97], v[132:133]
	v_pk_add_f32 v[96:97], v[96:97], v[132:133] neg_lo:[0,1] neg_hi:[0,1]
	v_pk_add_f32 v[132:133], v[124:125], v[130:131]
	v_pk_add_f32 v[124:125], v[124:125], v[130:131] neg_lo:[0,1] neg_hi:[0,1]
	v_pk_add_f32 v[130:131], v[120:121], v[118:119]
	v_pk_add_f32 v[68:69], v[120:121], v[118:119] neg_lo:[0,1] neg_hi:[0,1]
	v_pk_add_f32 v[118:119], v[106:107], v[126:127]
	v_pk_add_f32 v[106:107], v[106:107], v[126:127] neg_lo:[0,1] neg_hi:[0,1]
	v_pk_add_f32 v[126:127], v[78:79], v[72:73]
	v_pk_add_f32 v[72:73], v[78:79], v[72:73] neg_lo:[0,1] neg_hi:[0,1]
	v_mul_f32_e32 v78, 0x38800000, v105
	v_sin_f32_e32 v79, v78
	v_cos_f32_e32 v78, v78
	v_pk_add_f32 v[120:121], v[108:109], v[122:123]
	v_pk_add_f32 v[108:109], v[108:109], v[122:123] neg_lo:[0,1] neg_hi:[0,1]
	v_pk_add_f32 v[122:123], v[100:101], v[114:115]
	v_pk_add_f32 v[100:101], v[100:101], v[114:115] neg_lo:[0,1] neg_hi:[0,1]
	v_pk_add_f32 v[114:115], v[110:111], v[102:103]
	v_pk_add_f32 v[66:67], v[110:111], v[102:103] neg_lo:[0,1] neg_hi:[0,1]
	v_pk_add_f32 v[102:103], v[82:83], v[116:117]
	v_pk_add_f32 v[82:83], v[82:83], v[116:117] neg_lo:[0,1] neg_hi:[0,1]
	v_pk_add_f32 v[116:117], v[84:85], v[92:93]
	v_pk_add_f32 v[84:85], v[84:85], v[92:93] neg_lo:[0,1] neg_hi:[0,1]
	v_pk_add_f32 v[92:93], v[88:89], v[86:87]
	v_pk_add_f32 v[86:87], v[88:89], v[86:87] neg_lo:[0,1] neg_hi:[0,1]
	v_pk_add_f32 v[88:89], v[74:75], v[94:95]
	v_pk_add_f32 v[74:75], v[74:75], v[94:95] neg_lo:[0,1] neg_hi:[0,1]
	v_pk_add_f32 v[94:95], v[76:77], v[98:99]
	v_pk_add_f32 v[76:77], v[76:77], v[98:99] neg_lo:[0,1] neg_hi:[0,1]
	v_pk_add_f32 v[98:99], v[136:137], v[90:91]
	v_pk_add_f32 v[90:91], v[136:137], v[90:91] neg_lo:[0,1] neg_hi:[0,1]
	v_sin_f32_e32 v136, v71
	v_pk_add_f32 v[110:111], v[112:113], v[128:129]
	v_pk_add_f32 v[112:113], v[112:113], v[128:129] neg_lo:[0,1] neg_hi:[0,1]
	v_cos_f32_e32 v128, v71
	v_pk_mul_f32 v[140:141], v[138:139], v[78:79] op_sel:[1,1] op_sel_hi:[0,1] neg_lo:[0,1]
	s_nop 0
	v_pk_fma_f32 v[138:139], v[138:139], v[78:79], v[140:141] op_sel_hi:[1,0,1]
	ds_write_b64 v142, v[138:139]
	v_pk_mul_f32 v[138:139], v[136:137], v[78:79] op_sel:[0,1] op_sel_hi:[0,0] neg_lo:[1,0]
	v_pk_fma_f32 v[78:79], v[78:79], v[128:129], v[138:139] op_sel_hi:[1,0,1]
	s_nop 0
	v_pk_mul_f32 v[138:139], v[102:103], v[78:79] op_sel:[1,1] op_sel_hi:[0,1] neg_lo:[0,1]
	s_nop 0
	v_pk_fma_f32 v[102:103], v[102:103], v[78:79], v[138:139] op_sel_hi:[1,0,1]
	v_pk_mul_f32 v[138:139], v[136:137], v[78:79] op_sel:[0,1] op_sel_hi:[0,0] neg_lo:[1,0]
	v_pk_fma_f32 v[78:79], v[78:79], v[128:129], v[138:139] op_sel_hi:[1,0,1]
	s_nop 0
	v_pk_mul_f32 v[138:139], v[118:119], v[78:79] op_sel:[1,1] op_sel_hi:[0,1] neg_lo:[0,1]
	s_nop 0
	v_pk_fma_f32 v[118:119], v[118:119], v[78:79], v[138:139] op_sel_hi:[1,0,1]
	ds_write2_b64 v0, v[102:103], v[118:119] offset0:33 offset1:66
	v_pk_mul_f32 v[102:103], v[136:137], v[78:79] op_sel:[0,1] op_sel_hi:[0,0] neg_lo:[1,0]
	v_pk_fma_f32 v[78:79], v[78:79], v[128:129], v[102:103] op_sel_hi:[1,0,1]
	s_nop 0
	v_pk_mul_f32 v[102:103], v[88:89], v[78:79] op_sel:[1,1] op_sel_hi:[0,1] neg_lo:[0,1]
	s_nop 0
	v_pk_fma_f32 v[88:89], v[88:89], v[78:79], v[102:103] op_sel_hi:[1,0,1]
	v_pk_mul_f32 v[102:103], v[136:137], v[78:79] op_sel:[0,1] op_sel_hi:[0,0] neg_lo:[1,0]
	v_pk_fma_f32 v[78:79], v[78:79], v[128:129], v[102:103] op_sel_hi:[1,0,1]
	s_nop 0
	v_pk_mul_f32 v[102:103], v[132:133], v[78:79] op_sel:[1,1] op_sel_hi:[0,1] neg_lo:[0,1]
	s_nop 0
	v_pk_fma_f32 v[102:103], v[132:133], v[78:79], v[102:103] op_sel_hi:[1,0,1]
	ds_write2_b64 v0, v[88:89], v[102:103] offset0:99 offset1:132
	v_pk_mul_f32 v[88:89], v[136:137], v[78:79] op_sel:[0,1] op_sel_hi:[0,0] neg_lo:[1,0]
	v_pk_fma_f32 v[78:79], v[78:79], v[128:129], v[88:89] op_sel_hi:[1,0,1]
	s_nop 0
	v_pk_mul_f32 v[88:89], v[116:117], v[78:79] op_sel:[1,1] op_sel_hi:[0,1] neg_lo:[0,1]
	v_pk_mul_f32 v[102:103], v[136:137], v[78:79] op_sel:[0,1] op_sel_hi:[0,0] neg_lo:[1,0]
	v_pk_fma_f32 v[88:89], v[116:117], v[78:79], v[88:89] op_sel_hi:[1,0,1]
	v_pk_fma_f32 v[78:79], v[78:79], v[128:129], v[102:103] op_sel_hi:[1,0,1]
	s_nop 0
	v_pk_mul_f32 v[102:103], v[122:123], v[78:79] op_sel:[1,1] op_sel_hi:[0,1] neg_lo:[0,1]
	s_nop 0
	v_pk_fma_f32 v[102:103], v[122:123], v[78:79], v[102:103] op_sel_hi:[1,0,1]
	ds_write2_b64 v0, v[88:89], v[102:103] offset0:165 offset1:198
	v_pk_mul_f32 v[88:89], v[136:137], v[78:79] op_sel:[0,1] op_sel_hi:[0,0] neg_lo:[1,0]
	v_pk_fma_f32 v[78:79], v[78:79], v[128:129], v[88:89] op_sel_hi:[1,0,1]
	s_nop 0
	v_pk_mul_f32 v[88:89], v[98:99], v[78:79] op_sel:[1,1] op_sel_hi:[0,1] neg_lo:[0,1]
	s_nop 0
	v_pk_fma_f32 v[88:89], v[98:99], v[78:79], v[88:89] op_sel_hi:[1,0,1]
	v_pk_mul_f32 v[98:99], v[136:137], v[78:79] op_sel:[0,1] op_sel_hi:[0,0] neg_lo:[1,0]
	v_pk_fma_f32 v[78:79], v[78:79], v[128:129], v[98:99] op_sel_hi:[1,0,1]
	s_nop 0
	v_pk_mul_f32 v[98:99], v[134:135], v[78:79] op_sel:[1,1] op_sel_hi:[0,1] neg_lo:[0,1]
	s_nop 0
	v_pk_fma_f32 v[98:99], v[134:135], v[78:79], v[98:99] op_sel_hi:[1,0,1]
	ds_write2_b64 v143, v[88:89], v[98:99] offset0:103 offset1:136
	v_pk_mul_f32 v[88:89], v[136:137], v[78:79] op_sel:[0,1] op_sel_hi:[0,0] neg_lo:[1,0]
	v_pk_fma_f32 v[78:79], v[78:79], v[128:129], v[88:89] op_sel_hi:[1,0,1]
	s_nop 0
	v_pk_mul_f32 v[88:89], v[110:111], v[78:79] op_sel:[1,1] op_sel_hi:[0,1] neg_lo:[0,1]
	v_pk_mul_f32 v[98:99], v[136:137], v[78:79] op_sel:[0,1] op_sel_hi:[0,0] neg_lo:[1,0]
	v_pk_fma_f32 v[88:89], v[110:111], v[78:79], v[88:89] op_sel_hi:[1,0,1]
	v_pk_fma_f32 v[78:79], v[78:79], v[128:129], v[98:99] op_sel_hi:[1,0,1]
	s_nop 0
	v_pk_mul_f32 v[98:99], v[120:121], v[78:79] op_sel:[1,1] op_sel_hi:[0,1] neg_lo:[0,1]
	s_nop 0
	v_pk_fma_f32 v[98:99], v[120:121], v[78:79], v[98:99] op_sel_hi:[1,0,1]
	ds_write2_b64 v144, v[88:89], v[98:99] offset0:41 offset1:74
	v_pk_mul_f32 v[88:89], v[136:137], v[78:79] op_sel:[0,1] op_sel_hi:[0,0] neg_lo:[1,0]
	v_pk_fma_f32 v[78:79], v[78:79], v[128:129], v[88:89] op_sel_hi:[1,0,1]
	s_nop 0
	v_pk_mul_f32 v[88:89], v[94:95], v[78:79] op_sel:[1,1] op_sel_hi:[0,1] neg_lo:[0,1]
	s_nop 0
	v_pk_fma_f32 v[88:89], v[94:95], v[78:79], v[88:89] op_sel_hi:[1,0,1]
	v_pk_mul_f32 v[94:95], v[136:137], v[78:79] op_sel:[0,1] op_sel_hi:[0,0] neg_lo:[1,0]
	v_pk_fma_f32 v[78:79], v[78:79], v[128:129], v[94:95] op_sel_hi:[1,0,1]
	s_nop 0
	v_pk_mul_f32 v[94:95], v[130:131], v[78:79] op_sel:[1,1] op_sel_hi:[0,1] neg_lo:[0,1]
	v_pk_fma_f32 v[94:95], v[130:131], v[78:79], v[94:95] op_sel_hi:[1,0,1]
	ds_write2_b64 v144, v[88:89], v[94:95] offset0:107 offset1:140
	v_pk_mul_f32 v[88:89], v[136:137], v[78:79] op_sel:[0,1] op_sel_hi:[0,0] neg_lo:[1,0]
	v_pk_fma_f32 v[78:79], v[78:79], v[128:129], v[88:89] op_sel_hi:[1,0,1]
	s_nop 0
	v_pk_mul_f32 v[88:89], v[92:93], v[78:79] op_sel:[1,1] op_sel_hi:[0,1] neg_lo:[0,1]
	v_pk_fma_f32 v[88:89], v[92:93], v[78:79], v[88:89] op_sel_hi:[1,0,1]
	v_pk_mul_f32 v[92:93], v[136:137], v[78:79] op_sel:[0,1] op_sel_hi:[0,0] neg_lo:[1,0]
	v_pk_fma_f32 v[78:79], v[78:79], v[128:129], v[92:93] op_sel_hi:[1,0,1]
	s_nop 0
	v_pk_mul_f32 v[92:93], v[114:115], v[78:79] op_sel:[1,1] op_sel_hi:[0,1] neg_lo:[0,1]
	v_pk_fma_f32 v[92:93], v[114:115], v[78:79], v[92:93] op_sel_hi:[1,0,1]
	ds_write2_b64 v144, v[88:89], v[92:93] offset0:173 offset1:206
	v_pk_mul_f32 v[88:89], v[136:137], v[78:79] op_sel:[0,1] op_sel_hi:[0,0] neg_lo:[1,0]
	v_pk_fma_f32 v[78:79], v[78:79], v[128:129], v[88:89] op_sel_hi:[1,0,1]
	s_nop 0
	v_pk_mul_f32 v[88:89], v[126:127], v[78:79] op_sel:[1,1] op_sel_hi:[0,1] neg_lo:[0,1]
	v_pk_mul_f32 v[92:93], v[136:137], v[78:79] op_sel:[0,1] op_sel_hi:[0,0] neg_lo:[1,0]
	v_pk_fma_f32 v[88:89], v[126:127], v[78:79], v[88:89] op_sel_hi:[1,0,1]
	v_pk_fma_f32 v[78:79], v[78:79], v[128:129], v[92:93] op_sel_hi:[1,0,1]
	s_nop 0
	v_pk_mul_f32 v[92:93], v[80:81], v[78:79] op_sel:[1,1] op_sel_hi:[0,1] neg_lo:[0,1]
	v_pk_fma_f32 v[80:81], v[80:81], v[78:79], v[92:93] op_sel_hi:[1,0,1]
	ds_write2_b64 v145, v[88:89], v[80:81] offset0:111 offset1:144
	v_pk_mul_f32 v[80:81], v[136:137], v[78:79] op_sel:[0,1] op_sel_hi:[0,0] neg_lo:[1,0]
	v_pk_fma_f32 v[78:79], v[78:79], v[128:129], v[80:81] op_sel_hi:[1,0,1]
	s_nop 0
	v_pk_mul_f32 v[80:81], v[82:83], v[78:79] op_sel:[1,1] op_sel_hi:[0,1] neg_lo:[0,1]
	v_pk_fma_f32 v[80:81], v[82:83], v[78:79], v[80:81] op_sel_hi:[1,0,1]
	v_pk_mul_f32 v[82:83], v[136:137], v[78:79] op_sel:[0,1] op_sel_hi:[0,0] neg_lo:[1,0]
	v_pk_fma_f32 v[78:79], v[78:79], v[128:129], v[82:83] op_sel_hi:[1,0,1]
	s_nop 0
	v_pk_mul_f32 v[82:83], v[106:107], v[78:79] op_sel:[1,1] op_sel_hi:[0,1] neg_lo:[0,1]
	v_pk_fma_f32 v[82:83], v[106:107], v[78:79], v[82:83] op_sel_hi:[1,0,1]
	ds_write2_b64 v146, v[80:81], v[82:83] offset0:49 offset1:82
	v_pk_mul_f32 v[80:81], v[136:137], v[78:79] op_sel:[0,1] op_sel_hi:[0,0] neg_lo:[1,0]
	v_pk_fma_f32 v[78:79], v[78:79], v[128:129], v[80:81] op_sel_hi:[1,0,1]
	s_nop 0
	v_pk_mul_f32 v[80:81], v[74:75], v[78:79] op_sel:[1,1] op_sel_hi:[0,1] neg_lo:[0,1]
	v_pk_fma_f32 v[74:75], v[74:75], v[78:79], v[80:81] op_sel_hi:[1,0,1]
	v_pk_mul_f32 v[80:81], v[136:137], v[78:79] op_sel:[0,1] op_sel_hi:[0,0] neg_lo:[1,0]
	v_pk_fma_f32 v[78:79], v[78:79], v[128:129], v[80:81] op_sel_hi:[1,0,1]
	s_nop 0
	v_pk_mul_f32 v[80:81], v[124:125], v[78:79] op_sel:[1,1] op_sel_hi:[0,1] neg_lo:[0,1]
	v_pk_fma_f32 v[80:81], v[124:125], v[78:79], v[80:81] op_sel_hi:[1,0,1]
	ds_write2_b64 v146, v[74:75], v[80:81] offset0:115 offset1:148
	v_pk_mul_f32 v[74:75], v[136:137], v[78:79] op_sel:[0,1] op_sel_hi:[0,0] neg_lo:[1,0]
	v_pk_fma_f32 v[74:75], v[78:79], v[128:129], v[74:75] op_sel_hi:[1,0,1]
	s_nop 0
	v_pk_mul_f32 v[78:79], v[84:85], v[74:75] op_sel:[1,1] op_sel_hi:[0,1] neg_lo:[0,1]
	v_pk_mul_f32 v[80:81], v[136:137], v[74:75] op_sel:[0,1] op_sel_hi:[0,0] neg_lo:[1,0]
	v_pk_fma_f32 v[78:79], v[84:85], v[74:75], v[78:79] op_sel_hi:[1,0,1]
	v_pk_fma_f32 v[74:75], v[74:75], v[128:129], v[80:81] op_sel_hi:[1,0,1]
	s_nop 0
	v_pk_mul_f32 v[80:81], v[100:101], v[74:75] op_sel:[1,1] op_sel_hi:[0,1] neg_lo:[0,1]
	v_pk_fma_f32 v[80:81], v[100:101], v[74:75], v[80:81] op_sel_hi:[1,0,1]
	ds_write2_b64 v146, v[78:79], v[80:81] offset0:181 offset1:214
	v_pk_mul_f32 v[78:79], v[136:137], v[74:75] op_sel:[0,1] op_sel_hi:[0,0] neg_lo:[1,0]
	v_pk_fma_f32 v[74:75], v[74:75], v[128:129], v[78:79] op_sel_hi:[1,0,1]
	s_nop 0
	v_pk_mul_f32 v[78:79], v[90:91], v[74:75] op_sel:[1,1] op_sel_hi:[0,1] neg_lo:[0,1]
	v_pk_mul_f32 v[80:81], v[136:137], v[74:75] op_sel:[0,1] op_sel_hi:[0,0] neg_lo:[1,0]
	v_pk_fma_f32 v[78:79], v[90:91], v[74:75], v[78:79] op_sel_hi:[1,0,1]
	v_pk_fma_f32 v[74:75], v[74:75], v[128:129], v[80:81] op_sel_hi:[1,0,1]
	s_nop 0
	v_pk_mul_f32 v[80:81], v[96:97], v[74:75] op_sel:[1,1] op_sel_hi:[0,1] neg_lo:[0,1]
	v_pk_fma_f32 v[80:81], v[96:97], v[74:75], v[80:81] op_sel_hi:[1,0,1]
	ds_write2_b64 v147, v[78:79], v[80:81] offset0:119 offset1:152
	v_pk_mul_f32 v[78:79], v[136:137], v[74:75] op_sel:[0,1] op_sel_hi:[0,0] neg_lo:[1,0]
	v_pk_fma_f32 v[74:75], v[74:75], v[128:129], v[78:79] op_sel_hi:[1,0,1]
	s_nop 0
	v_pk_mul_f32 v[78:79], v[112:113], v[74:75] op_sel:[1,1] op_sel_hi:[0,1] neg_lo:[0,1]
	v_pk_mul_f32 v[80:81], v[136:137], v[74:75] op_sel:[0,1] op_sel_hi:[0,0] neg_lo:[1,0]
	v_pk_fma_f32 v[78:79], v[112:113], v[74:75], v[78:79] op_sel_hi:[1,0,1]
	v_pk_fma_f32 v[74:75], v[74:75], v[128:129], v[80:81] op_sel_hi:[1,0,1]
	s_nop 0
	v_pk_mul_f32 v[80:81], v[108:109], v[74:75] op_sel:[1,1] op_sel_hi:[0,1] neg_lo:[0,1]
	v_pk_fma_f32 v[80:81], v[108:109], v[74:75], v[80:81] op_sel_hi:[1,0,1]
	ds_write2_b64 v70, v[78:79], v[80:81] offset0:57 offset1:90
	v_pk_mul_f32 v[78:79], v[136:137], v[74:75] op_sel:[0,1] op_sel_hi:[0,0] neg_lo:[1,0]
	v_pk_fma_f32 v[74:75], v[74:75], v[128:129], v[78:79] op_sel_hi:[1,0,1]
	s_nop 0
	v_pk_mul_f32 v[78:79], v[76:77], v[74:75] op_sel:[1,1] op_sel_hi:[0,1] neg_lo:[0,1]
	v_pk_fma_f32 v[76:77], v[76:77], v[74:75], v[78:79] op_sel_hi:[1,0,1]
	v_pk_mul_f32 v[78:79], v[136:137], v[74:75] op_sel:[0,1] op_sel_hi:[0,0] neg_lo:[1,0]
	v_pk_fma_f32 v[74:75], v[74:75], v[128:129], v[78:79] op_sel_hi:[1,0,1]
	s_nop 0
	v_pk_mul_f32 v[78:79], v[68:69], v[74:75] op_sel:[1,1] op_sel_hi:[0,1] neg_lo:[0,1]
	v_pk_fma_f32 v[68:69], v[68:69], v[74:75], v[78:79] op_sel_hi:[1,0,1]
	ds_write2_b64 v70, v[76:77], v[68:69] offset0:123 offset1:156
	v_pk_mul_f32 v[68:69], v[136:137], v[74:75] op_sel:[0,1] op_sel_hi:[0,0] neg_lo:[1,0]
	v_pk_fma_f32 v[68:69], v[74:75], v[128:129], v[68:69] op_sel_hi:[1,0,1]
	s_nop 0
	v_pk_mul_f32 v[74:75], v[86:87], v[68:69] op_sel:[1,1] op_sel_hi:[0,1] neg_lo:[0,1]
	v_pk_mul_f32 v[76:77], v[136:137], v[68:69] op_sel:[0,1] op_sel_hi:[0,0] neg_lo:[1,0]
	v_pk_fma_f32 v[74:75], v[86:87], v[68:69], v[74:75] op_sel_hi:[1,0,1]
	v_pk_fma_f32 v[68:69], v[68:69], v[128:129], v[76:77] op_sel_hi:[1,0,1]
	s_nop 0
	v_pk_mul_f32 v[76:77], v[66:67], v[68:69] op_sel:[1,1] op_sel_hi:[0,1] neg_lo:[0,1]
	v_pk_fma_f32 v[66:67], v[66:67], v[68:69], v[76:77] op_sel_hi:[1,0,1]
	ds_write2_b64 v70, v[74:75], v[66:67] offset0:189 offset1:222
	v_pk_mul_f32 v[66:67], v[136:137], v[68:69] op_sel:[0,1] op_sel_hi:[0,0] neg_lo:[1,0]
	v_pk_fma_f32 v[66:67], v[68:69], v[128:129], v[66:67] op_sel_hi:[1,0,1]
	s_nop 0
	v_pk_mul_f32 v[68:69], v[72:73], v[66:67] op_sel:[1,1] op_sel_hi:[0,1] neg_lo:[0,1]
	v_pk_fma_f32 v[66:67], v[72:73], v[66:67], v[68:69] op_sel_hi:[1,0,1]
	ds_write_b64 v0, v[66:67] offset:8184
	s_waitcnt lgkmcnt(0)
	s_barrier
